# baseline (speedup 1.0000x reference)
; template <int NK, bool BNT = false> ...
;     ...
;   auto stage = [&](int kt, int bufc) {
;     unsigned char* sa = smem + bufc * BIG_STAGE;
;     const unsigned char* Ab = Abase + (long)kt * 8192 + soff;
;     const unsigned char* Bb = Bbase + (long)kt * 8192 + soff;
;     glds16(Ab, sa + sb0);
;     glds16(Ab + astride * 2, sa + 8192 + sb0);
;     if constexpr (BNT) {
;       glds16_nt(Bb, sa + 16384 + sb0);
;       glds16_nt(Bb + bstride * 2, sa + 24576 + sb0);
;     } else {
;       glds16(Bb, sa + 16384 + sb0);
;       glds16(Bb + bstride * 2, sa + 24576 + sb0);
;     }
;   };
;   const int rd = fr * 64 + ((fq ^ (((fr >> 3) & 1) << 1)) * 16);
;   const int aoff = wr * 64 * 64 + rd;
;   const int boff = 16384 + wc * 128 * 64 + rd;
;   auto kstep = [&](int T, int cur, int nxt, bool do_stage) {
;     const unsigned char* sa = smem + cur * BIG_STAGE;
;     bf16x8 af[4], bfr[4];
; #pragma unroll
;     for (int m = 0; m < 4; ++m) af[m] = *reinterpret_cast<const bf16x8*>(sa + aoff + m * 1024);
; #pragma unroll
;     for (int n = 0; n < 4; ++n) bfr[n] = *reinterpret_cast<const bf16x8*>(sa + boff + n * 1024);
;     __builtin_amdgcn_sched_barrier(0);
;     if (do_stage) stage(T + 3, nxt);
; #pragma unroll
;     for (int m = 0; m < 4; ++m)
; #pragma unroll
;       for (int n = 0; n < 4; ++n) acc[m][n] = __builtin_amdgcn_mfma_f32_16x16x32_bf16(af[m], bfr[n], acc[m][n], 0, 0, 0);
;     if (do_stage) {
; #pragma unroll
;       for (int q = 0; q < NG; ++q) {
;         __builtin_amdgcn_sched_group_barrier(0x008, 3, 0);
;         __builtin_amdgcn_sched_group_barrier(0x010, 1, 0);
;       }
;       __builtin_amdgcn_sched_group_barrier(0x008, 16 - 3 * NG, 0);
;     }
;     __builtin_amdgcn_sched_barrier(0);
; #pragma unroll
;     for (int n = 0; n < 4; ++n) bfr[n] = *reinterpret_cast<const bf16x8*>(sa + boff + (4 + n) * 1024);
; #pragma unroll
;     for (int m = 0; m < 4; ++m)
; #pragma unroll
;       for (int n = 0; n < 4; ++n)
;         acc[m][4 + n] = __builtin_amdgcn_mfma_f32_16x16x32_bf16(af[m], bfr[n], acc[m][4 + n], 0, 0, 0);
;     __builtin_amdgcn_sched_barrier(0);
;     ...
;   for (int it = 0; it < NK / 4 - 1; ++it) {
;     const int t = it * 4;
;     BIG_SYNC(2 * NG); kstep(t, 0, 3, true);
;     BIG_SYNC(2 * NG); kstep(t + 1, 1, 0, true);
;     BIG_SYNC(2 * NG); kstep(t + 2, 2, 1, true);
;     BIG_SYNC(2 * NG); kstep(t + 3, 3, 2, true);
.LBB0_68:
	s_waitcnt lgkmcnt(3)
	v_mfma_f32_16x16x32_bf16 v[124:127], v[216:219], v[232:235], v[124:127]
	v_add_u32_e32 v158, 0x18000, v166
	v_lshl_add_u64 v[144:145], v[138:139], 0, s[36:37]
	v_mfma_f32_16x16x32_bf16 v[108:111], v[220:223], v[232:235], v[108:111]
	v_add_u32_e32 v159, 0x1a000, v166
	v_lshl_add_u64 v[160:161], v[144:145], 0, s[60:61]
	v_mfma_f32_16x16x32_bf16 v[88:91], v[224:227], v[232:235], v[88:91]
	s_waitcnt vmcnt(4)
	s_barrier
	s_add_i32 m0, s100, 0x18000
	v_lshl_add_u64 v[142:143], v[140:141], 0, s[36:37]
	v_mfma_f32_16x16x32_bf16 v[44:47], v[228:231], v[232:235], v[44:47]
	v_lshl_add_u64 v[182:183], v[142:143], 0, s[60:61]
	global_load_lds_dwordx4 v[160:161], off
	s_waitcnt lgkmcnt(2)
	v_mfma_f32_16x16x32_bf16 v[120:123], v[216:219], v[236:239], v[120:123]
	ds_read_b128 v[232:235], v168 offset:20480
	v_mfma_f32_16x16x32_bf16 v[104:107], v[220:223], v[236:239], v[104:107]
	v_lshl_add_u64 v[160:161], v[144:145], 0, s[80:81]
	s_add_i32 m0, s100, 0x1a000
	v_mfma_f32_16x16x32_bf16 v[76:79], v[224:227], v[236:239], v[76:79]
	global_load_lds_dwordx4 v[160:161], off
	v_mfma_f32_16x16x32_bf16 v[40:43], v[228:231], v[236:239], v[40:43]
	v_add_u32_e32 v160, 0x1c000, v166
	s_waitcnt lgkmcnt(2)
	v_mfma_f32_16x16x32_bf16 v[116:119], v[216:219], v[240:243], v[116:119]
	ds_read_b128 v[236:239], v168 offset:21504
	v_mfma_f32_16x16x32_bf16 v[100:103], v[220:223], v[240:243], v[100:103]
	v_add_u32_e32 v161, 0x1e000, v166
	v_mfma_f32_16x16x32_bf16 v[68:71], v[224:227], v[240:243], v[68:71]
	s_add_i32 m0, s100, 0x1c000
	v_mfma_f32_16x16x32_bf16 v[36:39], v[228:231], v[240:243], v[36:39]
	global_load_lds_dwordx4 v[182:183], off
	s_waitcnt lgkmcnt(2)
	v_mfma_f32_16x16x32_bf16 v[112:115], v[216:219], v[244:247], v[112:115]
	ds_read_b128 v[240:243], v168 offset:22528
	v_mfma_f32_16x16x32_bf16 v[96:99], v[220:223], v[244:247], v[96:99]
	v_lshl_add_u64 v[182:183], v[142:143], 0, s[80:81]
	v_mfma_f32_16x16x32_bf16 v[64:67], v[224:227], v[244:247], v[64:67]
	s_add_i32 m0, s100, 0x1e000
	v_mfma_f32_16x16x32_bf16 v[32:35], v[228:231], v[244:247], v[32:35]
	global_load_lds_dwordx4 v[182:183], off
	s_waitcnt lgkmcnt(2)
	v_mfma_f32_16x16x32_bf16 v[92:95], v[216:219], v[232:235], v[92:95]
	ds_read_b128 v[244:247], v168 offset:23552
	v_mfma_f32_16x16x32_bf16 v[60:63], v[220:223], v[232:235], v[60:63]
	ds_read_b128 v[186:189], v167 offset:32768
	v_mfma_f32_16x16x32_bf16 v[28:31], v[224:227], v[232:235], v[28:31]
	ds_read_b128 v[190:193], v167 offset:33792
	v_mfma_f32_16x16x32_bf16 v[12:15], v[228:231], v[232:235], v[12:15]
	ds_read_b128 v[194:197], v167 offset:34816
	s_waitcnt lgkmcnt(5)
	v_mfma_f32_16x16x32_bf16 v[84:87], v[216:219], v[236:239], v[84:87]
	ds_read_b128 v[202:205], v167 offset:35840
	ds_read_b128 v[232:235], v168 offset:49152
	v_mfma_f32_16x16x32_bf16 v[56:59], v[220:223], v[236:239], v[56:59]
	v_mfma_f32_16x16x32_bf16 v[24:27], v[224:227], v[236:239], v[24:27]
	v_mfma_f32_16x16x32_bf16 v[8:11], v[228:231], v[236:239], v[8:11]
	s_waitcnt lgkmcnt(6)
	v_mfma_f32_16x16x32_bf16 v[80:83], v[216:219], v[240:243], v[80:83]
	ds_read_b128 v[236:239], v168 offset:50176
	v_mfma_f32_16x16x32_bf16 v[52:55], v[220:223], v[240:243], v[52:55]
	v_mfma_f32_16x16x32_bf16 v[20:23], v[224:227], v[240:243], v[20:23]
	v_mfma_f32_16x16x32_bf16 v[4:7], v[228:231], v[240:243], v[4:7]
	s_waitcnt lgkmcnt(6)
	v_mfma_f32_16x16x32_bf16 v[72:75], v[216:219], v[244:247], v[72:75]
	ds_read_b128 v[240:243], v168 offset:51200
	v_mfma_f32_16x16x32_bf16 v[48:51], v[220:223], v[244:247], v[48:51]
	v_mfma_f32_16x16x32_bf16 v[16:19], v[224:227], v[244:247], v[16:19]
	v_mfma_f32_16x16x32_bf16 v[0:3], v[228:231], v[244:247], v[0:3]
	ds_read_b128 v[244:247], v168 offset:52224
	s_waitcnt lgkmcnt(3)
	v_mfma_f32_16x16x32_bf16 v[124:127], v[186:189], v[232:235], v[124:127]
	v_lshl_add_u64 v[182:183], v[144:145], 0, s[62:63]
	v_mfma_f32_16x16x32_bf16 v[108:111], v[190:193], v[232:235], v[108:111]
	s_mov_b32 m0, s100
	v_mfma_f32_16x16x32_bf16 v[88:91], v[194:197], v[232:235], v[88:91]
	s_waitcnt vmcnt(4)
	s_barrier
	v_lshl_add_u64 v[198:199], v[142:143], 0, s[62:63]
	v_mfma_f32_16x16x32_bf16 v[44:47], v[202:205], v[232:235], v[44:47]
	global_load_lds_dwordx4 v[182:183], off
	s_waitcnt lgkmcnt(2)
	v_mfma_f32_16x16x32_bf16 v[120:123], v[186:189], v[236:239], v[120:123]
	ds_read_b128 v[232:235], v168 offset:53248
	v_mfma_f32_16x16x32_bf16 v[104:107], v[190:193], v[236:239], v[104:107]
	v_lshl_add_u64 v[182:183], v[144:145], 0, s[0:1]
	v_mfma_f32_16x16x32_bf16 v[76:79], v[194:197], v[236:239], v[76:79]
	s_add_i32 m0, s100, 0x2000
	v_mfma_f32_16x16x32_bf16 v[40:43], v[202:205], v[236:239], v[40:43]
	global_load_lds_dwordx4 v[182:183], off
	s_waitcnt lgkmcnt(2)
	v_mfma_f32_16x16x32_bf16 v[116:119], v[186:189], v[240:243], v[116:119]
	ds_read_b128 v[236:239], v168 offset:54272
	v_mfma_f32_16x16x32_bf16 v[100:103], v[190:193], v[240:243], v[100:103]
	s_add_i32 m0, s100, 0x4000
	v_mfma_f32_16x16x32_bf16 v[68:71], v[194:197], v[240:243], v[68:71]
	v_lshl_add_u64 v[182:183], v[142:143], 0, s[0:1]
	v_mfma_f32_16x16x32_bf16 v[36:39], v[202:205], v[240:243], v[36:39]
	global_load_lds_dwordx4 v[198:199], off
	s_waitcnt lgkmcnt(2)
	v_mfma_f32_16x16x32_bf16 v[112:115], v[186:189], v[244:247], v[112:115]
	ds_read_b128 v[240:243], v168 offset:55296
	v_mfma_f32_16x16x32_bf16 v[96:99], v[190:193], v[244:247], v[96:99]
	s_add_i32 m0, s100, 0x6000
	v_mfma_f32_16x16x32_bf16 v[64:67], v[194:197], v[244:247], v[64:67]
	global_load_lds_dwordx4 v[182:183], off
	v_mfma_f32_16x16x32_bf16 v[32:35], v[202:205], v[244:247], v[32:35]
	s_waitcnt lgkmcnt(2)
; #define BIG_SYNC(N)                                              \
;   asm volatile("s_waitcnt vmcnt(%0)" ::"n"(N) : "memory");       \
;   __builtin_amdgcn_s_barrier();                                  \
;   asm volatile("" ::: "memory");                                 \
;   __builtin_amdgcn_sched_barrier(0);
; template <int NK, bool BNT = false> ...
;     ...
;   auto kstep = [&](int T, int cur, int nxt, bool do_stage) {
;     const unsigned char* sa = smem + cur * BIG_STAGE;
;     bf16x8 af[4], bfr[4];
; #pragma unroll
;     for (int m = 0; m < 4; ++m) af[m] = *reinterpret_cast<const bf16x8*>(sa + aoff + m * 1024);
; #pragma unroll
;     for (int n = 0; n < 4; ++n) bfr[n] = *reinterpret_cast<const bf16x8*>(sa + boff + n * 1024);
;     __builtin_amdgcn_sched_barrier(0);
;     if (do_stage) stage(T + 3, nxt);
; #pragma unroll
;     for (int m = 0; m < 4; ++m)
; #pragma unroll
;       for (int n = 0; n < 4; ++n) acc[m][n] = __builtin_amdgcn_mfma_f32_16x16x32_bf16(af[m], bfr[n], acc[m][n], 0, 0, 0);
;     if (do_stage) {
; #pragma unroll
;       for (int q = 0; q < NG; ++q) {
;         __builtin_amdgcn_sched_group_barrier(0x008, 3, 0);
;         __builtin_amdgcn_sched_group_barrier(0x010, 1, 0);
;       }
;       __builtin_amdgcn_sched_group_barrier(0x008, 16 - 3 * NG, 0);
;     }
;     __builtin_amdgcn_sched_barrier(0);
; #pragma unroll
;     for (int n = 0; n < 4; ++n) bfr[n] = *reinterpret_cast<const bf16x8*>(sa + boff + (4 + n) * 1024);
; #pragma unroll
;     for (int m = 0; m < 4; ++m)
; #pragma unroll
;       for (int n = 0; n < 4; ++n)
;         acc[m][4 + n] = __builtin_amdgcn_mfma_f32_16x16x32_bf16(af[m], bfr[n], acc[m][4 + n], 0, 0, 0);
;     __builtin_amdgcn_sched_barrier(0);
;     ...
;   for (int it = 0; it < NK / 4 - 1; ++it) {
;     const int t = it * 4;
;     BIG_SYNC(2 * NG); kstep(t, 0, 3, true);
;     BIG_SYNC(2 * NG); kstep(t + 1, 1, 0, true);
;     BIG_SYNC(2 * NG); kstep(t + 2, 2, 1, true);
;     BIG_SYNC(2 * NG); kstep(t + 3, 3, 2, true);
	v_mfma_f32_16x16x32_bf16 v[92:95], v[186:189], v[232:235], v[92:95]
	ds_read_b128 v[244:247], v168 offset:56320
	v_mfma_f32_16x16x32_bf16 v[60:63], v[190:193], v[232:235], v[60:63]
	ds_read_b128 v[216:219], v210
	v_mfma_f32_16x16x32_bf16 v[28:31], v[194:197], v[232:235], v[28:31]
	ds_read_b128 v[220:223], v210 offset:1024
	v_mfma_f32_16x16x32_bf16 v[12:15], v[202:205], v[232:235], v[12:15]
	ds_read_b128 v[224:227], v210 offset:2048
	s_waitcnt lgkmcnt(5)
	v_mfma_f32_16x16x32_bf16 v[84:87], v[186:189], v[236:239], v[84:87]
	ds_read_b128 v[228:231], v210 offset:3072
	ds_read_b128 v[232:235], v211
	v_mfma_f32_16x16x32_bf16 v[56:59], v[190:193], v[236:239], v[56:59]
	v_mfma_f32_16x16x32_bf16 v[24:27], v[194:197], v[236:239], v[24:27]
	v_mfma_f32_16x16x32_bf16 v[8:11], v[202:205], v[236:239], v[8:11]
	s_waitcnt lgkmcnt(6)
	v_mfma_f32_16x16x32_bf16 v[80:83], v[186:189], v[240:243], v[80:83]
	ds_read_b128 v[236:239], v211 offset:1024
	v_mfma_f32_16x16x32_bf16 v[52:55], v[190:193], v[240:243], v[52:55]
	v_mfma_f32_16x16x32_bf16 v[20:23], v[194:197], v[240:243], v[20:23]
	v_mfma_f32_16x16x32_bf16 v[4:7], v[202:205], v[240:243], v[4:7]
	s_waitcnt lgkmcnt(6)
	v_mfma_f32_16x16x32_bf16 v[72:75], v[186:189], v[244:247], v[72:75]
	ds_read_b128 v[240:243], v211 offset:2048
	v_mfma_f32_16x16x32_bf16 v[48:51], v[190:193], v[244:247], v[48:51]
	v_mfma_f32_16x16x32_bf16 v[16:19], v[194:197], v[244:247], v[16:19]
	v_mfma_f32_16x16x32_bf16 v[0:3], v[202:205], v[244:247], v[0:3]
	ds_read_b128 v[244:247], v211 offset:3072
	s_waitcnt lgkmcnt(3)
	v_mfma_f32_16x16x32_bf16 v[124:127], v[216:219], v[232:235], v[124:127]
	v_lshl_add_u64 v[174:175], v[144:145], 0, s[2:3]
	v_mfma_f32_16x16x32_bf16 v[108:111], v[220:223], v[232:235], v[108:111]
	s_add_i32 m0, s100, 0x8000
	v_mfma_f32_16x16x32_bf16 v[88:91], v[224:227], v[232:235], v[88:91]
	s_waitcnt vmcnt(4)
	s_barrier
	v_lshl_add_u64 v[178:179], v[142:143], 0, s[2:3]
	v_mfma_f32_16x16x32_bf16 v[44:47], v[228:231], v[232:235], v[44:47]
	global_load_lds_dwordx4 v[174:175], off
	s_waitcnt lgkmcnt(2)
	v_mfma_f32_16x16x32_bf16 v[120:123], v[216:219], v[236:239], v[120:123]
	ds_read_b128 v[232:235], v211 offset:4096
	v_mfma_f32_16x16x32_bf16 v[104:107], v[220:223], v[236:239], v[104:107]
	v_lshl_add_u64 v[174:175], v[144:145], 0, s[52:53]
	v_mfma_f32_16x16x32_bf16 v[76:79], v[224:227], v[236:239], v[76:79]
	s_add_i32 m0, s100, 0xa000
	v_mfma_f32_16x16x32_bf16 v[40:43], v[228:231], v[236:239], v[40:43]
	global_load_lds_dwordx4 v[174:175], off
	s_waitcnt lgkmcnt(2)
	v_mfma_f32_16x16x32_bf16 v[116:119], v[216:219], v[240:243], v[116:119]
	ds_read_b128 v[236:239], v211 offset:5120
	v_mfma_f32_16x16x32_bf16 v[100:103], v[220:223], v[240:243], v[100:103]
	s_add_i32 m0, s100, 0xc000
	v_mfma_f32_16x16x32_bf16 v[68:71], v[224:227], v[240:243], v[68:71]
	v_lshl_add_u64 v[174:175], v[142:143], 0, s[52:53]
	v_mfma_f32_16x16x32_bf16 v[36:39], v[228:231], v[240:243], v[36:39]
	global_load_lds_dwordx4 v[178:179], off
	s_waitcnt lgkmcnt(2)
	v_mfma_f32_16x16x32_bf16 v[112:115], v[216:219], v[244:247], v[112:115]
	ds_read_b128 v[240:243], v211 offset:6144
	v_mfma_f32_16x16x32_bf16 v[96:99], v[220:223], v[244:247], v[96:99]
	s_add_i32 m0, s100, 0xe000
	v_mfma_f32_16x16x32_bf16 v[64:67], v[224:227], v[244:247], v[64:67]
	global_load_lds_dwordx4 v[174:175], off
	v_mfma_f32_16x16x32_bf16 v[32:35], v[228:231], v[244:247], v[32:35]
	s_waitcnt lgkmcnt(2)
	v_mfma_f32_16x16x32_bf16 v[92:95], v[216:219], v[232:235], v[92:95]
	ds_read_b128 v[244:247], v211 offset:7168
	v_mfma_f32_16x16x32_bf16 v[60:63], v[220:223], v[232:235], v[60:63]
	ds_read_b128 v[186:189], v210 offset:32768
	v_mfma_f32_16x16x32_bf16 v[28:31], v[224:227], v[232:235], v[28:31]
	ds_read_b128 v[190:193], v210 offset:33792
	v_mfma_f32_16x16x32_bf16 v[12:15], v[228:231], v[232:235], v[12:15]
	ds_read_b128 v[194:197], v210 offset:34816
	s_waitcnt lgkmcnt(5)
	v_mfma_f32_16x16x32_bf16 v[84:87], v[216:219], v[236:239], v[84:87]
	ds_read_b128 v[202:205], v210 offset:35840
	ds_read_b128 v[232:235], v211 offset:32768
	v_mfma_f32_16x16x32_bf16 v[56:59], v[220:223], v[236:239], v[56:59]
	v_mfma_f32_16x16x32_bf16 v[24:27], v[224:227], v[236:239], v[24:27]
	v_mfma_f32_16x16x32_bf16 v[8:11], v[228:231], v[236:239], v[8:11]
	s_waitcnt lgkmcnt(6)
	v_mfma_f32_16x16x32_bf16 v[80:83], v[216:219], v[240:243], v[80:83]
	ds_read_b128 v[236:239], v211 offset:33792
	v_mfma_f32_16x16x32_bf16 v[52:55], v[220:223], v[240:243], v[52:55]
	v_mfma_f32_16x16x32_bf16 v[20:23], v[224:227], v[240:243], v[20:23]
	v_mfma_f32_16x16x32_bf16 v[4:7], v[228:231], v[240:243], v[4:7]
	s_waitcnt lgkmcnt(6)
	v_mfma_f32_16x16x32_bf16 v[72:75], v[216:219], v[244:247], v[72:75]
	ds_read_b128 v[240:243], v211 offset:34816
	v_mfma_f32_16x16x32_bf16 v[48:51], v[220:223], v[244:247], v[48:51]
	v_mfma_f32_16x16x32_bf16 v[16:19], v[224:227], v[244:247], v[16:19]
	v_mfma_f32_16x16x32_bf16 v[0:3], v[228:231], v[244:247], v[0:3]
	ds_read_b128 v[244:247], v211 offset:35840
	s_waitcnt lgkmcnt(3)
	v_mfma_f32_16x16x32_bf16 v[124:127], v[186:189], v[232:235], v[124:127]
	v_lshl_add_u64 v[248:249], v[144:145], 0, s[54:55]
	v_mfma_f32_16x16x32_bf16 v[108:111], v[190:193], v[232:235], v[108:111]
	s_add_i32 m0, s100, 0x10000
	v_mfma_f32_16x16x32_bf16 v[88:91], v[194:197], v[232:235], v[88:91]
	s_waitcnt vmcnt(4)
	s_barrier
; #define BIG_SYNC(N)                                              \
;   asm volatile("s_waitcnt vmcnt(%0)" ::"n"(N) : "memory");       \
;   __builtin_amdgcn_s_barrier();                                  \
;   asm volatile("" ::: "memory");                                 \
;   __builtin_amdgcn_sched_barrier(0);
; template <int NK, bool BNT = false> ...
;     ...
;   auto kstep = [&](int T, int cur, int nxt, bool do_stage) {
;     const unsigned char* sa = smem + cur * BIG_STAGE;
;     bf16x8 af[4], bfr[4];
; #pragma unroll
;     for (int m = 0; m < 4; ++m) af[m] = *reinterpret_cast<const bf16x8*>(sa + aoff + m * 1024);
; #pragma unroll
;     for (int n = 0; n < 4; ++n) bfr[n] = *reinterpret_cast<const bf16x8*>(sa + boff + n * 1024);
;     __builtin_amdgcn_sched_barrier(0);
;     if (do_stage) stage(T + 3, nxt);
; #pragma unroll
;     for (int m = 0; m < 4; ++m)
; #pragma unroll
;       for (int n = 0; n < 4; ++n) acc[m][n] = __builtin_amdgcn_mfma_f32_16x16x32_bf16(af[m], bfr[n], acc[m][n], 0, 0, 0);
;     if (do_stage) {
; #pragma unroll
;       for (int q = 0; q < NG; ++q) {
;         __builtin_amdgcn_sched_group_barrier(0x008, 3, 0);
;         __builtin_amdgcn_sched_group_barrier(0x010, 1, 0);
;       }
;       __builtin_amdgcn_sched_group_barrier(0x008, 16 - 3 * NG, 0);
;     }
;     __builtin_amdgcn_sched_barrier(0);
; #pragma unroll
;     for (int n = 0; n < 4; ++n) bfr[n] = *reinterpret_cast<const bf16x8*>(sa + boff + (4 + n) * 1024);
; #pragma unroll
;     for (int m = 0; m < 4; ++m)
; #pragma unroll
;       for (int n = 0; n < 4; ++n)
;         acc[m][4 + n] = __builtin_amdgcn_mfma_f32_16x16x32_bf16(af[m], bfr[n], acc[m][4 + n], 0, 0, 0);
;     __builtin_amdgcn_sched_barrier(0);
;     ...
;   for (int it = 0; it < NK / 4 - 1; ++it) {
;     const int t = it * 4;
;     BIG_SYNC(2 * NG); kstep(t, 0, 3, true);
;     BIG_SYNC(2 * NG); kstep(t + 1, 1, 0, true);
;     BIG_SYNC(2 * NG); kstep(t + 2, 2, 1, true);
;     BIG_SYNC(2 * NG); kstep(t + 3, 3, 2, true);
;   }
;   BIG_SYNC(2 * NG); kstep(NK - 4, 0, 3, true);
	v_lshl_add_u64 v[144:145], v[144:145], 0, s[56:57]
	v_mfma_f32_16x16x32_bf16 v[44:47], v[202:205], v[232:235], v[44:47]
	v_lshl_add_u64 v[250:251], v[142:143], 0, s[54:55]
	s_waitcnt lgkmcnt(2)
	v_mfma_f32_16x16x32_bf16 v[120:123], v[186:189], v[236:239], v[120:123]
	ds_read_b128 v[232:235], v211 offset:36864
	v_mfma_f32_16x16x32_bf16 v[104:107], v[190:193], v[236:239], v[104:107]
	v_lshl_add_u64 v[142:143], v[142:143], 0, s[56:57]
	v_mfma_f32_16x16x32_bf16 v[76:79], v[194:197], v[236:239], v[76:79]
	global_load_lds_dwordx4 v[248:249], off
	v_mfma_f32_16x16x32_bf16 v[40:43], v[202:205], v[236:239], v[40:43]
	s_add_i32 m0, s100, 0x12000
	s_waitcnt lgkmcnt(2)
	v_mfma_f32_16x16x32_bf16 v[116:119], v[186:189], v[240:243], v[116:119]
	ds_read_b128 v[236:239], v211 offset:37888
	v_mfma_f32_16x16x32_bf16 v[100:103], v[190:193], v[240:243], v[100:103]
	global_load_lds_dwordx4 v[144:145], off
	v_mfma_f32_16x16x32_bf16 v[68:71], v[194:197], v[240:243], v[68:71]
	s_add_i32 m0, s100, 0x14000
	v_mfma_f32_16x16x32_bf16 v[36:39], v[202:205], v[240:243], v[36:39]
	global_load_lds_dwordx4 v[250:251], off
	s_waitcnt lgkmcnt(2)
	v_mfma_f32_16x16x32_bf16 v[112:115], v[186:189], v[244:247], v[112:115]
	ds_read_b128 v[240:243], v211 offset:38912
	v_mfma_f32_16x16x32_bf16 v[96:99], v[190:193], v[244:247], v[96:99]
	s_add_i32 m0, s100, 0x16000
	v_mfma_f32_16x16x32_bf16 v[64:67], v[194:197], v[244:247], v[64:67]
	global_load_lds_dwordx4 v[142:143], off
	v_mfma_f32_16x16x32_bf16 v[32:35], v[202:205], v[244:247], v[32:35]
	s_waitcnt lgkmcnt(2)
	v_mfma_f32_16x16x32_bf16 v[92:95], v[186:189], v[232:235], v[92:95]
	ds_read_b128 v[244:247], v211 offset:39936
	v_mfma_f32_16x16x32_bf16 v[60:63], v[190:193], v[232:235], v[60:63]
	ds_read_b128 v[216:219], v167
	v_mfma_f32_16x16x32_bf16 v[28:31], v[194:197], v[232:235], v[28:31]
	ds_read_b128 v[220:223], v167 offset:1024
	v_mfma_f32_16x16x32_bf16 v[12:15], v[202:205], v[232:235], v[12:15]
	ds_read_b128 v[224:227], v167 offset:2048
	s_waitcnt lgkmcnt(5)
	v_mfma_f32_16x16x32_bf16 v[84:87], v[186:189], v[236:239], v[84:87]
	ds_read_b128 v[228:231], v167 offset:3072
	ds_read_b128 v[232:235], v168 offset:16384
	v_mfma_f32_16x16x32_bf16 v[56:59], v[190:193], v[236:239], v[56:59]
	v_mfma_f32_16x16x32_bf16 v[24:27], v[194:197], v[236:239], v[24:27]
	v_mfma_f32_16x16x32_bf16 v[8:11], v[202:205], v[236:239], v[8:11]
	s_waitcnt lgkmcnt(6)
	v_mfma_f32_16x16x32_bf16 v[80:83], v[186:189], v[240:243], v[80:83]
	ds_read_b128 v[236:239], v168 offset:17408
	v_mfma_f32_16x16x32_bf16 v[52:55], v[190:193], v[240:243], v[52:55]
	v_mfma_f32_16x16x32_bf16 v[20:23], v[194:197], v[240:243], v[20:23]
	v_mfma_f32_16x16x32_bf16 v[4:7], v[202:205], v[240:243], v[4:7]
	s_waitcnt lgkmcnt(6)
	v_mfma_f32_16x16x32_bf16 v[72:75], v[186:189], v[244:247], v[72:75]
	ds_read_b128 v[240:243], v168 offset:18432
	v_mfma_f32_16x16x32_bf16 v[48:51], v[190:193], v[244:247], v[48:51]
	v_mfma_f32_16x16x32_bf16 v[16:19], v[194:197], v[244:247], v[16:19]
	v_mfma_f32_16x16x32_bf16 v[0:3], v[202:205], v[244:247], v[0:3]
	ds_read_b128 v[244:247], v168 offset:19456
	s_add_u32 s36, s36, 0x8000
	s_addc_u32 s37, s37, 0
	s_cmp_lg_u32 s36, 0x38000
	s_cbranch_scc1 .LBB0_68
	v_add_u32_e32 v162, 0x10000, v167
	v_or_b32_e32 v163, 0x10000, v169
	v_add_u32_e32 v164, 0x10400, v169
	v_add_u32_e32 v165, 0x10800, v169
	v_add_u32_e32 v172, 0x10c00, v169
	v_add_u32_e32 v173, 0x11000, v169
	v_add_u32_e32 v174, 0x11400, v169
	v_add_u32_e32 v175, 0x11800, v169
	v_add_u32_e32 v178, 0x11c00, v169
	v_add_u32_e32 v176, 0x18000, v167
	v_or_b32_e32 v179, 0x18000, v169
	v_add_u32_e32 v180, 0x18400, v169
	v_add_u32_e32 v181, 0x18800, v169
	v_add_u32_e32 v182, 0x18c00, v169
	v_add_u32_e32 v142, 0x19000, v169
	v_add_u32_e32 v143, 0x19400, v169
	v_add_u32_e32 v144, 0x19800, v169
	v_add_u32_e32 v145, 0x19c00, v169
	s_waitcnt lgkmcnt(3)
	v_mfma_f32_16x16x32_bf16 v[124:127], v[216:219], v[232:235], v[124:127]
	s_sext_i32_i8 s9, s14
	s_mov_b64 s[18:19], 0x3e000
	v_mfma_f32_16x16x32_bf16 v[108:111], v[220:223], v[232:235], v[108:111]
	v_readfirstlane_b32 s11, v158
	v_lshl_add_u64 v[150:151], v[130:131], 0, s[18:19]
	v_mfma_f32_16x16x32_bf16 v[88:91], v[224:227], v[232:235], v[88:91]
	s_waitcnt vmcnt(4)
	s_barrier
	v_lshl_add_u64 v[198:199], v[128:129], 0, s[18:19]
	s_mov_b32 m0, s11
	v_mfma_f32_16x16x32_bf16 v[44:47], v[228:231], v[232:235], v[44:47]
	s_mov_b64 s[18:19], 0x7e000
	v_readfirstlane_b32 s11, v159
	s_waitcnt lgkmcnt(2)
	v_mfma_f32_16x16x32_bf16 v[120:123], v[216:219], v[236:239], v[120:123]
	ds_read_b128 v[232:235], v168 offset:20480
	v_mfma_f32_16x16x32_bf16 v[104:107], v[220:223], v[236:239], v[104:107]
	v_lshl_add_u64 v[130:131], v[130:131], 0, s[18:19]
	v_lshl_add_u64 v[128:129], v[128:129], 0, s[18:19]
	v_mfma_f32_16x16x32_bf16 v[76:79], v[224:227], v[236:239], v[76:79]
	global_load_lds_dwordx4 v[150:151], off
	s_mov_b32 m0, s11
	v_mfma_f32_16x16x32_bf16 v[40:43], v[228:231], v[236:239], v[40:43]
	v_readfirstlane_b32 s11, v160
	s_waitcnt lgkmcnt(2)
	v_mfma_f32_16x16x32_bf16 v[116:119], v[216:219], v[240:243], v[116:119]
	ds_read_b128 v[236:239], v168 offset:21504
	v_mfma_f32_16x16x32_bf16 v[100:103], v[220:223], v[240:243], v[100:103]
	global_load_lds_dwordx4 v[130:131], off
	v_mfma_f32_16x16x32_bf16 v[68:71], v[224:227], v[240:243], v[68:71]
	s_mov_b32 m0, s11
	v_mfma_f32_16x16x32_bf16 v[36:39], v[228:231], v[240:243], v[36:39]
	v_readfirstlane_b32 s11, v161
	s_waitcnt lgkmcnt(2)
; #define BIG_SYNC(N)                                              \
;   asm volatile("s_waitcnt vmcnt(%0)" ::"n"(N) : "memory");       \
;   __builtin_amdgcn_s_barrier();                                  \
;   asm volatile("" ::: "memory");                                 \
;   __builtin_amdgcn_sched_barrier(0);
; template <int NK, bool BNT = false> ...
;     ...
;   auto kstep = [&](int T, int cur, int nxt, bool do_stage) {
;     const unsigned char* sa = smem + cur * BIG_STAGE;
;     bf16x8 af[4], bfr[4];
; #pragma unroll
;     for (int m = 0; m < 4; ++m) af[m] = *reinterpret_cast<const bf16x8*>(sa + aoff + m * 1024);
; #pragma unroll
;     for (int n = 0; n < 4; ++n) bfr[n] = *reinterpret_cast<const bf16x8*>(sa + boff + n * 1024);
;     __builtin_amdgcn_sched_barrier(0);
;     if (do_stage) stage(T + 3, nxt);
; #pragma unroll
;     for (int m = 0; m < 4; ++m)
; #pragma unroll
;       for (int n = 0; n < 4; ++n) acc[m][n] = __builtin_amdgcn_mfma_f32_16x16x32_bf16(af[m], bfr[n], acc[m][n], 0, 0, 0);
;     if (do_stage) {
; #pragma unroll
;       for (int q = 0; q < NG; ++q) {
;         __builtin_amdgcn_sched_group_barrier(0x008, 3, 0);
;         __builtin_amdgcn_sched_group_barrier(0x010, 1, 0);
;       }
;       __builtin_amdgcn_sched_group_barrier(0x008, 16 - 3 * NG, 0);
;     }
;     __builtin_amdgcn_sched_barrier(0);
; #pragma unroll
;     for (int n = 0; n < 4; ++n) bfr[n] = *reinterpret_cast<const bf16x8*>(sa + boff + (4 + n) * 1024);
; #pragma unroll
;     for (int m = 0; m < 4; ++m)
; #pragma unroll
;       for (int n = 0; n < 4; ++n)
;         acc[m][4 + n] = __builtin_amdgcn_mfma_f32_16x16x32_bf16(af[m], bfr[n], acc[m][4 + n], 0, 0, 0);
;     __builtin_amdgcn_sched_barrier(0);
;     ...
;   BIG_SYNC(2 * NG); kstep(NK - 4, 0, 3, true);
;   BIG_SYNC(2 * NG); kstep(NK - 3, 1, 0, false);
;   BIG_SYNC(NG);     kstep(NK - 2, 2, 0, false);
	v_mfma_f32_16x16x32_bf16 v[112:115], v[216:219], v[244:247], v[112:115]
	ds_read_b128 v[240:243], v168 offset:22528
	v_mfma_f32_16x16x32_bf16 v[96:99], v[220:223], v[244:247], v[96:99]
	global_load_lds_dwordx4 v[198:199], off
	v_mfma_f32_16x16x32_bf16 v[64:67], v[224:227], v[244:247], v[64:67]
	s_mov_b32 m0, s11
	v_mfma_f32_16x16x32_bf16 v[32:35], v[228:231], v[244:247], v[32:35]
	global_load_lds_dwordx4 v[128:129], off
	s_waitcnt lgkmcnt(2)
	v_mfma_f32_16x16x32_bf16 v[92:95], v[216:219], v[232:235], v[92:95]
	ds_read_b128 v[244:247], v168 offset:23552
	v_mfma_f32_16x16x32_bf16 v[60:63], v[220:223], v[232:235], v[60:63]
	ds_read_b128 v[186:189], v167 offset:32768
	v_mfma_f32_16x16x32_bf16 v[28:31], v[224:227], v[232:235], v[28:31]
	ds_read_b128 v[190:193], v167 offset:33792
	v_mfma_f32_16x16x32_bf16 v[12:15], v[228:231], v[232:235], v[12:15]
	ds_read_b128 v[194:197], v167 offset:34816
	s_waitcnt lgkmcnt(5)
	v_mfma_f32_16x16x32_bf16 v[84:87], v[216:219], v[236:239], v[84:87]
	ds_read_b128 v[202:205], v167 offset:35840
	ds_read_b128 v[232:235], v168 offset:49152
	v_mfma_f32_16x16x32_bf16 v[56:59], v[220:223], v[236:239], v[56:59]
	v_mfma_f32_16x16x32_bf16 v[24:27], v[224:227], v[236:239], v[24:27]
	v_mfma_f32_16x16x32_bf16 v[8:11], v[228:231], v[236:239], v[8:11]
	s_waitcnt lgkmcnt(6)
	v_mfma_f32_16x16x32_bf16 v[80:83], v[216:219], v[240:243], v[80:83]
	ds_read_b128 v[236:239], v168 offset:50176
	v_mfma_f32_16x16x32_bf16 v[52:55], v[220:223], v[240:243], v[52:55]
	v_mfma_f32_16x16x32_bf16 v[20:23], v[224:227], v[240:243], v[20:23]
	v_mfma_f32_16x16x32_bf16 v[4:7], v[228:231], v[240:243], v[4:7]
	s_waitcnt lgkmcnt(6)
	v_mfma_f32_16x16x32_bf16 v[72:75], v[216:219], v[244:247], v[72:75]
	ds_read_b128 v[240:243], v168 offset:51200
	v_mfma_f32_16x16x32_bf16 v[48:51], v[220:223], v[244:247], v[48:51]
	v_mfma_f32_16x16x32_bf16 v[16:19], v[224:227], v[244:247], v[16:19]
	v_mfma_f32_16x16x32_bf16 v[0:3], v[228:231], v[244:247], v[0:3]
	ds_read_b128 v[244:247], v168 offset:52224
	s_waitcnt lgkmcnt(3)
	v_mfma_f32_16x16x32_bf16 v[124:127], v[186:189], v[232:235], v[124:127]
	v_mfma_f32_16x16x32_bf16 v[108:111], v[190:193], v[232:235], v[108:111]
	v_mfma_f32_16x16x32_bf16 v[88:91], v[194:197], v[232:235], v[88:91]
	v_mfma_f32_16x16x32_bf16 v[44:47], v[202:205], v[232:235], v[44:47]
	s_waitcnt vmcnt(4)
	s_barrier
	s_waitcnt lgkmcnt(2)
	v_mfma_f32_16x16x32_bf16 v[120:123], v[186:189], v[236:239], v[120:123]
	ds_read_b128 v[232:235], v168 offset:53248
	v_mfma_f32_16x16x32_bf16 v[104:107], v[190:193], v[236:239], v[104:107]
	v_mfma_f32_16x16x32_bf16 v[76:79], v[194:197], v[236:239], v[76:79]
	v_mfma_f32_16x16x32_bf16 v[40:43], v[202:205], v[236:239], v[40:43]
	s_waitcnt lgkmcnt(2)
	v_mfma_f32_16x16x32_bf16 v[116:119], v[186:189], v[240:243], v[116:119]
	ds_read_b128 v[236:239], v168 offset:54272
	v_mfma_f32_16x16x32_bf16 v[100:103], v[190:193], v[240:243], v[100:103]
	v_mfma_f32_16x16x32_bf16 v[68:71], v[194:197], v[240:243], v[68:71]
	v_mfma_f32_16x16x32_bf16 v[36:39], v[202:205], v[240:243], v[36:39]
	s_waitcnt lgkmcnt(2)
	v_mfma_f32_16x16x32_bf16 v[112:115], v[186:189], v[244:247], v[112:115]
	ds_read_b128 v[240:243], v168 offset:55296
	v_mfma_f32_16x16x32_bf16 v[96:99], v[190:193], v[244:247], v[96:99]
	v_mfma_f32_16x16x32_bf16 v[64:67], v[194:197], v[244:247], v[64:67]
	v_mfma_f32_16x16x32_bf16 v[32:35], v[202:205], v[244:247], v[32:35]
	s_waitcnt lgkmcnt(2)
	v_mfma_f32_16x16x32_bf16 v[92:95], v[186:189], v[232:235], v[92:95]
	ds_read_b128 v[244:247], v168 offset:56320
	v_mfma_f32_16x16x32_bf16 v[60:63], v[190:193], v[232:235], v[60:63]
	v_mfma_f32_16x16x32_bf16 v[28:31], v[194:197], v[232:235], v[28:31]
	v_mfma_f32_16x16x32_bf16 v[12:15], v[202:205], v[232:235], v[12:15]
	s_waitcnt lgkmcnt(2)
	v_mfma_f32_16x16x32_bf16 v[84:87], v[186:189], v[236:239], v[84:87]
	v_mfma_f32_16x16x32_bf16 v[56:59], v[190:193], v[236:239], v[56:59]
	v_mfma_f32_16x16x32_bf16 v[24:27], v[194:197], v[236:239], v[24:27]
	v_mfma_f32_16x16x32_bf16 v[8:11], v[202:205], v[236:239], v[8:11]
	s_waitcnt lgkmcnt(1)
	v_mfma_f32_16x16x32_bf16 v[80:83], v[186:189], v[240:243], v[80:83]
	v_mfma_f32_16x16x32_bf16 v[52:55], v[190:193], v[240:243], v[52:55]
	v_mfma_f32_16x16x32_bf16 v[20:23], v[194:197], v[240:243], v[20:23]
	v_mfma_f32_16x16x32_bf16 v[4:7], v[202:205], v[240:243], v[4:7]
	s_waitcnt lgkmcnt(0)
	v_mfma_f32_16x16x32_bf16 v[72:75], v[186:189], v[244:247], v[72:75]
	v_mfma_f32_16x16x32_bf16 v[48:51], v[190:193], v[244:247], v[48:51]
	v_mfma_f32_16x16x32_bf16 v[16:19], v[194:197], v[244:247], v[16:19]
	v_mfma_f32_16x16x32_bf16 v[0:3], v[202:205], v[244:247], v[0:3]
	v_mov_b32_e32 v186, 0xf149f2ca
	v_mov_b32_e32 v187, 0x3c0881c4
	v_mov_b32_e32 v188, 0xbab64f3b
	v_mov_b32_e32 v189, 0x24800
	v_mov_b32_e32 v190, 1
	v_mov_b32_e32 v191, 0x24804
	v_mov_b32_e32 v192, 0xfcf
	v_mov_b32_e32 v193, 0x7cf
	v_mov_b32_e32 v194, 0xfdf
	v_mov_b32_e32 v195, 0x7df
	v_mov_b32_e32 v196, 0xfef
	v_mov_b32_e32 v197, 0x7ef
	v_mov_b32_e32 v198, 0xfff
	v_mov_b32_e32 v199, 0x7ff
	v_mov_b32_e32 v200, 0x20000
	v_mov_b32_e32 v201, 0xf8f
	v_mov_b32_e32 v202, 0x78f
	v_mov_b32_e32 v203, 0xf9f
	v_mov_b32_e32 v204, 0x79f
	v_mov_b32_e32 v205, 0xfaf
	v_mov_b32_e32 v210, 0x7f800000
	v_not_b32_e32 v211, 63
	v_not_b32_e32 v212, 31
	v_mov_b32_e32 v213, 0x7fc00000
	s_waitcnt vmcnt(4)
	s_barrier
; #define BIG_SYNC(N)                                              \
;   asm volatile("s_waitcnt vmcnt(%0)" ::"n"(N) : "memory");       \
;   __builtin_amdgcn_s_barrier();                                  \
;   asm volatile("" ::: "memory");                                 \
;   __builtin_amdgcn_sched_barrier(0);
; template <int NK, bool BNT = false> ...
;     ...
;   auto kstep = [&](int T, int cur, int nxt, bool do_stage) {
;     const unsigned char* sa = smem + cur * BIG_STAGE;
;     bf16x8 af[4], bfr[4];
; #pragma unroll
;     for (int m = 0; m < 4; ++m) af[m] = *reinterpret_cast<const bf16x8*>(sa + aoff + m * 1024);
; #pragma unroll
;     for (int n = 0; n < 4; ++n) bfr[n] = *reinterpret_cast<const bf16x8*>(sa + boff + n * 1024);
;     __builtin_amdgcn_sched_barrier(0);
;     if (do_stage) stage(T + 3, nxt);
; #pragma unroll
;     for (int m = 0; m < 4; ++m)
; #pragma unroll
;       for (int n = 0; n < 4; ++n) acc[m][n] = __builtin_amdgcn_mfma_f32_16x16x32_bf16(af[m], bfr[n], acc[m][n], 0, 0, 0);
;     if (do_stage) {
; #pragma unroll
;       for (int q = 0; q < NG; ++q) {
;         __builtin_amdgcn_sched_group_barrier(0x008, 3, 0);
;         __builtin_amdgcn_sched_group_barrier(0x010, 1, 0);
;       }
;       __builtin_amdgcn_sched_group_barrier(0x008, 16 - 3 * NG, 0);
;     }
;     __builtin_amdgcn_sched_barrier(0);
; #pragma unroll
;     for (int n = 0; n < 4; ++n) bfr[n] = *reinterpret_cast<const bf16x8*>(sa + boff + (4 + n) * 1024);
; #pragma unroll
;     for (int m = 0; m < 4; ++m)
; #pragma unroll
;       for (int n = 0; n < 4; ++n)
;         acc[m][4 + n] = __builtin_amdgcn_mfma_f32_16x16x32_bf16(af[m], bfr[n], acc[m][4 + n], 0, 0, 0);
;     __builtin_amdgcn_sched_barrier(0);
;     ...
;   BIG_SYNC(NG);     kstep(NK - 2, 2, 0, false);
;   BIG_SYNC(0);      kstep(NK - 1, 3, 0, false);
	ds_read_b128 v[128:131], v162
	ds_read_b128 v[138:141], v162 offset:1024
	ds_read_b128 v[146:149], v162 offset:2048
	ds_read_b128 v[154:157], v162 offset:3072
	ds_read_b128 v[158:161], v163
	ds_read_b128 v[216:219], v164
	ds_read_b128 v[162:165], v165
	ds_read_b128 v[220:223], v172
	s_waitcnt lgkmcnt(0)
	v_mfma_f32_16x16x32_bf16 v[124:127], v[128:131], v[158:161], v[124:127]
	v_mfma_f32_16x16x32_bf16 v[116:119], v[128:131], v[162:165], v[116:119]
	v_mfma_f32_16x16x32_bf16 v[112:115], v[128:131], v[220:223], v[112:115]
	v_mfma_f32_16x16x32_bf16 v[104:107], v[138:141], v[216:219], v[104:107]
	v_mfma_f32_16x16x32_bf16 v[100:103], v[138:141], v[162:165], v[100:103]
	v_mfma_f32_16x16x32_bf16 v[96:99], v[138:141], v[220:223], v[96:99]
	v_mfma_f32_16x16x32_bf16 v[68:71], v[146:149], v[162:165], v[68:71]
	v_mfma_f32_16x16x32_bf16 v[64:67], v[146:149], v[220:223], v[64:67]
	v_mfma_f32_16x16x32_bf16 v[44:47], v[154:157], v[158:161], v[44:47]
	v_mfma_f32_16x16x32_bf16 v[40:43], v[154:157], v[216:219], v[40:43]
	v_mfma_f32_16x16x32_bf16 v[36:39], v[154:157], v[162:165], v[36:39]
	v_mfma_f32_16x16x32_bf16 v[32:35], v[154:157], v[220:223], v[32:35]
	v_mfma_f32_16x16x32_bf16 v[120:123], v[128:131], v[216:219], v[120:123]
	v_mfma_f32_16x16x32_bf16 v[224:227], v[138:141], v[158:161], v[108:111]
	v_mfma_f32_16x16x32_bf16 v[228:231], v[146:149], v[158:161], v[88:91]
	v_mfma_f32_16x16x32_bf16 v[232:235], v[146:149], v[216:219], v[76:79]
	s_nop 2
	ds_read_b128 v[76:79], v173
	ds_read_b128 v[88:91], v174
	s_waitcnt lgkmcnt(0)
	v_mfma_f32_16x16x32_bf16 v[158:161], v[128:131], v[76:79], v[92:95]
	s_nop 2
	ds_read_b128 v[92:95], v178
	v_mfma_f32_16x16x32_bf16 v[162:165], v[128:131], v[88:91], v[84:87]
	s_nop 2
	ds_read_b128 v[84:87], v175
	s_waitcnt lgkmcnt(0)
	v_mfma_f32_16x16x32_bf16 v[172:175], v[128:131], v[84:87], v[80:83]
	v_mfma_f32_16x16x32_bf16 v[128:131], v[128:131], v[92:95], v[72:75]
	v_mfma_f32_16x16x32_bf16 v[216:219], v[138:141], v[76:79], v[60:63]
	v_mfma_f32_16x16x32_bf16 v[220:223], v[138:141], v[88:91], v[56:59]
	v_mfma_f32_16x16x32_bf16 v[52:55], v[138:141], v[84:87], v[52:55]
	v_mfma_f32_16x16x32_bf16 v[48:51], v[138:141], v[92:95], v[48:51]
	v_mfma_f32_16x16x32_bf16 v[138:141], v[146:149], v[76:79], v[28:31]
	v_mfma_f32_16x16x32_bf16 v[236:239], v[146:149], v[88:91], v[24:27]
	v_mfma_f32_16x16x32_bf16 v[20:23], v[146:149], v[84:87], v[20:23]
	v_mfma_f32_16x16x32_bf16 v[16:19], v[146:149], v[92:95], v[16:19]
	v_mfma_f32_16x16x32_bf16 v[146:149], v[154:157], v[76:79], v[12:15]
	v_mfma_f32_16x16x32_bf16 v[0:3], v[154:157], v[92:95], v[0:3]
	v_mfma_f32_16x16x32_bf16 v[240:243], v[154:157], v[88:91], v[8:11]
	v_mfma_f32_16x16x32_bf16 v[244:247], v[154:157], v[84:87], v[4:7]
	s_waitcnt vmcnt(0)
	s_barrier
	s_nop 1
	ds_read_b128 v[4:7], v176
	ds_read_b128 v[8:11], v176 offset:1024
	ds_read_b128 v[154:157], v176 offset:2048
	ds_read_b128 v[12:15], v179
	ds_read_b128 v[24:27], v180
	ds_read_b128 v[28:31], v181
	ds_read_b128 v[56:59], v182
	ds_read_b128 v[248:251], v176 offset:3072
	s_waitcnt lgkmcnt(0)
	v_mfma_f32_16x16x32_bf16 v[108:111], v[4:7], v[24:27], v[120:123]
	v_mfma_f32_16x16x32_bf16 v[92:95], v[4:7], v[28:31], v[116:119]
	v_mfma_f32_16x16x32_bf16 v[76:79], v[4:7], v[56:59], v[112:115]
	v_mfma_f32_16x16x32_bf16 v[104:107], v[8:11], v[24:27], v[104:107]
	v_mfma_f32_16x16x32_bf16 v[88:91], v[8:11], v[28:31], v[100:103]
	v_mfma_f32_16x16x32_bf16 v[72:75], v[8:11], v[56:59], v[96:99]
	v_mfma_f32_16x16x32_bf16 v[100:103], v[154:157], v[24:27], v[232:235]
	v_mfma_f32_16x16x32_bf16 v[84:87], v[154:157], v[28:31], v[68:71]
	v_mfma_f32_16x16x32_bf16 v[68:71], v[154:157], v[56:59], v[64:67]
	v_mfma_f32_16x16x32_bf16 v[116:119], v[248:251], v[12:15], v[44:47]
	v_mfma_f32_16x16x32_bf16 v[96:99], v[248:251], v[24:27], v[40:43]
	v_mfma_f32_16x16x32_bf16 v[80:83], v[248:251], v[28:31], v[36:39]
	v_mfma_f32_16x16x32_bf16 v[64:67], v[248:251], v[56:59], v[32:35]
	v_mfma_f32_16x16x32_bf16 v[178:181], v[4:7], v[12:15], v[124:127]
	v_mfma_f32_16x16x32_bf16 v[224:227], v[8:11], v[12:15], v[224:227]
	v_mfma_f32_16x16x32_bf16 v[120:123], v[154:157], v[12:15], v[228:231]
	ds_read_b128 v[32:35], v142
	ds_read_b128 v[112:115], v143
	ds_read_b128 v[124:127], v144
	ds_read_b128 v[142:145], v145
	s_waitcnt lgkmcnt(0)
; __device__ __forceinline__ float bf2f(bf16_t b) { return __uint_as_float(((unsigned)b) << 16); }
; __device__ __forceinline__ int widen_off(int fq) { return ((fq & 1) << 4) + ((fq >> 1) << 3); }
; template <int MODE, int NSUB>
; __device__ __forceinline__ void epilogue(const Params& p, int layer, f32x4 (&acc)[4][NSUB], int tm, int tn, int g,
;                                          const float* s_rstd, const int tid_in) {
;     ...
;   } else if constexpr (MODE == EPI_RES) {
;     const int fb = tm * 128 + wr * 64 + fq * 4;
;     const int tb = tn * (NSUB * 32) + wc * (NSUB * 16) + fr;
;     const int fw = tm * 128 + wr * 64 + widen_off(fq);
;     u32x4 curw[2], nxtw[2];
; #pragma unroll
;     for (int mp = 0; mp < 2; ++mp) curw[mp] = *reinterpret_cast<const u32x4*>(p.xb + blk(tb, fw + mp * 32, 32));
; #pragma unroll
;     for (int n = 0; n < NSUB; ++n) {
;       if (n + 1 < NSUB) {
; #pragma unroll
;         for (int mp = 0; mp < 2; ++mp) nxtw[mp] = *reinterpret_cast<const u32x4*>(p.xb + blk(tb + (n + 1) * 16, fw + mp * 32, 32));
;       }
;       bf16x4 cur[4];
;       unwiden_pair(curw[0], cur[0], cur[1]);
;       unwiden_pair(curw[1], cur[2], cur[3]);
;       const int t = tb + n * 16;
;       float ss = 0.f;
; #pragma unroll
;       for (int mp = 0; mp < 2; ++mp) {
;         bf16x4 pk[2];
; #pragma unroll
;         for (int h2 = 0; h2 < 2; ++h2) {
;           const int m = mp * 2 + h2;
;           const float x0 = bf2f((bf16_t)cur[m][0]) + acc[m][n][0], x1 = bf2f((bf16_t)cur[m][1]) + acc[m][n][1];
;           const float x2 = bf2f((bf16_t)cur[m][2]) + acc[m][n][2], x3 = bf2f((bf16_t)cur[m][3]) + acc[m][n][3];
;           ss += x0 * x0 + x1 * x1 + x2 * x2 + x3 * x3;
;           pk[h2] = pack4(x0, x1, x2, x3);
;         }
;         const int f = tm * 128 + wr * 64 + mp * 32 + widen_off(fq);
;         *reinterpret_cast<u32x4*>(p.xb + blk(t, f, 32)) = widen_pair(pk[0], pk[1]);
;       }
;       ss = red_fq(ss);
;       if (fq == 0) p.part[(long)t * 16 + tm * 2 + wr] = ss;
;       curw[0] = nxtw[0];
;       curw[1] = nxtw[1];
;     }
	v_mfma_f32_16x16x32_bf16 v[60:63], v[4:7], v[32:35], v[158:161]
	v_mfma_f32_16x16x32_bf16 v[44:47], v[4:7], v[112:115], v[162:165]
	v_mfma_f32_16x16x32_bf16 v[28:31], v[4:7], v[124:127], v[172:175]
	v_mfma_f32_16x16x32_bf16 v[12:15], v[4:7], v[142:145], v[128:131]
	v_mfma_f32_16x16x32_bf16 v[56:59], v[8:11], v[32:35], v[216:219]
	v_mfma_f32_16x16x32_bf16 v[40:43], v[8:11], v[112:115], v[220:223]
	v_mfma_f32_16x16x32_bf16 v[24:27], v[8:11], v[124:127], v[52:55]
	v_mfma_f32_16x16x32_bf16 v[8:11], v[8:11], v[142:145], v[48:51]
	v_mfma_f32_16x16x32_bf16 v[52:55], v[154:157], v[32:35], v[138:141]
	v_mfma_f32_16x16x32_bf16 v[36:39], v[154:157], v[112:115], v[236:239]
	v_mfma_f32_16x16x32_bf16 v[20:23], v[154:157], v[124:127], v[20:23]
	v_mfma_f32_16x16x32_bf16 v[4:7], v[154:157], v[142:145], v[16:19]
	v_mfma_f32_16x16x32_bf16 v[48:51], v[248:251], v[32:35], v[146:149]
	v_mfma_f32_16x16x32_bf16 v[32:35], v[248:251], v[112:115], v[240:243]
	v_mfma_f32_16x16x32_bf16 v[16:19], v[248:251], v[124:127], v[244:247]
	v_mfma_f32_16x16x32_bf16 v[0:3], v[248:251], v[142:145], v[0:3]
	v_lshl_add_u32 v124, s9, 1, v170
	v_mov_b32_e32 v112, v215
	v_lshlrev_b32_e32 v113, 7, v124
	v_ashrrev_i32_e32 v138, 7, v112
	v_lshl_add_u32 v114, v138, 6, v113
	v_lshlrev_b32_e32 v113, 1, v112
	v_and_b32_e32 v113, 0x80, v113
	v_lshl_or_b32 v127, s10, 8, v113
	v_lshrrev_b32_e32 v113, 2, v112
	v_and_b32_e32 v125, 15, v112
	v_and_b32_e32 v113, 8, v113
	v_ashrrev_i32_e32 v115, 2, v127
	v_readlane_b32 s80, v253, 25
	v_ashrrev_i32_e32 v114, 5, v114
	v_bfe_u32 v126, v112, 4, 2
	v_and_or_b32 v112, v112, 16, v113
	v_lshlrev_b32_e32 v156, 6, v125
	v_mov_b32_e32 v157, v153
	v_readlane_b32 s84, v253, 29
	v_readlane_b32 s85, v253, 30
	v_add_u32_e32 v114, v114, v115
	v_lshlrev_b32_e32 v152, 1, v112
	v_lshl_add_u64 v[144:145], s[84:85], 0, v[156:157]
	v_ashrrev_i32_e32 v115, 31, v114
	v_lshl_add_u64 v[112:113], v[144:145], 0, v[152:153]
	v_lshlrev_b64 v[146:147], 13, v[114:115]
	v_or_b32_e32 v114, 1, v114
	v_lshl_add_u64 v[150:151], v[112:113], 0, v[146:147]
	v_ashrrev_i32_e32 v115, 31, v114
	global_load_dwordx4 v[158:161], v[150:151], off
	v_lshlrev_b64 v[148:149], 13, v[114:115]
	v_lshl_add_u64 v[154:155], v[112:113], 0, v[148:149]
	global_load_dwordx4 v[128:131], v[154:155], off
	v_and_b32_e32 v113, 64, v185
	v_xor_b32_e32 v112, 16, v185
	v_add_u32_e32 v113, 64, v113
	v_cmp_lt_i32_e32 vcc, v112, v113
	v_or_b32_e32 v142, v127, v125
	v_lshlrev_b32_e32 v140, 1, v124
	v_cndmask_b32_e32 v112, v185, v112, vcc
	v_lshlrev_b32_e32 v172, 2, v112
	v_xor_b32_e32 v112, 32, v185
	v_cmp_lt_i32_e32 vcc, v112, v113
	v_ashrrev_i32_e32 v141, 31, v140
	v_ashrrev_i32_e32 v139, 31, v138
	v_cndmask_b32_e32 v112, v185, v112, vcc
	v_lshlrev_b32_e32 v173, 2, v112
	v_cmp_eq_u32_e32 vcc, 0, v126
	global_load_dwordx4 v[124:127], v[150:151], off offset:1024
	global_load_dwordx4 v[112:115], v[154:155], off offset:1024
	v_readlane_b32 s81, v253, 26
	v_readlane_b32 s82, v253, 27
	v_readlane_b32 s83, v253, 28
	v_readlane_b32 s86, v253, 31
	v_readlane_b32 s87, v253, 32
	v_readlane_b32 s88, v253, 33
	v_readlane_b32 s89, v253, 34
	v_readlane_b32 s90, v253, 35
	v_readlane_b32 s91, v253, 36
	v_readlane_b32 s92, v253, 37
	v_readlane_b32 s93, v253, 38
	v_readlane_b32 s94, v253, 39
	v_readlane_b32 s95, v253, 40
	s_waitcnt vmcnt(0)
	v_mov_b32_e32 v143, v160
	s_nop 1
	v_permlane16_swap_b32_e32 v158, v143
	v_mov_b32_e32 v164, v161
	s_nop 1
	v_permlane16_swap_b32_e32 v159, v164
	v_mov_b32_e32 v176, v130
	v_mov_b32_e32 v182, v131
	v_and_b32_e32 v131, 0xffff0000, v158
	v_lshlrev_b32_e32 v130, 16, v158
	v_pk_add_f32 v[130:131], v[178:179], v[130:131]
	v_and_b32_e32 v161, 0xffff0000, v159
	v_lshlrev_b32_e32 v160, 16, v159
	v_pk_add_f32 v[162:163], v[180:181], v[160:161]
	v_pk_mul_f32 v[160:161], v[130:131], v[130:131]
	v_cvt_pk_bf16_f32 v178, v130, v131
	v_and_b32_e32 v131, 0xffff0000, v143
	v_lshlrev_b32_e32 v130, 16, v143
	v_pk_mul_f32 v[158:159], v[162:163], v[162:163]
	v_cvt_pk_bf16_f32 v179, v162, v163
	v_pk_add_f32 v[130:131], v[224:225], v[130:131]
	v_and_b32_e32 v163, 0xffff0000, v164
	v_lshlrev_b32_e32 v162, 16, v164
	v_pk_add_f32 v[174:175], v[226:227], v[162:163]
	v_pk_mul_f32 v[164:165], v[130:131], v[130:131]
	v_cvt_pk_bf16_f32 v180, v130, v131
	v_lshl_add_u64 v[130:131], s[84:85], 0, v[146:147]
	v_pk_mul_f32 v[162:163], v[174:175], v[174:175]
	v_cvt_pk_bf16_f32 v181, v174, v175
	v_lshl_add_u64 v[174:175], v[130:131], 0, v[156:157]
	v_permlane16_swap_b32_e32 v128, v176
	v_permlane16_swap_b32_e32 v178, v180
	v_permlane16_swap_b32_e32 v179, v181
	v_lshl_add_u64 v[174:175], v[174:175], 0, v[152:153]
	v_permlane16_swap_b32_e32 v129, v182
	global_store_dwordx4 v[174:175], v[178:181], off
	v_and_b32_e32 v175, 0xffff0000, v128
	v_lshlrev_b32_e32 v174, 16, v128
	v_pk_add_f32 v[120:121], v[120:121], v[174:175]
	v_and_b32_e32 v175, 0xffff0000, v129
	v_lshlrev_b32_e32 v174, 16, v129
	v_pk_add_f32 v[122:123], v[122:123], v[174:175]
	v_pk_mul_f32 v[128:129], v[120:121], v[120:121]
	v_pk_mul_f32 v[174:175], v[122:123], v[122:123]
	v_cvt_pk_bf16_f32 v120, v120, v121
	v_cvt_pk_bf16_f32 v121, v122, v123
	v_and_b32_e32 v123, 0xffff0000, v176
	v_lshlrev_b32_e32 v122, 16, v176
	v_pk_add_f32 v[116:117], v[116:117], v[122:123]
	v_and_b32_e32 v123, 0xffff0000, v182
	v_lshlrev_b32_e32 v122, 16, v182
	v_add_f32_e32 v143, v164, v165
	v_add_f32_e32 v160, v160, v161
	v_pk_add_f32 v[118:119], v[118:119], v[122:123]
	v_pk_mul_f32 v[122:123], v[116:117], v[116:117]
	v_add_f32_e32 v143, v162, v143
	v_add_f32_e32 v158, v158, v160
	v_add_f32_e32 v128, v128, v129
	v_pk_mul_f32 v[178:179], v[118:119], v[118:119]
	v_add_f32_e32 v143, v163, v143
	v_add_f32_e32 v158, v159, v158
	v_add_f32_e32 v128, v174, v128
	v_add_f32_e32 v122, v122, v123
	v_add_f32_e32 v143, v158, v143
	v_add_f32_e32 v128, v175, v128
	v_add_f32_e32 v122, v178, v122
	v_add_f32_e32 v128, v143, v128
	v_add_f32_e32 v122, v179, v122
	v_add_f32_e32 v143, v122, v128
	v_lshl_add_u64 v[128:129], s[84:85], 0, v[148:149]
	v_cvt_pk_bf16_f32 v122, v116, v117
	v_cvt_pk_bf16_f32 v123, v118, v119
	v_lshl_add_u64 v[116:117], v[128:129], 0, v[156:157]
	v_permlane16_swap_b32_e32 v120, v122
	v_permlane16_swap_b32_e32 v121, v123
	v_lshl_add_u64 v[116:117], v[116:117], 0, v[152:153]
	global_store_dwordx4 v[116:117], v[120:123], off
	ds_bpermute_b32 v116, v172, v143
	s_waitcnt lgkmcnt(0)
	v_add_f32_e32 v116, v143, v116
	ds_bpermute_b32 v117, v173, v116
	s_and_saveexec_b64 s[10:11], vcc
	s_cbranch_execz .LBB0_71
; template <int MODE, int NSUB>
; __device__ __forceinline__ void epilogue(const Params& p, int layer, f32x4 (&acc)[4][NSUB], int tm, int tn, int g,
;                                          const float* s_rstd, const int tid_in) {
;     ...
;       ss = red_fq(ss);
;       if (fq == 0) p.part[(long)t * 16 + tm * 2 + wr] = ss;
	v_ashrrev_i32_e32 v143, 31, v142
	v_readlane_b32 s64, v253, 25
	v_lshlrev_b64 v[118:119], 6, v[142:143]
	v_readlane_b32 s70, v253, 31
	v_readlane_b32 s71, v253, 32
	s_waitcnt lgkmcnt(0)
	v_add_f32_e32 v116, v116, v117
	v_readlane_b32 s65, v253, 26
	v_lshl_add_u64 v[118:119], s[70:71], 0, v[118:119]
	v_lshl_add_u64 v[118:119], v[140:141], 2, v[118:119]
	v_lshl_add_u64 v[118:119], v[138:139], 2, v[118:119]
	v_readlane_b32 s66, v253, 27
	v_readlane_b32 s67, v253, 28
	v_readlane_b32 s68, v253, 29
	v_readlane_b32 s69, v253, 30
	v_readlane_b32 s72, v253, 33
	v_readlane_b32 s73, v253, 34
	v_readlane_b32 s74, v253, 35
	v_readlane_b32 s75, v253, 36
	v_readlane_b32 s76, v253, 37
	v_readlane_b32 s77, v253, 38
	v_readlane_b32 s78, v253, 39
	v_readlane_b32 s79, v253, 40
	global_store_dword v[118:119], v116, off

; template <int NK, bool BNT = false> ...
;     ...
;   auto stage = [&](int kt, int bufc) {
;     unsigned char* sa = smem + bufc * BIG_STAGE;
;     const unsigned char* Ab = Abase + (long)kt * 8192 + soff;
;     const unsigned char* Bb = Bbase + (long)kt * 8192 + soff;
;     glds16(Ab, sa + sb0);
;     glds16(Ab + astride * 2, sa + 8192 + sb0);
;     if constexpr (BNT) {
;       glds16_nt(Bb, sa + 16384 + sb0);
;       glds16_nt(Bb + bstride * 2, sa + 24576 + sb0);
;     } else {
;       glds16(Bb, sa + 16384 + sb0);
;       glds16(Bb + bstride * 2, sa + 24576 + sb0);
;     }
;   };
;   const int rd = fr * 64 + ((fq ^ (((fr >> 3) & 1) << 1)) * 16);
;   const int aoff = wr * 64 * 64 + rd;
;   const int boff = 16384 + wc * 128 * 64 + rd;
;   auto kstep = [&](int T, int cur, int nxt, bool do_stage) {
;     const unsigned char* sa = smem + cur * BIG_STAGE;
;     bf16x8 af[4], bfr[4];
; #pragma unroll
;     for (int m = 0; m < 4; ++m) af[m] = *reinterpret_cast<const bf16x8*>(sa + aoff + m * 1024);
; #pragma unroll
;     for (int n = 0; n < 4; ++n) bfr[n] = *reinterpret_cast<const bf16x8*>(sa + boff + n * 1024);
;     __builtin_amdgcn_sched_barrier(0);
;     if (do_stage) stage(T + 3, nxt);
; #pragma unroll
;     for (int m = 0; m < 4; ++m)
; #pragma unroll
;       for (int n = 0; n < 4; ++n) acc[m][n] = __builtin_amdgcn_mfma_f32_16x16x32_bf16(af[m], bfr[n], acc[m][n], 0, 0, 0);
;     if (do_stage) {
; #pragma unroll
;       for (int q = 0; q < NG; ++q) {
;         __builtin_amdgcn_sched_group_barrier(0x008, 3, 0);
;         __builtin_amdgcn_sched_group_barrier(0x010, 1, 0);
;       }
;       __builtin_amdgcn_sched_group_barrier(0x008, 16 - 3 * NG, 0);
;     }
;     __builtin_amdgcn_sched_barrier(0);
; #pragma unroll
;     for (int n = 0; n < 4; ++n) bfr[n] = *reinterpret_cast<const bf16x8*>(sa + boff + (4 + n) * 1024);
; #pragma unroll
;     for (int m = 0; m < 4; ++m)
; #pragma unroll
;       for (int n = 0; n < 4; ++n)
;         acc[m][4 + n] = __builtin_amdgcn_mfma_f32_16x16x32_bf16(af[m], bfr[n], acc[m][4 + n], 0, 0, 0);
;     __builtin_amdgcn_sched_barrier(0);
.LBB0_264:
	s_waitcnt lgkmcnt(3)
	v_mfma_f32_16x16x32_bf16 v[124:127], v[216:219], v[232:235], v[124:127]
	v_add_u32_e32 v158, 0x18000, v166
	v_lshl_add_u64 v[144:145], v[138:139], 0, s[36:37]
	v_mfma_f32_16x16x32_bf16 v[108:111], v[220:223], v[232:235], v[108:111]
	v_add_u32_e32 v159, 0x1a000, v166
	v_lshl_add_u64 v[160:161], v[144:145], 0, s[60:61]
	v_mfma_f32_16x16x32_bf16 v[88:91], v[224:227], v[232:235], v[88:91]
	s_waitcnt vmcnt(4)
	s_barrier
	s_add_i32 m0, s100, 0x18000
	v_lshl_add_u64 v[142:143], v[140:141], 0, s[36:37]
	v_mfma_f32_16x16x32_bf16 v[44:47], v[228:231], v[232:235], v[44:47]
	v_lshl_add_u64 v[182:183], v[142:143], 0, s[60:61]
	global_load_lds_dwordx4 v[160:161], off
	s_waitcnt lgkmcnt(2)
	v_mfma_f32_16x16x32_bf16 v[120:123], v[216:219], v[236:239], v[120:123]
	ds_read_b128 v[232:235], v168 offset:20480
	v_mfma_f32_16x16x32_bf16 v[104:107], v[220:223], v[236:239], v[104:107]
	v_lshl_add_u64 v[160:161], v[144:145], 0, s[18:19]
	s_add_i32 m0, s100, 0x1a000
	v_mfma_f32_16x16x32_bf16 v[76:79], v[224:227], v[236:239], v[76:79]
	global_load_lds_dwordx4 v[160:161], off
	v_mfma_f32_16x16x32_bf16 v[40:43], v[228:231], v[236:239], v[40:43]
	v_add_u32_e32 v160, 0x1c000, v166
	s_waitcnt lgkmcnt(2)
	v_mfma_f32_16x16x32_bf16 v[116:119], v[216:219], v[240:243], v[116:119]
	ds_read_b128 v[236:239], v168 offset:21504
	v_mfma_f32_16x16x32_bf16 v[100:103], v[220:223], v[240:243], v[100:103]
	v_add_u32_e32 v161, 0x1e000, v166
	v_mfma_f32_16x16x32_bf16 v[68:71], v[224:227], v[240:243], v[68:71]
	s_add_i32 m0, s100, 0x1c000
	v_mfma_f32_16x16x32_bf16 v[36:39], v[228:231], v[240:243], v[36:39]
	global_load_lds_dwordx4 v[182:183], off nt
	s_waitcnt lgkmcnt(2)
	v_mfma_f32_16x16x32_bf16 v[112:115], v[216:219], v[244:247], v[112:115]
	ds_read_b128 v[240:243], v168 offset:22528
	v_mfma_f32_16x16x32_bf16 v[96:99], v[220:223], v[244:247], v[96:99]
	v_lshl_add_u64 v[182:183], v[142:143], 0, s[18:19]
	v_mfma_f32_16x16x32_bf16 v[64:67], v[224:227], v[244:247], v[64:67]
	s_add_i32 m0, s100, 0x1e000
	v_mfma_f32_16x16x32_bf16 v[32:35], v[228:231], v[244:247], v[32:35]
	global_load_lds_dwordx4 v[182:183], off nt
	s_waitcnt lgkmcnt(2)
	v_mfma_f32_16x16x32_bf16 v[92:95], v[216:219], v[232:235], v[92:95]
	ds_read_b128 v[244:247], v168 offset:23552
	v_mfma_f32_16x16x32_bf16 v[60:63], v[220:223], v[232:235], v[60:63]
	ds_read_b128 v[186:189], v167 offset:32768
	v_mfma_f32_16x16x32_bf16 v[28:31], v[224:227], v[232:235], v[28:31]
	ds_read_b128 v[190:193], v167 offset:33792
	v_mfma_f32_16x16x32_bf16 v[12:15], v[228:231], v[232:235], v[12:15]
	ds_read_b128 v[194:197], v167 offset:34816
	s_waitcnt lgkmcnt(5)
	v_mfma_f32_16x16x32_bf16 v[84:87], v[216:219], v[236:239], v[84:87]
	ds_read_b128 v[202:205], v167 offset:35840
	ds_read_b128 v[232:235], v168 offset:49152
	v_mfma_f32_16x16x32_bf16 v[56:59], v[220:223], v[236:239], v[56:59]
	v_mfma_f32_16x16x32_bf16 v[24:27], v[224:227], v[236:239], v[24:27]
	v_mfma_f32_16x16x32_bf16 v[8:11], v[228:231], v[236:239], v[8:11]
	s_waitcnt lgkmcnt(6)
	v_mfma_f32_16x16x32_bf16 v[80:83], v[216:219], v[240:243], v[80:83]
	ds_read_b128 v[236:239], v168 offset:50176
	v_mfma_f32_16x16x32_bf16 v[52:55], v[220:223], v[240:243], v[52:55]
	v_mfma_f32_16x16x32_bf16 v[20:23], v[224:227], v[240:243], v[20:23]
	v_mfma_f32_16x16x32_bf16 v[4:7], v[228:231], v[240:243], v[4:7]
	s_waitcnt lgkmcnt(6)
	v_mfma_f32_16x16x32_bf16 v[72:75], v[216:219], v[244:247], v[72:75]
	ds_read_b128 v[240:243], v168 offset:51200
	v_mfma_f32_16x16x32_bf16 v[48:51], v[220:223], v[244:247], v[48:51]
	v_mfma_f32_16x16x32_bf16 v[16:19], v[224:227], v[244:247], v[16:19]
	v_mfma_f32_16x16x32_bf16 v[0:3], v[228:231], v[244:247], v[0:3]
	ds_read_b128 v[244:247], v168 offset:52224
	s_waitcnt lgkmcnt(3)
	v_mfma_f32_16x16x32_bf16 v[124:127], v[186:189], v[232:235], v[124:127]
	v_lshl_add_u64 v[182:183], v[144:145], 0, s[62:63]
	v_mfma_f32_16x16x32_bf16 v[108:111], v[190:193], v[232:235], v[108:111]
	s_mov_b32 m0, s100
	v_mfma_f32_16x16x32_bf16 v[88:91], v[194:197], v[232:235], v[88:91]
	s_waitcnt vmcnt(4)
	s_barrier
	v_lshl_add_u64 v[198:199], v[142:143], 0, s[62:63]
	v_mfma_f32_16x16x32_bf16 v[44:47], v[202:205], v[232:235], v[44:47]
	global_load_lds_dwordx4 v[182:183], off
	s_waitcnt lgkmcnt(2)
	v_mfma_f32_16x16x32_bf16 v[120:123], v[186:189], v[236:239], v[120:123]
	ds_read_b128 v[232:235], v168 offset:53248
	v_mfma_f32_16x16x32_bf16 v[104:107], v[190:193], v[236:239], v[104:107]
	v_lshl_add_u64 v[182:183], v[144:145], 0, s[20:21]
	v_mfma_f32_16x16x32_bf16 v[76:79], v[194:197], v[236:239], v[76:79]
	s_add_i32 m0, s100, 0x2000
	v_mfma_f32_16x16x32_bf16 v[40:43], v[202:205], v[236:239], v[40:43]
	global_load_lds_dwordx4 v[182:183], off
	s_waitcnt lgkmcnt(2)
	v_mfma_f32_16x16x32_bf16 v[116:119], v[186:189], v[240:243], v[116:119]
	ds_read_b128 v[236:239], v168 offset:54272
	v_mfma_f32_16x16x32_bf16 v[100:103], v[190:193], v[240:243], v[100:103]
	s_add_i32 m0, s100, 0x4000
	v_mfma_f32_16x16x32_bf16 v[68:71], v[194:197], v[240:243], v[68:71]
	v_lshl_add_u64 v[182:183], v[142:143], 0, s[20:21]
	v_mfma_f32_16x16x32_bf16 v[36:39], v[202:205], v[240:243], v[36:39]
	global_load_lds_dwordx4 v[198:199], off nt
	s_waitcnt lgkmcnt(2)
	v_mfma_f32_16x16x32_bf16 v[112:115], v[186:189], v[244:247], v[112:115]
	ds_read_b128 v[240:243], v168 offset:55296
	v_mfma_f32_16x16x32_bf16 v[96:99], v[190:193], v[244:247], v[96:99]
	s_add_i32 m0, s100, 0x6000
	v_mfma_f32_16x16x32_bf16 v[64:67], v[194:197], v[244:247], v[64:67]
	global_load_lds_dwordx4 v[182:183], off nt
	v_mfma_f32_16x16x32_bf16 v[32:35], v[202:205], v[244:247], v[32:35]
	s_waitcnt lgkmcnt(2)
; template <int NK, bool BNT = false> ...
;     ...
;   auto kstep = [&](int T, int cur, int nxt, bool do_stage) {
;     const unsigned char* sa = smem + cur * BIG_STAGE;
;     bf16x8 af[4], bfr[4];
; #pragma unroll
;     for (int m = 0; m < 4; ++m) af[m] = *reinterpret_cast<const bf16x8*>(sa + aoff + m * 1024);
; #pragma unroll
;     for (int n = 0; n < 4; ++n) bfr[n] = *reinterpret_cast<const bf16x8*>(sa + boff + n * 1024);
;     __builtin_amdgcn_sched_barrier(0);
;     if (do_stage) stage(T + 3, nxt);
; #pragma unroll
;     for (int m = 0; m < 4; ++m)
; #pragma unroll
;       for (int n = 0; n < 4; ++n) acc[m][n] = __builtin_amdgcn_mfma_f32_16x16x32_bf16(af[m], bfr[n], acc[m][n], 0, 0, 0);
;     if (do_stage) {
; #pragma unroll
;       for (int q = 0; q < NG; ++q) {
;         __builtin_amdgcn_sched_group_barrier(0x008, 3, 0);
;         __builtin_amdgcn_sched_group_barrier(0x010, 1, 0);
;       }
;       __builtin_amdgcn_sched_group_barrier(0x008, 16 - 3 * NG, 0);
;     }
;     __builtin_amdgcn_sched_barrier(0);
; #pragma unroll
;     for (int n = 0; n < 4; ++n) bfr[n] = *reinterpret_cast<const bf16x8*>(sa + boff + (4 + n) * 1024);
; #pragma unroll
;     for (int m = 0; m < 4; ++m)
; #pragma unroll
;       for (int n = 0; n < 4; ++n)
;         acc[m][4 + n] = __builtin_amdgcn_mfma_f32_16x16x32_bf16(af[m], bfr[n], acc[m][4 + n], 0, 0, 0);
;     __builtin_amdgcn_sched_barrier(0);
	v_mfma_f32_16x16x32_bf16 v[92:95], v[186:189], v[232:235], v[92:95]
	ds_read_b128 v[244:247], v168 offset:56320
	v_mfma_f32_16x16x32_bf16 v[60:63], v[190:193], v[232:235], v[60:63]
	ds_read_b128 v[216:219], v210
	v_mfma_f32_16x16x32_bf16 v[28:31], v[194:197], v[232:235], v[28:31]
	ds_read_b128 v[220:223], v210 offset:1024
	v_mfma_f32_16x16x32_bf16 v[12:15], v[202:205], v[232:235], v[12:15]
	ds_read_b128 v[224:227], v210 offset:2048
	s_waitcnt lgkmcnt(5)
	v_mfma_f32_16x16x32_bf16 v[84:87], v[186:189], v[236:239], v[84:87]
	ds_read_b128 v[228:231], v210 offset:3072
	ds_read_b128 v[232:235], v211
	v_mfma_f32_16x16x32_bf16 v[56:59], v[190:193], v[236:239], v[56:59]
	v_mfma_f32_16x16x32_bf16 v[24:27], v[194:197], v[236:239], v[24:27]
	v_mfma_f32_16x16x32_bf16 v[8:11], v[202:205], v[236:239], v[8:11]
	s_waitcnt lgkmcnt(6)
	v_mfma_f32_16x16x32_bf16 v[80:83], v[186:189], v[240:243], v[80:83]
	ds_read_b128 v[236:239], v211 offset:1024
	v_mfma_f32_16x16x32_bf16 v[52:55], v[190:193], v[240:243], v[52:55]
	v_mfma_f32_16x16x32_bf16 v[20:23], v[194:197], v[240:243], v[20:23]
	v_mfma_f32_16x16x32_bf16 v[4:7], v[202:205], v[240:243], v[4:7]
	s_waitcnt lgkmcnt(6)
	v_mfma_f32_16x16x32_bf16 v[72:75], v[186:189], v[244:247], v[72:75]
	ds_read_b128 v[240:243], v211 offset:2048
	v_mfma_f32_16x16x32_bf16 v[48:51], v[190:193], v[244:247], v[48:51]
	v_mfma_f32_16x16x32_bf16 v[16:19], v[194:197], v[244:247], v[16:19]
	v_mfma_f32_16x16x32_bf16 v[0:3], v[202:205], v[244:247], v[0:3]
	ds_read_b128 v[244:247], v211 offset:3072
	s_waitcnt lgkmcnt(3)
	v_mfma_f32_16x16x32_bf16 v[124:127], v[216:219], v[232:235], v[124:127]
	v_lshl_add_u64 v[174:175], v[144:145], 0, s[2:3]
	v_mfma_f32_16x16x32_bf16 v[108:111], v[220:223], v[232:235], v[108:111]
	s_add_i32 m0, s100, 0x8000
	v_mfma_f32_16x16x32_bf16 v[88:91], v[224:227], v[232:235], v[88:91]
	s_waitcnt vmcnt(4)
	s_barrier
	v_lshl_add_u64 v[178:179], v[142:143], 0, s[2:3]
	v_mfma_f32_16x16x32_bf16 v[44:47], v[228:231], v[232:235], v[44:47]
	global_load_lds_dwordx4 v[174:175], off
	s_waitcnt lgkmcnt(2)
	v_mfma_f32_16x16x32_bf16 v[120:123], v[216:219], v[236:239], v[120:123]
	ds_read_b128 v[232:235], v211 offset:4096
	v_mfma_f32_16x16x32_bf16 v[104:107], v[220:223], v[236:239], v[104:107]
	v_lshl_add_u64 v[174:175], v[144:145], 0, s[22:23]
	v_mfma_f32_16x16x32_bf16 v[76:79], v[224:227], v[236:239], v[76:79]
	s_add_i32 m0, s100, 0xa000
	v_mfma_f32_16x16x32_bf16 v[40:43], v[228:231], v[236:239], v[40:43]
	global_load_lds_dwordx4 v[174:175], off
	s_waitcnt lgkmcnt(2)
	v_mfma_f32_16x16x32_bf16 v[116:119], v[216:219], v[240:243], v[116:119]
	ds_read_b128 v[236:239], v211 offset:5120
	v_mfma_f32_16x16x32_bf16 v[100:103], v[220:223], v[240:243], v[100:103]
	s_add_i32 m0, s100, 0xc000
	v_mfma_f32_16x16x32_bf16 v[68:71], v[224:227], v[240:243], v[68:71]
	v_lshl_add_u64 v[174:175], v[142:143], 0, s[22:23]
	v_mfma_f32_16x16x32_bf16 v[36:39], v[228:231], v[240:243], v[36:39]
	global_load_lds_dwordx4 v[178:179], off nt
	s_waitcnt lgkmcnt(2)
	v_mfma_f32_16x16x32_bf16 v[112:115], v[216:219], v[244:247], v[112:115]
	ds_read_b128 v[240:243], v211 offset:6144
	v_mfma_f32_16x16x32_bf16 v[96:99], v[220:223], v[244:247], v[96:99]
	s_add_i32 m0, s100, 0xe000
	v_mfma_f32_16x16x32_bf16 v[64:67], v[224:227], v[244:247], v[64:67]
	global_load_lds_dwordx4 v[174:175], off nt
	v_mfma_f32_16x16x32_bf16 v[32:35], v[228:231], v[244:247], v[32:35]
	s_waitcnt lgkmcnt(2)
	v_mfma_f32_16x16x32_bf16 v[92:95], v[216:219], v[232:235], v[92:95]
	ds_read_b128 v[244:247], v211 offset:7168
	v_mfma_f32_16x16x32_bf16 v[60:63], v[220:223], v[232:235], v[60:63]
	ds_read_b128 v[186:189], v210 offset:32768
	v_mfma_f32_16x16x32_bf16 v[28:31], v[224:227], v[232:235], v[28:31]
	ds_read_b128 v[190:193], v210 offset:33792
	v_mfma_f32_16x16x32_bf16 v[12:15], v[228:231], v[232:235], v[12:15]
	ds_read_b128 v[194:197], v210 offset:34816
	s_waitcnt lgkmcnt(5)
	v_mfma_f32_16x16x32_bf16 v[84:87], v[216:219], v[236:239], v[84:87]
	ds_read_b128 v[202:205], v210 offset:35840
	ds_read_b128 v[232:235], v211 offset:32768
	v_mfma_f32_16x16x32_bf16 v[56:59], v[220:223], v[236:239], v[56:59]
	v_mfma_f32_16x16x32_bf16 v[24:27], v[224:227], v[236:239], v[24:27]
	v_mfma_f32_16x16x32_bf16 v[8:11], v[228:231], v[236:239], v[8:11]
	s_waitcnt lgkmcnt(6)
	v_mfma_f32_16x16x32_bf16 v[80:83], v[216:219], v[240:243], v[80:83]
	ds_read_b128 v[236:239], v211 offset:33792
	v_mfma_f32_16x16x32_bf16 v[52:55], v[220:223], v[240:243], v[52:55]
	v_mfma_f32_16x16x32_bf16 v[20:23], v[224:227], v[240:243], v[20:23]
	v_mfma_f32_16x16x32_bf16 v[4:7], v[228:231], v[240:243], v[4:7]
	s_waitcnt lgkmcnt(6)
	v_mfma_f32_16x16x32_bf16 v[72:75], v[216:219], v[244:247], v[72:75]
	ds_read_b128 v[240:243], v211 offset:34816
	v_mfma_f32_16x16x32_bf16 v[48:51], v[220:223], v[244:247], v[48:51]
	v_mfma_f32_16x16x32_bf16 v[16:19], v[224:227], v[244:247], v[16:19]
	v_mfma_f32_16x16x32_bf16 v[0:3], v[228:231], v[244:247], v[0:3]
	ds_read_b128 v[244:247], v211 offset:35840
	s_waitcnt lgkmcnt(3)
	v_mfma_f32_16x16x32_bf16 v[124:127], v[186:189], v[232:235], v[124:127]
	v_lshl_add_u64 v[248:249], v[144:145], 0, s[54:55]
	v_mfma_f32_16x16x32_bf16 v[108:111], v[190:193], v[232:235], v[108:111]
	s_add_i32 m0, s100, 0x10000
	v_mfma_f32_16x16x32_bf16 v[88:91], v[194:197], v[232:235], v[88:91]
	s_waitcnt vmcnt(4)
	s_barrier
; #define BIG_SYNC(N)                                              \
;   asm volatile("s_waitcnt vmcnt(%0)" ::"n"(N) : "memory");       \
;   __builtin_amdgcn_s_barrier();                                  \
;   asm volatile("" ::: "memory");                                 \
;   __builtin_amdgcn_sched_barrier(0);
; template <int NK, bool BNT = false> ...
;     ...
;   auto kstep = [&](int T, int cur, int nxt, bool do_stage) {
;     const unsigned char* sa = smem + cur * BIG_STAGE;
;     bf16x8 af[4], bfr[4];
; #pragma unroll
;     for (int m = 0; m < 4; ++m) af[m] = *reinterpret_cast<const bf16x8*>(sa + aoff + m * 1024);
; #pragma unroll
;     for (int n = 0; n < 4; ++n) bfr[n] = *reinterpret_cast<const bf16x8*>(sa + boff + n * 1024);
;     __builtin_amdgcn_sched_barrier(0);
;     if (do_stage) stage(T + 3, nxt);
; #pragma unroll
;     for (int m = 0; m < 4; ++m)
; #pragma unroll
;       for (int n = 0; n < 4; ++n) acc[m][n] = __builtin_amdgcn_mfma_f32_16x16x32_bf16(af[m], bfr[n], acc[m][n], 0, 0, 0);
;     if (do_stage) {
; #pragma unroll
;       for (int q = 0; q < NG; ++q) {
;         __builtin_amdgcn_sched_group_barrier(0x008, 3, 0);
;         __builtin_amdgcn_sched_group_barrier(0x010, 1, 0);
;       }
;       __builtin_amdgcn_sched_group_barrier(0x008, 16 - 3 * NG, 0);
;     }
;     __builtin_amdgcn_sched_barrier(0);
; #pragma unroll
;     for (int n = 0; n < 4; ++n) bfr[n] = *reinterpret_cast<const bf16x8*>(sa + boff + (4 + n) * 1024);
; #pragma unroll
;     for (int m = 0; m < 4; ++m)
; #pragma unroll
;       for (int n = 0; n < 4; ++n)
;         acc[m][4 + n] = __builtin_amdgcn_mfma_f32_16x16x32_bf16(af[m], bfr[n], acc[m][4 + n], 0, 0, 0);
;     __builtin_amdgcn_sched_barrier(0);
;   };
;     ...
;   stage(0, 0);
;   stage(1, 1);
;   stage(2, 2);
;   for (int it = 0; it < NK / 4 - 1; ++it) {
;     const int t = it * 4;
;     BIG_SYNC(2 * NG); kstep(t, 0, 3, true);
;     BIG_SYNC(2 * NG); kstep(t + 1, 1, 0, true);
;     BIG_SYNC(2 * NG); kstep(t + 2, 2, 1, true);
;     BIG_SYNC(2 * NG); kstep(t + 3, 3, 2, true);
;   }
;   BIG_SYNC(2 * NG); kstep(NK - 4, 0, 3, true);
;   BIG_SYNC(2 * NG); kstep(NK - 3, 1, 0, false);
;   BIG_SYNC(NG);     kstep(NK - 2, 2, 0, false);
;   BIG_SYNC(0);      kstep(NK - 1, 3, 0, false);
	v_lshl_add_u64 v[144:145], v[144:145], 0, s[24:25]
	v_mfma_f32_16x16x32_bf16 v[44:47], v[202:205], v[232:235], v[44:47]
	v_lshl_add_u64 v[250:251], v[142:143], 0, s[54:55]
	s_waitcnt lgkmcnt(2)
	v_mfma_f32_16x16x32_bf16 v[120:123], v[186:189], v[236:239], v[120:123]
	ds_read_b128 v[232:235], v211 offset:36864
	v_mfma_f32_16x16x32_bf16 v[104:107], v[190:193], v[236:239], v[104:107]
	v_lshl_add_u64 v[142:143], v[142:143], 0, s[24:25]
	v_mfma_f32_16x16x32_bf16 v[76:79], v[194:197], v[236:239], v[76:79]
	global_load_lds_dwordx4 v[248:249], off
	v_mfma_f32_16x16x32_bf16 v[40:43], v[202:205], v[236:239], v[40:43]
	s_add_i32 m0, s100, 0x12000
	s_waitcnt lgkmcnt(2)
	v_mfma_f32_16x16x32_bf16 v[116:119], v[186:189], v[240:243], v[116:119]
	ds_read_b128 v[236:239], v211 offset:37888
	v_mfma_f32_16x16x32_bf16 v[100:103], v[190:193], v[240:243], v[100:103]
	global_load_lds_dwordx4 v[144:145], off
	v_mfma_f32_16x16x32_bf16 v[68:71], v[194:197], v[240:243], v[68:71]
	s_add_i32 m0, s100, 0x14000
	v_mfma_f32_16x16x32_bf16 v[36:39], v[202:205], v[240:243], v[36:39]
	global_load_lds_dwordx4 v[250:251], off nt
	s_waitcnt lgkmcnt(2)
	v_mfma_f32_16x16x32_bf16 v[112:115], v[186:189], v[244:247], v[112:115]
	ds_read_b128 v[240:243], v211 offset:38912
	v_mfma_f32_16x16x32_bf16 v[96:99], v[190:193], v[244:247], v[96:99]
	s_add_i32 m0, s100, 0x16000
	v_mfma_f32_16x16x32_bf16 v[64:67], v[194:197], v[244:247], v[64:67]
	global_load_lds_dwordx4 v[142:143], off nt
	v_mfma_f32_16x16x32_bf16 v[32:35], v[202:205], v[244:247], v[32:35]
	s_waitcnt lgkmcnt(2)
	v_mfma_f32_16x16x32_bf16 v[92:95], v[186:189], v[232:235], v[92:95]
	ds_read_b128 v[244:247], v211 offset:39936
	v_mfma_f32_16x16x32_bf16 v[60:63], v[190:193], v[232:235], v[60:63]
	ds_read_b128 v[216:219], v167
	v_mfma_f32_16x16x32_bf16 v[28:31], v[194:197], v[232:235], v[28:31]
	ds_read_b128 v[220:223], v167 offset:1024
	v_mfma_f32_16x16x32_bf16 v[12:15], v[202:205], v[232:235], v[12:15]
	ds_read_b128 v[224:227], v167 offset:2048
	s_waitcnt lgkmcnt(5)
	v_mfma_f32_16x16x32_bf16 v[84:87], v[186:189], v[236:239], v[84:87]
	ds_read_b128 v[228:231], v167 offset:3072
	ds_read_b128 v[232:235], v168 offset:16384
	v_mfma_f32_16x16x32_bf16 v[56:59], v[190:193], v[236:239], v[56:59]
	v_mfma_f32_16x16x32_bf16 v[24:27], v[194:197], v[236:239], v[24:27]
	v_mfma_f32_16x16x32_bf16 v[8:11], v[202:205], v[236:239], v[8:11]
	s_waitcnt lgkmcnt(6)
	v_mfma_f32_16x16x32_bf16 v[80:83], v[186:189], v[240:243], v[80:83]
	ds_read_b128 v[236:239], v168 offset:17408
	v_mfma_f32_16x16x32_bf16 v[52:55], v[190:193], v[240:243], v[52:55]
	v_mfma_f32_16x16x32_bf16 v[20:23], v[194:197], v[240:243], v[20:23]
	v_mfma_f32_16x16x32_bf16 v[4:7], v[202:205], v[240:243], v[4:7]
	s_waitcnt lgkmcnt(6)
	v_mfma_f32_16x16x32_bf16 v[72:75], v[186:189], v[244:247], v[72:75]
	ds_read_b128 v[240:243], v168 offset:18432
	v_mfma_f32_16x16x32_bf16 v[48:51], v[190:193], v[244:247], v[48:51]
	v_mfma_f32_16x16x32_bf16 v[16:19], v[194:197], v[244:247], v[16:19]
	v_mfma_f32_16x16x32_bf16 v[0:3], v[202:205], v[244:247], v[0:3]
	ds_read_b128 v[244:247], v168 offset:19456
	s_add_u32 s36, s36, 0x8000
	s_addc_u32 s37, s37, 0
	s_cmp_lg_u32 s36, 0xf8000
	s_cbranch_scc1 .LBB0_264
	v_add_u32_e32 v162, 0x10000, v167
	v_or_b32_e32 v163, 0x10000, v169
	v_add_u32_e32 v164, 0x10400, v169
	v_add_u32_e32 v165, 0x10800, v169
	v_add_u32_e32 v172, 0x10c00, v169
	v_add_u32_e32 v173, 0x11000, v169
	v_add_u32_e32 v174, 0x11400, v169
	v_add_u32_e32 v175, 0x11800, v169
	v_add_u32_e32 v178, 0x11c00, v169
	v_add_u32_e32 v176, 0x18000, v167
	v_or_b32_e32 v179, 0x18000, v169
	v_add_u32_e32 v180, 0x18400, v169
	v_add_u32_e32 v181, 0x18800, v169
	v_add_u32_e32 v182, 0x18c00, v169
	v_add_u32_e32 v142, 0x19000, v169
	v_add_u32_e32 v143, 0x19400, v169
	v_add_u32_e32 v144, 0x19800, v169
	v_add_u32_e32 v145, 0x19c00, v169
	s_waitcnt lgkmcnt(3)
	v_mfma_f32_16x16x32_bf16 v[124:127], v[216:219], v[232:235], v[124:127]
	s_sext_i32_i8 s13, s14
	s_mov_b64 s[18:19], 0xfe000
	v_mfma_f32_16x16x32_bf16 v[108:111], v[220:223], v[232:235], v[108:111]
	v_readfirstlane_b32 s14, v158
	v_lshl_add_u64 v[150:151], v[130:131], 0, s[18:19]
	v_mfma_f32_16x16x32_bf16 v[88:91], v[224:227], v[232:235], v[88:91]
	s_waitcnt vmcnt(4)
	s_barrier
	v_lshl_add_u64 v[198:199], v[128:129], 0, s[18:19]
	s_mov_b32 m0, s14
	v_mfma_f32_16x16x32_bf16 v[44:47], v[228:231], v[232:235], v[44:47]
	s_mov_b64 s[18:19], 0x1fe000
	v_readfirstlane_b32 s14, v159
	s_waitcnt lgkmcnt(2)
	v_mfma_f32_16x16x32_bf16 v[120:123], v[216:219], v[236:239], v[120:123]
	ds_read_b128 v[232:235], v168 offset:20480
	v_mfma_f32_16x16x32_bf16 v[104:107], v[220:223], v[236:239], v[104:107]
	v_lshl_add_u64 v[130:131], v[130:131], 0, s[18:19]
	v_lshl_add_u64 v[128:129], v[128:129], 0, s[18:19]
	v_mfma_f32_16x16x32_bf16 v[76:79], v[224:227], v[236:239], v[76:79]
	global_load_lds_dwordx4 v[150:151], off
	s_mov_b32 m0, s14
	v_mfma_f32_16x16x32_bf16 v[40:43], v[228:231], v[236:239], v[40:43]
	v_readfirstlane_b32 s14, v160
	s_waitcnt lgkmcnt(2)
	v_mfma_f32_16x16x32_bf16 v[116:119], v[216:219], v[240:243], v[116:119]
	ds_read_b128 v[236:239], v168 offset:21504
	v_mfma_f32_16x16x32_bf16 v[100:103], v[220:223], v[240:243], v[100:103]
	global_load_lds_dwordx4 v[130:131], off
	v_mfma_f32_16x16x32_bf16 v[68:71], v[224:227], v[240:243], v[68:71]
	s_mov_b32 m0, s14
	v_mfma_f32_16x16x32_bf16 v[36:39], v[228:231], v[240:243], v[36:39]
	v_readfirstlane_b32 s14, v161
	s_waitcnt lgkmcnt(2)
; #define BIG_SYNC(N)                                              \
;   asm volatile("s_waitcnt vmcnt(%0)" ::"n"(N) : "memory");       \
;   __builtin_amdgcn_s_barrier();                                  \
;   asm volatile("" ::: "memory");                                 \
;   __builtin_amdgcn_sched_barrier(0);
; template <int NK, bool BNT = false> ...
;     ...
;   auto kstep = [&](int T, int cur, int nxt, bool do_stage) {
;     const unsigned char* sa = smem + cur * BIG_STAGE;
;     bf16x8 af[4], bfr[4];
; #pragma unroll
;     for (int m = 0; m < 4; ++m) af[m] = *reinterpret_cast<const bf16x8*>(sa + aoff + m * 1024);
; #pragma unroll
;     for (int n = 0; n < 4; ++n) bfr[n] = *reinterpret_cast<const bf16x8*>(sa + boff + n * 1024);
;     __builtin_amdgcn_sched_barrier(0);
;     if (do_stage) stage(T + 3, nxt);
; #pragma unroll
;     for (int m = 0; m < 4; ++m)
; #pragma unroll
;       for (int n = 0; n < 4; ++n) acc[m][n] = __builtin_amdgcn_mfma_f32_16x16x32_bf16(af[m], bfr[n], acc[m][n], 0, 0, 0);
;     if (do_stage) {
; #pragma unroll
;       for (int q = 0; q < NG; ++q) {
;         __builtin_amdgcn_sched_group_barrier(0x008, 3, 0);
;         __builtin_amdgcn_sched_group_barrier(0x010, 1, 0);
;       }
;       __builtin_amdgcn_sched_group_barrier(0x008, 16 - 3 * NG, 0);
;     }
;     __builtin_amdgcn_sched_barrier(0);
; #pragma unroll
;     for (int n = 0; n < 4; ++n) bfr[n] = *reinterpret_cast<const bf16x8*>(sa + boff + (4 + n) * 1024);
; #pragma unroll
;     for (int m = 0; m < 4; ++m)
; #pragma unroll
;       for (int n = 0; n < 4; ++n)
;         acc[m][4 + n] = __builtin_amdgcn_mfma_f32_16x16x32_bf16(af[m], bfr[n], acc[m][4 + n], 0, 0, 0);
;     __builtin_amdgcn_sched_barrier(0);
;   };
;     ...
;   stage(0, 0);
;   stage(1, 1);
;   stage(2, 2);
;   for (int it = 0; it < NK / 4 - 1; ++it) {
;     const int t = it * 4;
;     BIG_SYNC(2 * NG); kstep(t, 0, 3, true);
;     BIG_SYNC(2 * NG); kstep(t + 1, 1, 0, true);
;     BIG_SYNC(2 * NG); kstep(t + 2, 2, 1, true);
;     BIG_SYNC(2 * NG); kstep(t + 3, 3, 2, true);
;   }
;   BIG_SYNC(2 * NG); kstep(NK - 4, 0, 3, true);
;   BIG_SYNC(2 * NG); kstep(NK - 3, 1, 0, false);
;   BIG_SYNC(NG);     kstep(NK - 2, 2, 0, false);
;   BIG_SYNC(0);      kstep(NK - 1, 3, 0, false);
	v_mfma_f32_16x16x32_bf16 v[112:115], v[216:219], v[244:247], v[112:115]
	ds_read_b128 v[240:243], v168 offset:22528
	v_mfma_f32_16x16x32_bf16 v[96:99], v[220:223], v[244:247], v[96:99]
	global_load_lds_dwordx4 v[198:199], off nt
	v_mfma_f32_16x16x32_bf16 v[64:67], v[224:227], v[244:247], v[64:67]
	s_mov_b32 m0, s14
	v_mfma_f32_16x16x32_bf16 v[32:35], v[228:231], v[244:247], v[32:35]
	global_load_lds_dwordx4 v[128:129], off nt
	s_waitcnt lgkmcnt(2)
	v_mfma_f32_16x16x32_bf16 v[92:95], v[216:219], v[232:235], v[92:95]
	ds_read_b128 v[244:247], v168 offset:23552
	v_mfma_f32_16x16x32_bf16 v[60:63], v[220:223], v[232:235], v[60:63]
	ds_read_b128 v[186:189], v167 offset:32768
	v_mfma_f32_16x16x32_bf16 v[28:31], v[224:227], v[232:235], v[28:31]
	ds_read_b128 v[190:193], v167 offset:33792
	v_mfma_f32_16x16x32_bf16 v[12:15], v[228:231], v[232:235], v[12:15]
	ds_read_b128 v[194:197], v167 offset:34816
	s_waitcnt lgkmcnt(5)
	v_mfma_f32_16x16x32_bf16 v[84:87], v[216:219], v[236:239], v[84:87]
	ds_read_b128 v[202:205], v167 offset:35840
	ds_read_b128 v[232:235], v168 offset:49152
	v_mfma_f32_16x16x32_bf16 v[56:59], v[220:223], v[236:239], v[56:59]
	v_mfma_f32_16x16x32_bf16 v[24:27], v[224:227], v[236:239], v[24:27]
	v_mfma_f32_16x16x32_bf16 v[8:11], v[228:231], v[236:239], v[8:11]
	s_waitcnt lgkmcnt(6)
	v_mfma_f32_16x16x32_bf16 v[80:83], v[216:219], v[240:243], v[80:83]
	ds_read_b128 v[236:239], v168 offset:50176
	v_mfma_f32_16x16x32_bf16 v[52:55], v[220:223], v[240:243], v[52:55]
	v_mfma_f32_16x16x32_bf16 v[20:23], v[224:227], v[240:243], v[20:23]
	v_mfma_f32_16x16x32_bf16 v[4:7], v[228:231], v[240:243], v[4:7]
	s_waitcnt lgkmcnt(6)
	v_mfma_f32_16x16x32_bf16 v[72:75], v[216:219], v[244:247], v[72:75]
	ds_read_b128 v[240:243], v168 offset:51200
	v_mfma_f32_16x16x32_bf16 v[48:51], v[220:223], v[244:247], v[48:51]
	v_mfma_f32_16x16x32_bf16 v[16:19], v[224:227], v[244:247], v[16:19]
	v_mfma_f32_16x16x32_bf16 v[0:3], v[228:231], v[244:247], v[0:3]
	ds_read_b128 v[244:247], v168 offset:52224
	s_waitcnt lgkmcnt(3)
	v_mfma_f32_16x16x32_bf16 v[124:127], v[186:189], v[232:235], v[124:127]
	v_mfma_f32_16x16x32_bf16 v[108:111], v[190:193], v[232:235], v[108:111]
	v_mfma_f32_16x16x32_bf16 v[88:91], v[194:197], v[232:235], v[88:91]
	v_mfma_f32_16x16x32_bf16 v[44:47], v[202:205], v[232:235], v[44:47]
	s_waitcnt vmcnt(4)
	s_barrier
	s_waitcnt lgkmcnt(2)
	v_mfma_f32_16x16x32_bf16 v[120:123], v[186:189], v[236:239], v[120:123]
	ds_read_b128 v[232:235], v168 offset:53248
	v_mfma_f32_16x16x32_bf16 v[104:107], v[190:193], v[236:239], v[104:107]
	v_mfma_f32_16x16x32_bf16 v[76:79], v[194:197], v[236:239], v[76:79]
	v_mfma_f32_16x16x32_bf16 v[40:43], v[202:205], v[236:239], v[40:43]
	s_waitcnt lgkmcnt(2)
	v_mfma_f32_16x16x32_bf16 v[116:119], v[186:189], v[240:243], v[116:119]
	ds_read_b128 v[236:239], v168 offset:54272
	v_mfma_f32_16x16x32_bf16 v[100:103], v[190:193], v[240:243], v[100:103]
	v_mfma_f32_16x16x32_bf16 v[68:71], v[194:197], v[240:243], v[68:71]
	v_mfma_f32_16x16x32_bf16 v[36:39], v[202:205], v[240:243], v[36:39]
	s_waitcnt lgkmcnt(2)
	v_mfma_f32_16x16x32_bf16 v[112:115], v[186:189], v[244:247], v[112:115]
	ds_read_b128 v[240:243], v168 offset:55296
	v_mfma_f32_16x16x32_bf16 v[96:99], v[190:193], v[244:247], v[96:99]
	v_mfma_f32_16x16x32_bf16 v[64:67], v[194:197], v[244:247], v[64:67]
	v_mfma_f32_16x16x32_bf16 v[32:35], v[202:205], v[244:247], v[32:35]
	s_waitcnt lgkmcnt(2)
	v_mfma_f32_16x16x32_bf16 v[92:95], v[186:189], v[232:235], v[92:95]
	ds_read_b128 v[244:247], v168 offset:56320
	v_mfma_f32_16x16x32_bf16 v[60:63], v[190:193], v[232:235], v[60:63]
	v_mfma_f32_16x16x32_bf16 v[28:31], v[194:197], v[232:235], v[28:31]
	v_mfma_f32_16x16x32_bf16 v[12:15], v[202:205], v[232:235], v[12:15]
	s_waitcnt lgkmcnt(2)
	v_mfma_f32_16x16x32_bf16 v[84:87], v[186:189], v[236:239], v[84:87]
	v_mfma_f32_16x16x32_bf16 v[56:59], v[190:193], v[236:239], v[56:59]
	v_mfma_f32_16x16x32_bf16 v[24:27], v[194:197], v[236:239], v[24:27]
	v_mfma_f32_16x16x32_bf16 v[8:11], v[202:205], v[236:239], v[8:11]
	s_waitcnt lgkmcnt(1)
	v_mfma_f32_16x16x32_bf16 v[80:83], v[186:189], v[240:243], v[80:83]
	v_mfma_f32_16x16x32_bf16 v[52:55], v[190:193], v[240:243], v[52:55]
	v_mfma_f32_16x16x32_bf16 v[20:23], v[194:197], v[240:243], v[20:23]
	v_mfma_f32_16x16x32_bf16 v[4:7], v[202:205], v[240:243], v[4:7]
	s_waitcnt lgkmcnt(0)
	v_mfma_f32_16x16x32_bf16 v[72:75], v[186:189], v[244:247], v[72:75]
	v_mfma_f32_16x16x32_bf16 v[48:51], v[190:193], v[244:247], v[48:51]
	v_mfma_f32_16x16x32_bf16 v[16:19], v[194:197], v[244:247], v[16:19]
	v_mfma_f32_16x16x32_bf16 v[0:3], v[202:205], v[244:247], v[0:3]
	v_mov_b32_e32 v186, 0xf149f2ca
	v_mov_b32_e32 v187, 0x3c0881c4
	v_mov_b32_e32 v188, 0xbab64f3b
	v_mov_b32_e32 v189, 0x24800
	v_mov_b32_e32 v190, 1
	v_mov_b32_e32 v191, 0x24804
	v_mov_b32_e32 v192, 0xfcf
	v_mov_b32_e32 v193, 0x7cf
	v_mov_b32_e32 v194, 0xfdf
	v_mov_b32_e32 v195, 0x7df
	v_mov_b32_e32 v196, 0xfef
	v_mov_b32_e32 v197, 0x7ef
	v_mov_b32_e32 v198, 0xfff
	v_mov_b32_e32 v199, 0x7ff
	v_mov_b32_e32 v200, 0x20000
	v_mov_b32_e32 v201, 0xf8f
	v_mov_b32_e32 v202, 0x78f
	v_mov_b32_e32 v203, 0xf9f
	v_mov_b32_e32 v204, 0x79f
	v_mov_b32_e32 v205, 0xfaf
	v_mov_b32_e32 v210, 0x7f800000
	v_not_b32_e32 v211, 63
	v_not_b32_e32 v212, 31
	v_mov_b32_e32 v213, 0x7fc00000
	s_waitcnt vmcnt(4)
	s_barrier
; #define BIG_SYNC(N)                                              \
;   asm volatile("s_waitcnt vmcnt(%0)" ::"n"(N) : "memory");       \
;   __builtin_amdgcn_s_barrier();                                  \
;   asm volatile("" ::: "memory");                                 \
;   __builtin_amdgcn_sched_barrier(0);
; template <int NK, bool BNT = false> ...
;     ...
;   BIG_SYNC(2 * NG); kstep(NK - 4, 0, 3, true);
;   BIG_SYNC(2 * NG); kstep(NK - 3, 1, 0, false);
;   BIG_SYNC(NG);     kstep(NK - 2, 2, 0, false);
;   BIG_SYNC(0);      kstep(NK - 1, 3, 0, false);
	ds_read_b128 v[128:131], v162
	ds_read_b128 v[138:141], v162 offset:1024
	ds_read_b128 v[146:149], v162 offset:2048
	ds_read_b128 v[154:157], v162 offset:3072
	ds_read_b128 v[158:161], v163
	ds_read_b128 v[216:219], v164
	ds_read_b128 v[162:165], v165
	ds_read_b128 v[220:223], v172
	s_waitcnt lgkmcnt(0)
	v_mfma_f32_16x16x32_bf16 v[124:127], v[128:131], v[158:161], v[124:127]
	v_mfma_f32_16x16x32_bf16 v[116:119], v[128:131], v[162:165], v[116:119]
	v_mfma_f32_16x16x32_bf16 v[112:115], v[128:131], v[220:223], v[112:115]
	v_mfma_f32_16x16x32_bf16 v[104:107], v[138:141], v[216:219], v[104:107]
	v_mfma_f32_16x16x32_bf16 v[100:103], v[138:141], v[162:165], v[100:103]
	v_mfma_f32_16x16x32_bf16 v[96:99], v[138:141], v[220:223], v[96:99]
	v_mfma_f32_16x16x32_bf16 v[68:71], v[146:149], v[162:165], v[68:71]
	v_mfma_f32_16x16x32_bf16 v[64:67], v[146:149], v[220:223], v[64:67]
	v_mfma_f32_16x16x32_bf16 v[44:47], v[154:157], v[158:161], v[44:47]
	v_mfma_f32_16x16x32_bf16 v[40:43], v[154:157], v[216:219], v[40:43]
	v_mfma_f32_16x16x32_bf16 v[36:39], v[154:157], v[162:165], v[36:39]
	v_mfma_f32_16x16x32_bf16 v[32:35], v[154:157], v[220:223], v[32:35]
	v_mfma_f32_16x16x32_bf16 v[120:123], v[128:131], v[216:219], v[120:123]
	v_mfma_f32_16x16x32_bf16 v[224:227], v[138:141], v[158:161], v[108:111]
	v_mfma_f32_16x16x32_bf16 v[228:231], v[146:149], v[158:161], v[88:91]
	v_mfma_f32_16x16x32_bf16 v[232:235], v[146:149], v[216:219], v[76:79]
	s_nop 2
	ds_read_b128 v[76:79], v173
	ds_read_b128 v[88:91], v174
	s_waitcnt lgkmcnt(0)
	v_mfma_f32_16x16x32_bf16 v[158:161], v[128:131], v[76:79], v[92:95]
	s_nop 2
	ds_read_b128 v[92:95], v178
	v_mfma_f32_16x16x32_bf16 v[162:165], v[128:131], v[88:91], v[84:87]
	s_nop 2
	ds_read_b128 v[84:87], v175
	s_waitcnt lgkmcnt(0)
	v_mfma_f32_16x16x32_bf16 v[172:175], v[128:131], v[84:87], v[80:83]
	v_mfma_f32_16x16x32_bf16 v[128:131], v[128:131], v[92:95], v[72:75]
	v_mfma_f32_16x16x32_bf16 v[216:219], v[138:141], v[76:79], v[60:63]
	v_mfma_f32_16x16x32_bf16 v[220:223], v[138:141], v[88:91], v[56:59]
	v_mfma_f32_16x16x32_bf16 v[52:55], v[138:141], v[84:87], v[52:55]
	v_mfma_f32_16x16x32_bf16 v[48:51], v[138:141], v[92:95], v[48:51]
	v_mfma_f32_16x16x32_bf16 v[138:141], v[146:149], v[76:79], v[28:31]
	v_mfma_f32_16x16x32_bf16 v[236:239], v[146:149], v[88:91], v[24:27]
	v_mfma_f32_16x16x32_bf16 v[20:23], v[146:149], v[84:87], v[20:23]
	v_mfma_f32_16x16x32_bf16 v[16:19], v[146:149], v[92:95], v[16:19]
	v_mfma_f32_16x16x32_bf16 v[146:149], v[154:157], v[76:79], v[12:15]
	v_mfma_f32_16x16x32_bf16 v[0:3], v[154:157], v[92:95], v[0:3]
	v_mfma_f32_16x16x32_bf16 v[240:243], v[154:157], v[88:91], v[8:11]
	v_mfma_f32_16x16x32_bf16 v[244:247], v[154:157], v[84:87], v[4:7]
	s_waitcnt vmcnt(0)
	s_barrier
	s_nop 1
	ds_read_b128 v[4:7], v176
	ds_read_b128 v[8:11], v176 offset:1024
	ds_read_b128 v[154:157], v176 offset:2048
	ds_read_b128 v[12:15], v179
	ds_read_b128 v[24:27], v180
	ds_read_b128 v[28:31], v181
	ds_read_b128 v[56:59], v182
	ds_read_b128 v[248:251], v176 offset:3072
	s_waitcnt lgkmcnt(0)
	v_mfma_f32_16x16x32_bf16 v[108:111], v[4:7], v[24:27], v[120:123]
	v_mfma_f32_16x16x32_bf16 v[92:95], v[4:7], v[28:31], v[116:119]
	v_mfma_f32_16x16x32_bf16 v[76:79], v[4:7], v[56:59], v[112:115]
	v_mfma_f32_16x16x32_bf16 v[104:107], v[8:11], v[24:27], v[104:107]
	v_mfma_f32_16x16x32_bf16 v[88:91], v[8:11], v[28:31], v[100:103]
	v_mfma_f32_16x16x32_bf16 v[72:75], v[8:11], v[56:59], v[96:99]
	v_mfma_f32_16x16x32_bf16 v[100:103], v[154:157], v[24:27], v[232:235]
	v_mfma_f32_16x16x32_bf16 v[84:87], v[154:157], v[28:31], v[68:71]
	v_mfma_f32_16x16x32_bf16 v[68:71], v[154:157], v[56:59], v[64:67]
	v_mfma_f32_16x16x32_bf16 v[116:119], v[248:251], v[12:15], v[44:47]
	v_mfma_f32_16x16x32_bf16 v[96:99], v[248:251], v[24:27], v[40:43]
	v_mfma_f32_16x16x32_bf16 v[80:83], v[248:251], v[28:31], v[36:39]
	v_mfma_f32_16x16x32_bf16 v[64:67], v[248:251], v[56:59], v[32:35]
	v_mfma_f32_16x16x32_bf16 v[178:181], v[4:7], v[12:15], v[124:127]
	v_mfma_f32_16x16x32_bf16 v[224:227], v[8:11], v[12:15], v[224:227]
	v_mfma_f32_16x16x32_bf16 v[120:123], v[154:157], v[12:15], v[228:231]
	ds_read_b128 v[32:35], v142
	ds_read_b128 v[112:115], v143
	ds_read_b128 v[124:127], v144
	ds_read_b128 v[142:145], v145
	s_waitcnt lgkmcnt(0)
; __device__ __forceinline__ float bf2f(bf16_t b) { return __uint_as_float(((unsigned)b) << 16); }
; __device__ __forceinline__ int widen_off(int fq) { return ((fq & 1) << 4) + ((fq >> 1) << 3); }
; template <int MODE, int NSUB>
; __device__ __forceinline__ void epilogue(const Params& p, int layer, f32x4 (&acc)[4][NSUB], int tm, int tn, int g,
;                                          const float* s_rstd, const int tid_in) {
;     ...
;   } else if constexpr (MODE == EPI_RES) {
;     const int fb = tm * 128 + wr * 64 + fq * 4;
;     const int tb = tn * (NSUB * 32) + wc * (NSUB * 16) + fr;
;     const int fw = tm * 128 + wr * 64 + widen_off(fq);
;     u32x4 curw[2], nxtw[2];
; #pragma unroll
;     for (int mp = 0; mp < 2; ++mp) curw[mp] = *reinterpret_cast<const u32x4*>(p.xb + blk(tb, fw + mp * 32, 32));
; #pragma unroll
;     for (int n = 0; n < NSUB; ++n) {
;       if (n + 1 < NSUB) {
; #pragma unroll
;         for (int mp = 0; mp < 2; ++mp) nxtw[mp] = *reinterpret_cast<const u32x4*>(p.xb + blk(tb + (n + 1) * 16, fw + mp * 32, 32));
;       }
;       bf16x4 cur[4];
;       unwiden_pair(curw[0], cur[0], cur[1]);
;       unwiden_pair(curw[1], cur[2], cur[3]);
;       const int t = tb + n * 16;
;       float ss = 0.f;
; #pragma unroll
;       for (int mp = 0; mp < 2; ++mp) {
;         bf16x4 pk[2];
; #pragma unroll
;         for (int h2 = 0; h2 < 2; ++h2) {
;           const int m = mp * 2 + h2;
;           const float x0 = bf2f((bf16_t)cur[m][0]) + acc[m][n][0], x1 = bf2f((bf16_t)cur[m][1]) + acc[m][n][1];
;           const float x2 = bf2f((bf16_t)cur[m][2]) + acc[m][n][2], x3 = bf2f((bf16_t)cur[m][3]) + acc[m][n][3];
;           ss += x0 * x0 + x1 * x1 + x2 * x2 + x3 * x3;
;           pk[h2] = pack4(x0, x1, x2, x3);
;         }
;         const int f = tm * 128 + wr * 64 + mp * 32 + widen_off(fq);
;         *reinterpret_cast<u32x4*>(p.xb + blk(t, f, 32)) = widen_pair(pk[0], pk[1]);
;       }
;       ss = red_fq(ss);
;       if (fq == 0) p.part[(long)t * 16 + tm * 2 + wr] = ss;
;       curw[0] = nxtw[0];
;       curw[1] = nxtw[1];
;     }
	v_mfma_f32_16x16x32_bf16 v[60:63], v[4:7], v[32:35], v[158:161]
	v_mfma_f32_16x16x32_bf16 v[44:47], v[4:7], v[112:115], v[162:165]
	v_mfma_f32_16x16x32_bf16 v[28:31], v[4:7], v[124:127], v[172:175]
	v_mfma_f32_16x16x32_bf16 v[12:15], v[4:7], v[142:145], v[128:131]
	v_mfma_f32_16x16x32_bf16 v[56:59], v[8:11], v[32:35], v[216:219]
	v_mfma_f32_16x16x32_bf16 v[40:43], v[8:11], v[112:115], v[220:223]
	v_mfma_f32_16x16x32_bf16 v[24:27], v[8:11], v[124:127], v[52:55]
	v_mfma_f32_16x16x32_bf16 v[8:11], v[8:11], v[142:145], v[48:51]
	v_mfma_f32_16x16x32_bf16 v[52:55], v[154:157], v[32:35], v[138:141]
	v_mfma_f32_16x16x32_bf16 v[36:39], v[154:157], v[112:115], v[236:239]
	v_mfma_f32_16x16x32_bf16 v[20:23], v[154:157], v[124:127], v[20:23]
	v_mfma_f32_16x16x32_bf16 v[4:7], v[154:157], v[142:145], v[16:19]
	v_mfma_f32_16x16x32_bf16 v[48:51], v[248:251], v[32:35], v[146:149]
	v_mfma_f32_16x16x32_bf16 v[32:35], v[248:251], v[112:115], v[240:243]
	v_mfma_f32_16x16x32_bf16 v[16:19], v[248:251], v[124:127], v[244:247]
	v_mfma_f32_16x16x32_bf16 v[0:3], v[248:251], v[142:145], v[0:3]
	v_lshl_add_u32 v124, s13, 1, v170
	v_mov_b32_e32 v112, v215
	v_lshlrev_b32_e32 v113, 7, v124
	v_ashrrev_i32_e32 v138, 7, v112
	s_mul_i32 s13, s15, 0x140
	v_lshl_add_u32 v114, v138, 6, v113
	v_lshlrev_b32_e32 v113, 1, v112
	s_add_i32 s12, s12, s13
	v_and_b32_e32 v113, 0x80, v113
	v_lshl_or_b32 v127, s12, 8, v113
	v_lshrrev_b32_e32 v113, 2, v112
	v_and_b32_e32 v125, 15, v112
	v_and_b32_e32 v113, 8, v113
	v_ashrrev_i32_e32 v115, 2, v127
	v_readlane_b32 s80, v253, 25
	v_ashrrev_i32_e32 v114, 5, v114
	v_bfe_u32 v126, v112, 4, 2
	v_and_or_b32 v112, v112, 16, v113
	v_lshlrev_b32_e32 v156, 6, v125
	v_mov_b32_e32 v157, v153
	v_readlane_b32 s84, v253, 29
	v_readlane_b32 s85, v253, 30
	v_add_u32_e32 v114, v114, v115
	v_lshlrev_b32_e32 v152, 1, v112
	v_lshl_add_u64 v[144:145], s[84:85], 0, v[156:157]
	v_ashrrev_i32_e32 v115, 31, v114
	v_lshl_add_u64 v[112:113], v[144:145], 0, v[152:153]
	v_lshlrev_b64 v[146:147], 13, v[114:115]
	v_or_b32_e32 v114, 1, v114
	v_lshl_add_u64 v[150:151], v[112:113], 0, v[146:147]
	v_ashrrev_i32_e32 v115, 31, v114
	global_load_dwordx4 v[158:161], v[150:151], off
	v_lshlrev_b64 v[148:149], 13, v[114:115]
	v_lshl_add_u64 v[154:155], v[112:113], 0, v[148:149]
	global_load_dwordx4 v[128:131], v[154:155], off
	v_and_b32_e32 v113, 64, v185
	v_xor_b32_e32 v112, 16, v185
	v_add_u32_e32 v113, 64, v113
	v_cmp_lt_i32_e32 vcc, v112, v113
	v_or_b32_e32 v142, v127, v125
	v_lshlrev_b32_e32 v140, 1, v124
	v_cndmask_b32_e32 v112, v185, v112, vcc
	v_lshlrev_b32_e32 v172, 2, v112
	v_xor_b32_e32 v112, 32, v185
	v_cmp_lt_i32_e32 vcc, v112, v113
	v_ashrrev_i32_e32 v141, 31, v140
	v_ashrrev_i32_e32 v139, 31, v138
	v_cndmask_b32_e32 v112, v185, v112, vcc
	v_lshlrev_b32_e32 v173, 2, v112
	v_cmp_eq_u32_e32 vcc, 0, v126
	global_load_dwordx4 v[124:127], v[150:151], off offset:1024
	global_load_dwordx4 v[112:115], v[154:155], off offset:1024
	v_readlane_b32 s81, v253, 26
	v_readlane_b32 s82, v253, 27
	v_readlane_b32 s83, v253, 28
	v_readlane_b32 s86, v253, 31
	v_readlane_b32 s87, v253, 32
	v_readlane_b32 s88, v253, 33
	v_readlane_b32 s89, v253, 34
	v_readlane_b32 s90, v253, 35
	v_readlane_b32 s91, v253, 36
	v_readlane_b32 s92, v253, 37
	v_readlane_b32 s93, v253, 38
	v_readlane_b32 s94, v253, 39
	v_readlane_b32 s95, v253, 40
	s_waitcnt vmcnt(0)
	v_mov_b32_e32 v143, v160
	s_nop 1
	v_permlane16_swap_b32_e32 v158, v143
	v_mov_b32_e32 v164, v161
	s_nop 1
	v_permlane16_swap_b32_e32 v159, v164
	v_mov_b32_e32 v176, v130
	v_mov_b32_e32 v182, v131
	v_and_b32_e32 v131, 0xffff0000, v158
	v_lshlrev_b32_e32 v130, 16, v158
	v_pk_add_f32 v[130:131], v[178:179], v[130:131]
	v_and_b32_e32 v161, 0xffff0000, v159
	v_lshlrev_b32_e32 v160, 16, v159
	v_pk_add_f32 v[162:163], v[180:181], v[160:161]
	v_pk_mul_f32 v[160:161], v[130:131], v[130:131]
	v_cvt_pk_bf16_f32 v178, v130, v131
	v_and_b32_e32 v131, 0xffff0000, v143
	v_lshlrev_b32_e32 v130, 16, v143
	v_pk_mul_f32 v[158:159], v[162:163], v[162:163]
	v_cvt_pk_bf16_f32 v179, v162, v163
	v_pk_add_f32 v[130:131], v[224:225], v[130:131]
	v_and_b32_e32 v163, 0xffff0000, v164
	v_lshlrev_b32_e32 v162, 16, v164
	v_pk_add_f32 v[174:175], v[226:227], v[162:163]
	v_pk_mul_f32 v[164:165], v[130:131], v[130:131]
	v_cvt_pk_bf16_f32 v180, v130, v131
	v_lshl_add_u64 v[130:131], s[84:85], 0, v[146:147]
	v_pk_mul_f32 v[162:163], v[174:175], v[174:175]
	v_cvt_pk_bf16_f32 v181, v174, v175
	v_lshl_add_u64 v[174:175], v[130:131], 0, v[156:157]
	v_permlane16_swap_b32_e32 v128, v176
	v_permlane16_swap_b32_e32 v178, v180
	v_permlane16_swap_b32_e32 v179, v181
	v_lshl_add_u64 v[174:175], v[174:175], 0, v[152:153]
	v_permlane16_swap_b32_e32 v129, v182
	global_store_dwordx4 v[174:175], v[178:181], off
	v_and_b32_e32 v175, 0xffff0000, v128
	v_lshlrev_b32_e32 v174, 16, v128
	v_pk_add_f32 v[120:121], v[120:121], v[174:175]
	v_and_b32_e32 v175, 0xffff0000, v129
	v_lshlrev_b32_e32 v174, 16, v129
	v_pk_add_f32 v[122:123], v[122:123], v[174:175]
	v_pk_mul_f32 v[128:129], v[120:121], v[120:121]
	v_pk_mul_f32 v[174:175], v[122:123], v[122:123]
	v_cvt_pk_bf16_f32 v120, v120, v121
	v_cvt_pk_bf16_f32 v121, v122, v123
	v_and_b32_e32 v123, 0xffff0000, v176
	v_lshlrev_b32_e32 v122, 16, v176
	v_pk_add_f32 v[116:117], v[116:117], v[122:123]
	v_and_b32_e32 v123, 0xffff0000, v182
	v_lshlrev_b32_e32 v122, 16, v182
	v_add_f32_e32 v143, v164, v165
	v_add_f32_e32 v160, v160, v161
	v_pk_add_f32 v[118:119], v[118:119], v[122:123]
	v_pk_mul_f32 v[122:123], v[116:117], v[116:117]
	v_add_f32_e32 v143, v162, v143
	v_add_f32_e32 v158, v158, v160
	v_add_f32_e32 v128, v128, v129
	v_pk_mul_f32 v[178:179], v[118:119], v[118:119]
	v_add_f32_e32 v143, v163, v143
	v_add_f32_e32 v158, v159, v158
	v_add_f32_e32 v128, v174, v128
	v_add_f32_e32 v122, v122, v123
	v_add_f32_e32 v143, v158, v143
	v_add_f32_e32 v128, v175, v128
	v_add_f32_e32 v122, v178, v122
	v_add_f32_e32 v128, v143, v128
	v_add_f32_e32 v122, v179, v122
	v_add_f32_e32 v143, v122, v128
	v_lshl_add_u64 v[128:129], s[84:85], 0, v[148:149]
	v_cvt_pk_bf16_f32 v122, v116, v117
	v_cvt_pk_bf16_f32 v123, v118, v119
	v_lshl_add_u64 v[116:117], v[128:129], 0, v[156:157]
	v_permlane16_swap_b32_e32 v120, v122
	v_permlane16_swap_b32_e32 v121, v123
	v_lshl_add_u64 v[116:117], v[116:117], 0, v[152:153]
	global_store_dwordx4 v[116:117], v[120:123], off
	ds_bpermute_b32 v116, v172, v143
	s_waitcnt lgkmcnt(0)
	v_add_f32_e32 v116, v143, v116
	ds_bpermute_b32 v117, v173, v116
	s_and_saveexec_b64 s[12:13], vcc
	s_cbranch_execz .LBB0_267
; template <int MODE, int NSUB>
; __device__ __forceinline__ void epilogue(const Params& p, int layer, f32x4 (&acc)[4][NSUB], int tm, int tn, int g,
;                                          const float* s_rstd, const int tid_in) {
;     ...
;       ss = red_fq(ss);
;       if (fq == 0) p.part[(long)t * 16 + tm * 2 + wr] = ss;
	v_ashrrev_i32_e32 v143, 31, v142
	v_readlane_b32 s64, v253, 25
	v_lshlrev_b64 v[118:119], 6, v[142:143]
	v_readlane_b32 s70, v253, 31
	v_readlane_b32 s71, v253, 32
	s_waitcnt lgkmcnt(0)
	v_add_f32_e32 v116, v116, v117
	v_readlane_b32 s65, v253, 26
	v_lshl_add_u64 v[118:119], s[70:71], 0, v[118:119]
	v_lshl_add_u64 v[118:119], v[140:141], 2, v[118:119]
	v_lshl_add_u64 v[118:119], v[138:139], 2, v[118:119]
	v_readlane_b32 s66, v253, 27
	v_readlane_b32 s67, v253, 28
	v_readlane_b32 s68, v253, 29
	v_readlane_b32 s69, v253, 30
	v_readlane_b32 s72, v253, 33
	v_readlane_b32 s73, v253, 34
	v_readlane_b32 s74, v253, 35
	v_readlane_b32 s75, v253, 36
	v_readlane_b32 s76, v253, 37
	v_readlane_b32 s77, v253, 38
	v_readlane_b32 s78, v253, 39
	v_readlane_b32 s79, v253, 40
	global_store_dword v[118:119], v116, off

; template <int NK, bool BNT = false> ...
;     ...
;   auto stage = [&](int kt, int bufc) {
;     unsigned char* sa = smem + bufc * BIG_STAGE;
;     const unsigned char* Ab = Abase + (long)kt * 8192 + soff;
;     const unsigned char* Bb = Bbase + (long)kt * 8192 + soff;
;     glds16(Ab, sa + sb0);
;     glds16(Ab + astride * 2, sa + 8192 + sb0);
;     if constexpr (BNT) {
;       glds16_nt(Bb, sa + 16384 + sb0);
;       glds16_nt(Bb + bstride * 2, sa + 24576 + sb0);
;     } else {
;       glds16(Bb, sa + 16384 + sb0);
;       glds16(Bb + bstride * 2, sa + 24576 + sb0);
;     }
;   };
;   const int rd = fr * 64 + ((fq ^ (((fr >> 3) & 1) << 1)) * 16);
;   const int aoff = wr * 64 * 64 + rd;
;   const int boff = 16384 + wc * 128 * 64 + rd;
;   auto kstep = [&](int T, int cur, int nxt, bool do_stage) {
;     const unsigned char* sa = smem + cur * BIG_STAGE;
;     bf16x8 af[4], bfr[4];
; #pragma unroll
;     for (int m = 0; m < 4; ++m) af[m] = *reinterpret_cast<const bf16x8*>(sa + aoff + m * 1024);
; #pragma unroll
;     for (int n = 0; n < 4; ++n) bfr[n] = *reinterpret_cast<const bf16x8*>(sa + boff + n * 1024);
;     __builtin_amdgcn_sched_barrier(0);
;     if (do_stage) stage(T + 3, nxt);
; #pragma unroll
;     for (int m = 0; m < 4; ++m)
; #pragma unroll
;       for (int n = 0; n < 4; ++n) acc[m][n] = __builtin_amdgcn_mfma_f32_16x16x32_bf16(af[m], bfr[n], acc[m][n], 0, 0, 0);
;     if (do_stage) {
; #pragma unroll
;       for (int q = 0; q < NG; ++q) {
;         __builtin_amdgcn_sched_group_barrier(0x008, 3, 0);
;         __builtin_amdgcn_sched_group_barrier(0x010, 1, 0);
;       }
;       __builtin_amdgcn_sched_group_barrier(0x008, 16 - 3 * NG, 0);
;     }
;     __builtin_amdgcn_sched_barrier(0);
; #pragma unroll
;     for (int n = 0; n < 4; ++n) bfr[n] = *reinterpret_cast<const bf16x8*>(sa + boff + (4 + n) * 1024);
; #pragma unroll
;     for (int m = 0; m < 4; ++m)
; #pragma unroll
;       for (int n = 0; n < 4; ++n)
;         acc[m][4 + n] = __builtin_amdgcn_mfma_f32_16x16x32_bf16(af[m], bfr[n], acc[m][4 + n], 0, 0, 0);
;     __builtin_amdgcn_sched_barrier(0);
.LBB0_290:
	s_waitcnt lgkmcnt(3)
	v_mfma_f32_16x16x32_bf16 v[124:127], v[216:219], v[232:235], v[124:127]
	v_add_u32_e32 v163, 0x18000, v146
	v_lshl_add_u64 v[144:145], v[138:139], 0, s[12:13]
	v_mfma_f32_16x16x32_bf16 v[108:111], v[220:223], v[232:235], v[108:111]
	v_lshl_add_u64 v[164:165], v[144:145], 0, s[60:61]
	s_add_i32 m0, s100, 0x18000
	v_mfma_f32_16x16x32_bf16 v[88:91], v[224:227], v[232:235], v[88:91]
	s_waitcnt vmcnt(4)
	s_barrier
	v_lshl_add_u64 v[142:143], v[140:141], 0, s[12:13]
	v_lshl_add_u64 v[168:169], v[144:145], 0, s[80:81]
	v_mfma_f32_16x16x32_bf16 v[44:47], v[228:231], v[232:235], v[44:47]
	v_lshl_add_u64 v[166:167], v[142:143], 0, s[60:61]
	global_load_lds_dwordx4 v[164:165], off
	s_waitcnt lgkmcnt(2)
	v_mfma_f32_16x16x32_bf16 v[120:123], v[216:219], v[236:239], v[120:123]
	ds_read_b128 v[232:235], v148 offset:20480
	v_mfma_f32_16x16x32_bf16 v[104:107], v[220:223], v[236:239], v[104:107]
	v_add_u32_e32 v164, 0x1a000, v146
	v_add_u32_e32 v165, 0x1c000, v146
	v_mfma_f32_16x16x32_bf16 v[76:79], v[224:227], v[236:239], v[76:79]
	s_add_i32 m0, s100, 0x1a000
	v_mfma_f32_16x16x32_bf16 v[40:43], v[228:231], v[236:239], v[40:43]
	global_load_lds_dwordx4 v[168:169], off
	s_waitcnt lgkmcnt(2)
	v_mfma_f32_16x16x32_bf16 v[116:119], v[216:219], v[240:243], v[116:119]
	ds_read_b128 v[236:239], v148 offset:21504
	v_mfma_f32_16x16x32_bf16 v[100:103], v[220:223], v[240:243], v[100:103]
	s_add_i32 m0, s100, 0x1c000
	v_mfma_f32_16x16x32_bf16 v[68:71], v[224:227], v[240:243], v[68:71]
	v_lshl_add_u64 v[168:169], v[142:143], 0, s[80:81]
	v_mfma_f32_16x16x32_bf16 v[36:39], v[228:231], v[240:243], v[36:39]
	global_load_lds_dwordx4 v[166:167], off
	s_waitcnt lgkmcnt(2)
	v_mfma_f32_16x16x32_bf16 v[112:115], v[216:219], v[244:247], v[112:115]
	ds_read_b128 v[240:243], v148 offset:22528
	v_mfma_f32_16x16x32_bf16 v[96:99], v[220:223], v[244:247], v[96:99]
	v_add_u32_e32 v166, 0x1e000, v146
	v_mfma_f32_16x16x32_bf16 v[64:67], v[224:227], v[244:247], v[64:67]
	s_add_i32 m0, s100, 0x1e000
	v_mfma_f32_16x16x32_bf16 v[32:35], v[228:231], v[244:247], v[32:35]
	global_load_lds_dwordx4 v[168:169], off
	s_waitcnt lgkmcnt(2)
	v_mfma_f32_16x16x32_bf16 v[92:95], v[216:219], v[232:235], v[92:95]
	ds_read_b128 v[244:247], v148 offset:23552
	v_mfma_f32_16x16x32_bf16 v[60:63], v[220:223], v[232:235], v[60:63]
	ds_read_b128 v[186:189], v147 offset:32768
	v_mfma_f32_16x16x32_bf16 v[28:31], v[224:227], v[232:235], v[28:31]
	ds_read_b128 v[190:193], v147 offset:33792
	v_mfma_f32_16x16x32_bf16 v[12:15], v[228:231], v[232:235], v[12:15]
	ds_read_b128 v[194:197], v147 offset:34816
	s_waitcnt lgkmcnt(5)
	v_mfma_f32_16x16x32_bf16 v[84:87], v[216:219], v[236:239], v[84:87]
	ds_read_b128 v[202:205], v147 offset:35840
	ds_read_b128 v[232:235], v148 offset:49152
	v_mfma_f32_16x16x32_bf16 v[56:59], v[220:223], v[236:239], v[56:59]
	v_mfma_f32_16x16x32_bf16 v[24:27], v[224:227], v[236:239], v[24:27]
	v_mfma_f32_16x16x32_bf16 v[8:11], v[228:231], v[236:239], v[8:11]
	s_waitcnt lgkmcnt(6)
	v_mfma_f32_16x16x32_bf16 v[80:83], v[216:219], v[240:243], v[80:83]
	ds_read_b128 v[236:239], v148 offset:50176
	v_mfma_f32_16x16x32_bf16 v[52:55], v[220:223], v[240:243], v[52:55]
	v_mfma_f32_16x16x32_bf16 v[20:23], v[224:227], v[240:243], v[20:23]
	v_mfma_f32_16x16x32_bf16 v[4:7], v[228:231], v[240:243], v[4:7]
	s_waitcnt lgkmcnt(6)
	v_mfma_f32_16x16x32_bf16 v[72:75], v[216:219], v[244:247], v[72:75]
	ds_read_b128 v[240:243], v148 offset:51200
	v_mfma_f32_16x16x32_bf16 v[48:51], v[220:223], v[244:247], v[48:51]
	v_mfma_f32_16x16x32_bf16 v[16:19], v[224:227], v[244:247], v[16:19]
	v_mfma_f32_16x16x32_bf16 v[0:3], v[228:231], v[244:247], v[0:3]
	ds_read_b128 v[244:247], v148 offset:52224
	s_waitcnt lgkmcnt(3)
	v_mfma_f32_16x16x32_bf16 v[124:127], v[186:189], v[232:235], v[124:127]
	v_lshl_add_u64 v[168:169], v[144:145], 0, s[62:63]
	v_mfma_f32_16x16x32_bf16 v[108:111], v[190:193], v[232:235], v[108:111]
	s_mov_b32 m0, s100
	v_mfma_f32_16x16x32_bf16 v[88:91], v[194:197], v[232:235], v[88:91]
	s_waitcnt vmcnt(4)
	s_barrier
	v_lshl_add_u64 v[182:183], v[142:143], 0, s[62:63]
	v_mfma_f32_16x16x32_bf16 v[44:47], v[202:205], v[232:235], v[44:47]
	global_load_lds_dwordx4 v[168:169], off
	s_waitcnt lgkmcnt(2)
	v_mfma_f32_16x16x32_bf16 v[120:123], v[186:189], v[236:239], v[120:123]
	ds_read_b128 v[232:235], v148 offset:53248
	v_mfma_f32_16x16x32_bf16 v[104:107], v[190:193], v[236:239], v[104:107]
	v_lshl_add_u64 v[168:169], v[144:145], 0, s[0:1]
	v_mfma_f32_16x16x32_bf16 v[76:79], v[194:197], v[236:239], v[76:79]
	s_add_i32 m0, s100, 0x2000
	v_mfma_f32_16x16x32_bf16 v[40:43], v[202:205], v[236:239], v[40:43]
	global_load_lds_dwordx4 v[168:169], off
	s_waitcnt lgkmcnt(2)
	v_mfma_f32_16x16x32_bf16 v[116:119], v[186:189], v[240:243], v[116:119]
	ds_read_b128 v[236:239], v148 offset:54272
	v_mfma_f32_16x16x32_bf16 v[100:103], v[190:193], v[240:243], v[100:103]
	s_add_i32 m0, s100, 0x4000
	v_mfma_f32_16x16x32_bf16 v[68:71], v[194:197], v[240:243], v[68:71]
	v_lshl_add_u64 v[168:169], v[142:143], 0, s[0:1]
	v_mfma_f32_16x16x32_bf16 v[36:39], v[202:205], v[240:243], v[36:39]
	global_load_lds_dwordx4 v[182:183], off
	s_waitcnt lgkmcnt(2)
	v_mfma_f32_16x16x32_bf16 v[112:115], v[186:189], v[244:247], v[112:115]
	ds_read_b128 v[240:243], v148 offset:55296
	v_mfma_f32_16x16x32_bf16 v[96:99], v[190:193], v[244:247], v[96:99]
	s_add_i32 m0, s100, 0x6000
	v_mfma_f32_16x16x32_bf16 v[64:67], v[194:197], v[244:247], v[64:67]
	global_load_lds_dwordx4 v[168:169], off
	v_mfma_f32_16x16x32_bf16 v[32:35], v[202:205], v[244:247], v[32:35]
	s_waitcnt lgkmcnt(2)
; template <int NK, bool BNT = false> ...
;     ...
;   auto kstep = [&](int T, int cur, int nxt, bool do_stage) {
;     const unsigned char* sa = smem + cur * BIG_STAGE;
;     bf16x8 af[4], bfr[4];
; #pragma unroll
;     for (int m = 0; m < 4; ++m) af[m] = *reinterpret_cast<const bf16x8*>(sa + aoff + m * 1024);
; #pragma unroll
;     for (int n = 0; n < 4; ++n) bfr[n] = *reinterpret_cast<const bf16x8*>(sa + boff + n * 1024);
;     __builtin_amdgcn_sched_barrier(0);
;     if (do_stage) stage(T + 3, nxt);
; #pragma unroll
;     for (int m = 0; m < 4; ++m)
; #pragma unroll
;       for (int n = 0; n < 4; ++n) acc[m][n] = __builtin_amdgcn_mfma_f32_16x16x32_bf16(af[m], bfr[n], acc[m][n], 0, 0, 0);
;     if (do_stage) {
; #pragma unroll
;       for (int q = 0; q < NG; ++q) {
;         __builtin_amdgcn_sched_group_barrier(0x008, 3, 0);
;         __builtin_amdgcn_sched_group_barrier(0x010, 1, 0);
;       }
;       __builtin_amdgcn_sched_group_barrier(0x008, 16 - 3 * NG, 0);
;     }
;     __builtin_amdgcn_sched_barrier(0);
; #pragma unroll
;     for (int n = 0; n < 4; ++n) bfr[n] = *reinterpret_cast<const bf16x8*>(sa + boff + (4 + n) * 1024);
; #pragma unroll
;     for (int m = 0; m < 4; ++m)
; #pragma unroll
;       for (int n = 0; n < 4; ++n)
;         acc[m][4 + n] = __builtin_amdgcn_mfma_f32_16x16x32_bf16(af[m], bfr[n], acc[m][4 + n], 0, 0, 0);
;     __builtin_amdgcn_sched_barrier(0);
	v_mfma_f32_16x16x32_bf16 v[92:95], v[186:189], v[232:235], v[92:95]
	ds_read_b128 v[244:247], v148 offset:56320
	v_mfma_f32_16x16x32_bf16 v[60:63], v[190:193], v[232:235], v[60:63]
	ds_read_b128 v[216:219], v210
	v_mfma_f32_16x16x32_bf16 v[28:31], v[194:197], v[232:235], v[28:31]
	ds_read_b128 v[220:223], v210 offset:1024
	v_mfma_f32_16x16x32_bf16 v[12:15], v[202:205], v[232:235], v[12:15]
	ds_read_b128 v[224:227], v210 offset:2048
	s_waitcnt lgkmcnt(5)
	v_mfma_f32_16x16x32_bf16 v[84:87], v[186:189], v[236:239], v[84:87]
	ds_read_b128 v[228:231], v210 offset:3072
	ds_read_b128 v[232:235], v211
	v_mfma_f32_16x16x32_bf16 v[56:59], v[190:193], v[236:239], v[56:59]
	v_mfma_f32_16x16x32_bf16 v[24:27], v[194:197], v[236:239], v[24:27]
	v_mfma_f32_16x16x32_bf16 v[8:11], v[202:205], v[236:239], v[8:11]
	s_waitcnt lgkmcnt(6)
	v_mfma_f32_16x16x32_bf16 v[80:83], v[186:189], v[240:243], v[80:83]
	ds_read_b128 v[236:239], v211 offset:1024
	v_mfma_f32_16x16x32_bf16 v[52:55], v[190:193], v[240:243], v[52:55]
	v_mfma_f32_16x16x32_bf16 v[20:23], v[194:197], v[240:243], v[20:23]
	v_mfma_f32_16x16x32_bf16 v[4:7], v[202:205], v[240:243], v[4:7]
	s_waitcnt lgkmcnt(6)
	v_mfma_f32_16x16x32_bf16 v[72:75], v[186:189], v[244:247], v[72:75]
	ds_read_b128 v[240:243], v211 offset:2048
	v_mfma_f32_16x16x32_bf16 v[48:51], v[190:193], v[244:247], v[48:51]
	v_mfma_f32_16x16x32_bf16 v[16:19], v[194:197], v[244:247], v[16:19]
	v_mfma_f32_16x16x32_bf16 v[0:3], v[202:205], v[244:247], v[0:3]
	ds_read_b128 v[244:247], v211 offset:3072
	s_waitcnt lgkmcnt(3)
	v_mfma_f32_16x16x32_bf16 v[124:127], v[216:219], v[232:235], v[124:127]
	v_lshl_add_u64 v[174:175], v[144:145], 0, s[2:3]
	v_mfma_f32_16x16x32_bf16 v[108:111], v[220:223], v[232:235], v[108:111]
	s_add_i32 m0, s100, 0x8000
	v_mfma_f32_16x16x32_bf16 v[88:91], v[224:227], v[232:235], v[88:91]
	s_waitcnt vmcnt(4)
	s_barrier
	v_lshl_add_u64 v[178:179], v[142:143], 0, s[2:3]
	v_mfma_f32_16x16x32_bf16 v[44:47], v[228:231], v[232:235], v[44:47]
	global_load_lds_dwordx4 v[174:175], off
	s_waitcnt lgkmcnt(2)
	v_mfma_f32_16x16x32_bf16 v[120:123], v[216:219], v[236:239], v[120:123]
	ds_read_b128 v[232:235], v211 offset:4096
	v_mfma_f32_16x16x32_bf16 v[104:107], v[220:223], v[236:239], v[104:107]
	v_lshl_add_u64 v[174:175], v[144:145], 0, s[52:53]
	v_mfma_f32_16x16x32_bf16 v[76:79], v[224:227], v[236:239], v[76:79]
	s_add_i32 m0, s100, 0xa000
	v_mfma_f32_16x16x32_bf16 v[40:43], v[228:231], v[236:239], v[40:43]
	global_load_lds_dwordx4 v[174:175], off
	s_waitcnt lgkmcnt(2)
	v_mfma_f32_16x16x32_bf16 v[116:119], v[216:219], v[240:243], v[116:119]
	ds_read_b128 v[236:239], v211 offset:5120
	v_mfma_f32_16x16x32_bf16 v[100:103], v[220:223], v[240:243], v[100:103]
	s_add_i32 m0, s100, 0xc000
	v_mfma_f32_16x16x32_bf16 v[68:71], v[224:227], v[240:243], v[68:71]
	v_lshl_add_u64 v[174:175], v[142:143], 0, s[52:53]
	v_mfma_f32_16x16x32_bf16 v[36:39], v[228:231], v[240:243], v[36:39]
	global_load_lds_dwordx4 v[178:179], off
	s_waitcnt lgkmcnt(2)
	v_mfma_f32_16x16x32_bf16 v[112:115], v[216:219], v[244:247], v[112:115]
	ds_read_b128 v[240:243], v211 offset:6144
	v_mfma_f32_16x16x32_bf16 v[96:99], v[220:223], v[244:247], v[96:99]
	s_add_i32 m0, s100, 0xe000
	v_mfma_f32_16x16x32_bf16 v[64:67], v[224:227], v[244:247], v[64:67]
	global_load_lds_dwordx4 v[174:175], off
	v_mfma_f32_16x16x32_bf16 v[32:35], v[228:231], v[244:247], v[32:35]
	s_waitcnt lgkmcnt(2)
	v_mfma_f32_16x16x32_bf16 v[92:95], v[216:219], v[232:235], v[92:95]
	ds_read_b128 v[244:247], v211 offset:7168
	v_mfma_f32_16x16x32_bf16 v[60:63], v[220:223], v[232:235], v[60:63]
	ds_read_b128 v[186:189], v210 offset:32768
	v_mfma_f32_16x16x32_bf16 v[28:31], v[224:227], v[232:235], v[28:31]
	ds_read_b128 v[190:193], v210 offset:33792
	v_mfma_f32_16x16x32_bf16 v[12:15], v[228:231], v[232:235], v[12:15]
	ds_read_b128 v[194:197], v210 offset:34816
	s_waitcnt lgkmcnt(5)
	v_mfma_f32_16x16x32_bf16 v[84:87], v[216:219], v[236:239], v[84:87]
	ds_read_b128 v[202:205], v210 offset:35840
	ds_read_b128 v[232:235], v211 offset:32768
	v_mfma_f32_16x16x32_bf16 v[56:59], v[220:223], v[236:239], v[56:59]
	v_mfma_f32_16x16x32_bf16 v[24:27], v[224:227], v[236:239], v[24:27]
	v_mfma_f32_16x16x32_bf16 v[8:11], v[228:231], v[236:239], v[8:11]
	s_waitcnt lgkmcnt(6)
	v_mfma_f32_16x16x32_bf16 v[80:83], v[216:219], v[240:243], v[80:83]
	ds_read_b128 v[236:239], v211 offset:33792
	v_mfma_f32_16x16x32_bf16 v[52:55], v[220:223], v[240:243], v[52:55]
	v_mfma_f32_16x16x32_bf16 v[20:23], v[224:227], v[240:243], v[20:23]
	v_mfma_f32_16x16x32_bf16 v[4:7], v[228:231], v[240:243], v[4:7]
	s_waitcnt lgkmcnt(6)
	v_mfma_f32_16x16x32_bf16 v[72:75], v[216:219], v[244:247], v[72:75]
	ds_read_b128 v[240:243], v211 offset:34816
	v_mfma_f32_16x16x32_bf16 v[48:51], v[220:223], v[244:247], v[48:51]
	v_mfma_f32_16x16x32_bf16 v[16:19], v[224:227], v[244:247], v[16:19]
	v_mfma_f32_16x16x32_bf16 v[0:3], v[228:231], v[244:247], v[0:3]
	ds_read_b128 v[244:247], v211 offset:35840
	s_waitcnt lgkmcnt(3)
	v_mfma_f32_16x16x32_bf16 v[124:127], v[186:189], v[232:235], v[124:127]
	v_lshl_add_u64 v[248:249], v[144:145], 0, s[54:55]
	v_mfma_f32_16x16x32_bf16 v[108:111], v[190:193], v[232:235], v[108:111]
	s_add_i32 m0, s100, 0x10000
	v_mfma_f32_16x16x32_bf16 v[88:91], v[194:197], v[232:235], v[88:91]
	s_waitcnt vmcnt(4)
	s_barrier
; #define BIG_SYNC(N)                                              \
;   asm volatile("s_waitcnt vmcnt(%0)" ::"n"(N) : "memory");       \
;   __builtin_amdgcn_s_barrier();                                  \
;   asm volatile("" ::: "memory");                                 \
;   __builtin_amdgcn_sched_barrier(0);
; template <int NK, bool BNT = false> ...
;     ...
;   for (int it = 0; it < NK / 4 - 1; ++it) {
;     const int t = it * 4;
;     BIG_SYNC(2 * NG); kstep(t, 0, 3, true);
;     BIG_SYNC(2 * NG); kstep(t + 1, 1, 0, true);
;     BIG_SYNC(2 * NG); kstep(t + 2, 2, 1, true);
;     BIG_SYNC(2 * NG); kstep(t + 3, 3, 2, true);
;   }
;   BIG_SYNC(2 * NG); kstep(NK - 4, 0, 3, true);
;   BIG_SYNC(2 * NG); kstep(NK - 3, 1, 0, false);
;   BIG_SYNC(NG);     kstep(NK - 2, 2, 0, false);
;   BIG_SYNC(0);      kstep(NK - 1, 3, 0, false);
	v_lshl_add_u64 v[144:145], v[144:145], 0, s[56:57]
	v_mfma_f32_16x16x32_bf16 v[44:47], v[202:205], v[232:235], v[44:47]
	v_lshl_add_u64 v[250:251], v[142:143], 0, s[54:55]
	s_waitcnt lgkmcnt(2)
	v_mfma_f32_16x16x32_bf16 v[120:123], v[186:189], v[236:239], v[120:123]
	ds_read_b128 v[232:235], v211 offset:36864
	v_mfma_f32_16x16x32_bf16 v[104:107], v[190:193], v[236:239], v[104:107]
	v_lshl_add_u64 v[142:143], v[142:143], 0, s[56:57]
	v_mfma_f32_16x16x32_bf16 v[76:79], v[194:197], v[236:239], v[76:79]
	global_load_lds_dwordx4 v[248:249], off
	v_mfma_f32_16x16x32_bf16 v[40:43], v[202:205], v[236:239], v[40:43]
	s_add_i32 m0, s100, 0x12000
	s_waitcnt lgkmcnt(2)
	v_mfma_f32_16x16x32_bf16 v[116:119], v[186:189], v[240:243], v[116:119]
	ds_read_b128 v[236:239], v211 offset:37888
	v_mfma_f32_16x16x32_bf16 v[100:103], v[190:193], v[240:243], v[100:103]
	global_load_lds_dwordx4 v[144:145], off
	v_mfma_f32_16x16x32_bf16 v[68:71], v[194:197], v[240:243], v[68:71]
	s_add_i32 m0, s100, 0x14000
	v_mfma_f32_16x16x32_bf16 v[36:39], v[202:205], v[240:243], v[36:39]
	global_load_lds_dwordx4 v[250:251], off
	s_waitcnt lgkmcnt(2)
	v_mfma_f32_16x16x32_bf16 v[112:115], v[186:189], v[244:247], v[112:115]
	ds_read_b128 v[240:243], v211 offset:38912
	v_mfma_f32_16x16x32_bf16 v[96:99], v[190:193], v[244:247], v[96:99]
	s_add_i32 m0, s100, 0x16000
	v_mfma_f32_16x16x32_bf16 v[64:67], v[194:197], v[244:247], v[64:67]
	global_load_lds_dwordx4 v[142:143], off
	v_mfma_f32_16x16x32_bf16 v[32:35], v[202:205], v[244:247], v[32:35]
	s_waitcnt lgkmcnt(2)
	v_mfma_f32_16x16x32_bf16 v[92:95], v[186:189], v[232:235], v[92:95]
	ds_read_b128 v[244:247], v211 offset:39936
	v_mfma_f32_16x16x32_bf16 v[60:63], v[190:193], v[232:235], v[60:63]
	ds_read_b128 v[216:219], v147
	v_mfma_f32_16x16x32_bf16 v[28:31], v[194:197], v[232:235], v[28:31]
	ds_read_b128 v[220:223], v147 offset:1024
	v_mfma_f32_16x16x32_bf16 v[12:15], v[202:205], v[232:235], v[12:15]
	ds_read_b128 v[224:227], v147 offset:2048
	s_waitcnt lgkmcnt(5)
	v_mfma_f32_16x16x32_bf16 v[84:87], v[186:189], v[236:239], v[84:87]
	ds_read_b128 v[228:231], v147 offset:3072
	ds_read_b128 v[232:235], v148 offset:16384
	v_mfma_f32_16x16x32_bf16 v[56:59], v[190:193], v[236:239], v[56:59]
	v_mfma_f32_16x16x32_bf16 v[24:27], v[194:197], v[236:239], v[24:27]
	v_mfma_f32_16x16x32_bf16 v[8:11], v[202:205], v[236:239], v[8:11]
	s_waitcnt lgkmcnt(6)
	v_mfma_f32_16x16x32_bf16 v[80:83], v[186:189], v[240:243], v[80:83]
	ds_read_b128 v[236:239], v148 offset:17408
	v_mfma_f32_16x16x32_bf16 v[52:55], v[190:193], v[240:243], v[52:55]
	v_mfma_f32_16x16x32_bf16 v[20:23], v[194:197], v[240:243], v[20:23]
	v_mfma_f32_16x16x32_bf16 v[4:7], v[202:205], v[240:243], v[4:7]
	s_waitcnt lgkmcnt(6)
	v_mfma_f32_16x16x32_bf16 v[72:75], v[186:189], v[244:247], v[72:75]
	ds_read_b128 v[240:243], v148 offset:18432
	v_mfma_f32_16x16x32_bf16 v[48:51], v[190:193], v[244:247], v[48:51]
	v_mfma_f32_16x16x32_bf16 v[16:19], v[194:197], v[244:247], v[16:19]
	v_mfma_f32_16x16x32_bf16 v[0:3], v[202:205], v[244:247], v[0:3]
	ds_read_b128 v[244:247], v148 offset:19456
	s_add_u32 s12, s12, 0x8000
	s_addc_u32 s13, s13, 0
	s_cmp_lg_u32 s12, 0x38000
	s_cbranch_scc1 .LBB0_290
	v_add_u32_e32 v167, 0x10000, v147
	v_or_b32_e32 v168, 0x10000, v149
	v_add_u32_e32 v169, 0x10400, v149
	v_add_u32_e32 v170, 0x10800, v149
	v_add_u32_e32 v172, 0x10c00, v149
	v_add_u32_e32 v173, 0x11000, v149
	v_add_u32_e32 v174, 0x11400, v149
	v_add_u32_e32 v175, 0x11800, v149
	v_add_u32_e32 v178, 0x11c00, v149
	v_add_u32_e32 v176, 0x18000, v147
	v_or_b32_e32 v179, 0x18000, v149
	v_add_u32_e32 v180, 0x18400, v149
	v_add_u32_e32 v181, 0x18800, v149
	v_add_u32_e32 v182, 0x18c00, v149
	v_add_u32_e32 v142, 0x19000, v149
	v_add_u32_e32 v143, 0x19400, v149
	v_add_u32_e32 v144, 0x19800, v149
	v_add_u32_e32 v145, 0x19c00, v149
	s_waitcnt lgkmcnt(3)
	v_mfma_f32_16x16x32_bf16 v[124:127], v[216:219], v[232:235], v[124:127]
	s_mov_b64 s[12:13], 0x3e000
	v_readfirstlane_b32 s11, v163
	v_mfma_f32_16x16x32_bf16 v[108:111], v[220:223], v[232:235], v[108:111]
	v_lshl_add_u64 v[198:199], v[136:137], 0, s[12:13]
	v_lshl_add_u64 v[200:201], v[134:135], 0, s[12:13]
	v_mfma_f32_16x16x32_bf16 v[88:91], v[224:227], v[232:235], v[88:91]
	s_waitcnt vmcnt(4)
	s_barrier
; #define BIG_SYNC(N)                                              \
;   asm volatile("s_waitcnt vmcnt(%0)" ::"n"(N) : "memory");       \
;   __builtin_amdgcn_s_barrier();                                  \
;   asm volatile("" ::: "memory");                                 \
;   __builtin_amdgcn_sched_barrier(0);
; template <int NK, bool BNT = false> ...
;     ...
;   auto kstep = [&](int T, int cur, int nxt, bool do_stage) {
;     const unsigned char* sa = smem + cur * BIG_STAGE;
;     bf16x8 af[4], bfr[4];
; #pragma unroll
;     for (int m = 0; m < 4; ++m) af[m] = *reinterpret_cast<const bf16x8*>(sa + aoff + m * 1024);
; #pragma unroll
;     for (int n = 0; n < 4; ++n) bfr[n] = *reinterpret_cast<const bf16x8*>(sa + boff + n * 1024);
;     __builtin_amdgcn_sched_barrier(0);
;     if (do_stage) stage(T + 3, nxt);
; #pragma unroll
;     for (int m = 0; m < 4; ++m)
; #pragma unroll
;       for (int n = 0; n < 4; ++n) acc[m][n] = __builtin_amdgcn_mfma_f32_16x16x32_bf16(af[m], bfr[n], acc[m][n], 0, 0, 0);
;     if (do_stage) {
; #pragma unroll
;       for (int q = 0; q < NG; ++q) {
;         __builtin_amdgcn_sched_group_barrier(0x008, 3, 0);
;         __builtin_amdgcn_sched_group_barrier(0x010, 1, 0);
;       }
;       __builtin_amdgcn_sched_group_barrier(0x008, 16 - 3 * NG, 0);
;     }
;     __builtin_amdgcn_sched_barrier(0);
; #pragma unroll
;     for (int n = 0; n < 4; ++n) bfr[n] = *reinterpret_cast<const bf16x8*>(sa + boff + (4 + n) * 1024);
; #pragma unroll
;     for (int m = 0; m < 4; ++m)
; #pragma unroll
;       for (int n = 0; n < 4; ++n)
;         acc[m][4 + n] = __builtin_amdgcn_mfma_f32_16x16x32_bf16(af[m], bfr[n], acc[m][4 + n], 0, 0, 0);
;     __builtin_amdgcn_sched_barrier(0);
;   };
;     ...
;   stage(0, 0);
;   stage(1, 1);
;   stage(2, 2);
;   for (int it = 0; it < NK / 4 - 1; ++it) {
;     const int t = it * 4;
;     BIG_SYNC(2 * NG); kstep(t, 0, 3, true);
;     BIG_SYNC(2 * NG); kstep(t + 1, 1, 0, true);
;     BIG_SYNC(2 * NG); kstep(t + 2, 2, 1, true);
;     BIG_SYNC(2 * NG); kstep(t + 3, 3, 2, true);
;   }
;   BIG_SYNC(2 * NG); kstep(NK - 4, 0, 3, true);
;   BIG_SYNC(2 * NG); kstep(NK - 3, 1, 0, false);
;   BIG_SYNC(NG);     kstep(NK - 2, 2, 0, false);
;   BIG_SYNC(0);      kstep(NK - 1, 3, 0, false);
	s_mov_b32 m0, s11
	s_mov_b64 s[12:13], 0x7e000
	v_mfma_f32_16x16x32_bf16 v[44:47], v[228:231], v[232:235], v[44:47]
	v_readfirstlane_b32 s11, v164
	v_lshl_add_u64 v[136:137], v[136:137], 0, s[12:13]
	s_waitcnt lgkmcnt(2)
	v_mfma_f32_16x16x32_bf16 v[120:123], v[216:219], v[236:239], v[120:123]
	ds_read_b128 v[232:235], v148 offset:20480
	v_mfma_f32_16x16x32_bf16 v[104:107], v[220:223], v[236:239], v[104:107]
	v_lshl_add_u64 v[134:135], v[134:135], 0, s[12:13]
	global_load_lds_dwordx4 v[198:199], off
	v_mfma_f32_16x16x32_bf16 v[76:79], v[224:227], v[236:239], v[76:79]
	s_mov_b32 m0, s11
	v_mfma_f32_16x16x32_bf16 v[40:43], v[228:231], v[236:239], v[40:43]
	v_readfirstlane_b32 s11, v165
	s_waitcnt lgkmcnt(2)
	v_mfma_f32_16x16x32_bf16 v[116:119], v[216:219], v[240:243], v[116:119]
	ds_read_b128 v[236:239], v148 offset:21504
	v_mfma_f32_16x16x32_bf16 v[100:103], v[220:223], v[240:243], v[100:103]
	global_load_lds_dwordx4 v[136:137], off
	v_mfma_f32_16x16x32_bf16 v[68:71], v[224:227], v[240:243], v[68:71]
	s_mov_b32 m0, s11
	v_mfma_f32_16x16x32_bf16 v[36:39], v[228:231], v[240:243], v[36:39]
	v_readfirstlane_b32 s11, v166
	s_waitcnt lgkmcnt(2)
	v_mfma_f32_16x16x32_bf16 v[112:115], v[216:219], v[244:247], v[112:115]
	ds_read_b128 v[240:243], v148 offset:22528
	v_mfma_f32_16x16x32_bf16 v[96:99], v[220:223], v[244:247], v[96:99]
	global_load_lds_dwordx4 v[200:201], off
	v_mfma_f32_16x16x32_bf16 v[64:67], v[224:227], v[244:247], v[64:67]
	s_mov_b32 m0, s11
	v_mfma_f32_16x16x32_bf16 v[32:35], v[228:231], v[244:247], v[32:35]
	global_load_lds_dwordx4 v[134:135], off
	s_waitcnt lgkmcnt(2)
	v_mfma_f32_16x16x32_bf16 v[92:95], v[216:219], v[232:235], v[92:95]
	ds_read_b128 v[244:247], v148 offset:23552
	v_mfma_f32_16x16x32_bf16 v[60:63], v[220:223], v[232:235], v[60:63]
	ds_read_b128 v[186:189], v147 offset:32768
	v_mfma_f32_16x16x32_bf16 v[28:31], v[224:227], v[232:235], v[28:31]
	ds_read_b128 v[190:193], v147 offset:33792
	v_mfma_f32_16x16x32_bf16 v[12:15], v[228:231], v[232:235], v[12:15]
	ds_read_b128 v[194:197], v147 offset:34816
	s_waitcnt lgkmcnt(5)
	v_mfma_f32_16x16x32_bf16 v[84:87], v[216:219], v[236:239], v[84:87]
	ds_read_b128 v[202:205], v147 offset:35840
	ds_read_b128 v[232:235], v148 offset:49152
	v_mfma_f32_16x16x32_bf16 v[56:59], v[220:223], v[236:239], v[56:59]
	v_mfma_f32_16x16x32_bf16 v[24:27], v[224:227], v[236:239], v[24:27]
	v_mfma_f32_16x16x32_bf16 v[8:11], v[228:231], v[236:239], v[8:11]
	s_waitcnt lgkmcnt(6)
	v_mfma_f32_16x16x32_bf16 v[80:83], v[216:219], v[240:243], v[80:83]
	ds_read_b128 v[236:239], v148 offset:50176
	v_mfma_f32_16x16x32_bf16 v[52:55], v[220:223], v[240:243], v[52:55]
	v_mfma_f32_16x16x32_bf16 v[20:23], v[224:227], v[240:243], v[20:23]
	v_mfma_f32_16x16x32_bf16 v[4:7], v[228:231], v[240:243], v[4:7]
	s_waitcnt lgkmcnt(6)
	v_mfma_f32_16x16x32_bf16 v[72:75], v[216:219], v[244:247], v[72:75]
	ds_read_b128 v[240:243], v148 offset:51200
	v_mfma_f32_16x16x32_bf16 v[48:51], v[220:223], v[244:247], v[48:51]
	v_mfma_f32_16x16x32_bf16 v[16:19], v[224:227], v[244:247], v[16:19]
	v_mfma_f32_16x16x32_bf16 v[0:3], v[228:231], v[244:247], v[0:3]
	ds_read_b128 v[244:247], v148 offset:52224
	s_waitcnt lgkmcnt(3)
	v_mfma_f32_16x16x32_bf16 v[124:127], v[186:189], v[232:235], v[124:127]
	v_mfma_f32_16x16x32_bf16 v[108:111], v[190:193], v[232:235], v[108:111]
	v_mfma_f32_16x16x32_bf16 v[88:91], v[194:197], v[232:235], v[88:91]
	v_mfma_f32_16x16x32_bf16 v[44:47], v[202:205], v[232:235], v[44:47]
	s_waitcnt vmcnt(4)
	s_barrier
	s_waitcnt lgkmcnt(2)
	v_mfma_f32_16x16x32_bf16 v[120:123], v[186:189], v[236:239], v[120:123]
	ds_read_b128 v[232:235], v148 offset:53248
	v_mfma_f32_16x16x32_bf16 v[104:107], v[190:193], v[236:239], v[104:107]
	v_mfma_f32_16x16x32_bf16 v[76:79], v[194:197], v[236:239], v[76:79]
	v_mfma_f32_16x16x32_bf16 v[40:43], v[202:205], v[236:239], v[40:43]
	s_waitcnt lgkmcnt(2)
	v_mfma_f32_16x16x32_bf16 v[116:119], v[186:189], v[240:243], v[116:119]
	ds_read_b128 v[236:239], v148 offset:54272
	v_mfma_f32_16x16x32_bf16 v[100:103], v[190:193], v[240:243], v[100:103]
	v_mfma_f32_16x16x32_bf16 v[68:71], v[194:197], v[240:243], v[68:71]
	v_mfma_f32_16x16x32_bf16 v[36:39], v[202:205], v[240:243], v[36:39]
	s_waitcnt lgkmcnt(2)
	v_mfma_f32_16x16x32_bf16 v[112:115], v[186:189], v[244:247], v[112:115]
	ds_read_b128 v[240:243], v148 offset:55296
	v_mfma_f32_16x16x32_bf16 v[96:99], v[190:193], v[244:247], v[96:99]
	v_mfma_f32_16x16x32_bf16 v[64:67], v[194:197], v[244:247], v[64:67]
	v_mfma_f32_16x16x32_bf16 v[32:35], v[202:205], v[244:247], v[32:35]
	s_waitcnt lgkmcnt(2)
	v_mfma_f32_16x16x32_bf16 v[92:95], v[186:189], v[232:235], v[92:95]
	ds_read_b128 v[244:247], v148 offset:56320
	v_mfma_f32_16x16x32_bf16 v[60:63], v[190:193], v[232:235], v[60:63]
	v_mfma_f32_16x16x32_bf16 v[28:31], v[194:197], v[232:235], v[28:31]
	v_mfma_f32_16x16x32_bf16 v[12:15], v[202:205], v[232:235], v[12:15]
	s_waitcnt lgkmcnt(2)
	v_mfma_f32_16x16x32_bf16 v[84:87], v[186:189], v[236:239], v[84:87]
	v_mfma_f32_16x16x32_bf16 v[56:59], v[190:193], v[236:239], v[56:59]
	v_mfma_f32_16x16x32_bf16 v[24:27], v[194:197], v[236:239], v[24:27]
	v_mfma_f32_16x16x32_bf16 v[8:11], v[202:205], v[236:239], v[8:11]
	s_waitcnt lgkmcnt(1)
	v_mfma_f32_16x16x32_bf16 v[80:83], v[186:189], v[240:243], v[80:83]
	v_mfma_f32_16x16x32_bf16 v[52:55], v[190:193], v[240:243], v[52:55]
	v_mfma_f32_16x16x32_bf16 v[20:23], v[194:197], v[240:243], v[20:23]
	v_mfma_f32_16x16x32_bf16 v[4:7], v[202:205], v[240:243], v[4:7]
	s_waitcnt lgkmcnt(0)
	v_mfma_f32_16x16x32_bf16 v[72:75], v[186:189], v[244:247], v[72:75]
	v_mfma_f32_16x16x32_bf16 v[48:51], v[190:193], v[244:247], v[48:51]
	v_mfma_f32_16x16x32_bf16 v[16:19], v[194:197], v[244:247], v[16:19]
	v_mfma_f32_16x16x32_bf16 v[0:3], v[202:205], v[244:247], v[0:3]
	v_mov_b32_e32 v186, 0xf149f2ca
	v_mov_b32_e32 v187, 0x3c0881c4
	v_mov_b32_e32 v188, 0xbab64f3b
	v_mov_b32_e32 v189, 0x24800
	v_mov_b32_e32 v190, 1
	v_mov_b32_e32 v191, 0x24804
	v_mov_b32_e32 v192, 0xfcf
	v_mov_b32_e32 v193, 0x7cf
	v_mov_b32_e32 v194, 0xfdf
	v_mov_b32_e32 v195, 0x7df
	v_mov_b32_e32 v196, 0xfef
	v_mov_b32_e32 v197, 0x7ef
	v_mov_b32_e32 v198, 0xfff
	v_mov_b32_e32 v199, 0x7ff
	v_mov_b32_e32 v200, 0x20000
	v_mov_b32_e32 v201, 0xf8f
	v_mov_b32_e32 v202, 0x78f
	v_mov_b32_e32 v203, 0xf9f
	v_mov_b32_e32 v204, 0x79f
	v_mov_b32_e32 v205, 0xfaf
	v_mov_b32_e32 v210, 0x7f800000
	v_not_b32_e32 v211, 63
	v_not_b32_e32 v212, 31
	v_mov_b32_e32 v213, 0x7fc00000
	s_waitcnt vmcnt(4)
	s_barrier
; template <int NK, bool BNT = false> ...
;     ...
;     for (int m = 0; m < 4; ++m) af[m] = *reinterpret_cast<const bf16x8*>(sa + aoff + m * 1024);
; #pragma unroll
;     for (int n = 0; n < 4; ++n) bfr[n] = *reinterpret_cast<const bf16x8*>(sa + boff + n * 1024);
;     __builtin_amdgcn_sched_barrier(0);
;     if (do_stage) stage(T + 3, nxt);
; #pragma unroll
;     for (int m = 0; m < 4; ++m)
; #pragma unroll
;       for (int n = 0; n < 4; ++n) acc[m][n] = __builtin_amdgcn_mfma_f32_16x16x32_bf16(af[m], bfr[n], acc[m][n], 0, 0, 0);
;     if (do_stage) {
; #pragma unroll
;       for (int q = 0; q < NG; ++q) {
;         __builtin_amdgcn_sched_group_barrier(0x008, 3, 0);
;         __builtin_amdgcn_sched_group_barrier(0x010, 1, 0);
;       }
;       __builtin_amdgcn_sched_group_barrier(0x008, 16 - 3 * NG, 0);
;     }
;     __builtin_amdgcn_sched_barrier(0);
; #pragma unroll
;     for (int n = 0; n < 4; ++n) bfr[n] = *reinterpret_cast<const bf16x8*>(sa + boff + (4 + n) * 1024);
; #pragma unroll
;     for (int m = 0; m < 4; ++m)
; #pragma unroll
;       for (int n = 0; n < 4; ++n)
;         acc[m][4 + n] = __builtin_amdgcn_mfma_f32_16x16x32_bf16(af[m], bfr[n], acc[m][4 + n], 0, 0, 0);
;     __builtin_amdgcn_sched_barrier(0);
; template <int MODE, int NSUB>
; __device__ __forceinline__ void epilogue(const Params& p, int layer, f32x4 (&acc)[4][NSUB], int tm, int tn, int g,
;                                          const float* s_rstd, const int tid_in) {
;     ...
;   } else if constexpr (MODE == EPI_UP) {
;     const int woff = widen_off(fq);
; #pragma unroll
;     for (int n = 0; n < NSUB; ++n) {
;       const int nl = wc * (NSUB * 16) + n * 16 + fr;
;       const int t = tn * (NSUB * 32) + nl;
;       const float rs = s_rstd[nl];
; #pragma unroll
;       for (int mp = 0; mp < 2; ++mp) {
;         bf16x4 pk[2];
; #pragma unroll
;         for (int h2 = 0; h2 < 2; ++h2) {
;           const int m = mp * 2 + h2;
;           float v[4];
; #pragma unroll
;           for (int j = 0; j < 4; ++j) {
;             float a = fmaxf(acc[m][n][j] * rs, 0.f);
;             v[j] = a * a;
;           }
;           pk[h2] = pack4(v[0], v[1], v[2], v[3]);
;         }
;         const int f = tm * 128 + wr * 64 + mp * 32 + woff;
;         __builtin_nontemporal_store(widen_pair(pk[0], pk[1]), reinterpret_cast<u32x4*>(p.hm + blk(t, f, 128)));
	ds_read_b128 v[134:137], v167
	ds_read_b128 v[138:141], v167 offset:1024
	ds_read_b128 v[154:157], v167 offset:2048
	ds_read_b128 v[158:161], v167 offset:3072
	ds_read_b128 v[162:165], v168
	ds_read_b128 v[166:169], v169
	ds_read_b128 v[216:219], v170
	ds_read_b128 v[220:223], v172
	s_waitcnt lgkmcnt(0)
	v_mfma_f32_16x16x32_bf16 v[124:127], v[134:137], v[162:165], v[124:127]
	v_mfma_f32_16x16x32_bf16 v[120:123], v[134:137], v[166:169], v[120:123]
	v_mfma_f32_16x16x32_bf16 v[116:119], v[134:137], v[216:219], v[116:119]
	v_mfma_f32_16x16x32_bf16 v[112:115], v[134:137], v[220:223], v[112:115]
	v_mfma_f32_16x16x32_bf16 v[224:227], v[138:141], v[162:165], v[108:111]
	v_mfma_f32_16x16x32_bf16 v[104:107], v[138:141], v[166:169], v[104:107]
	v_mfma_f32_16x16x32_bf16 v[100:103], v[138:141], v[216:219], v[100:103]
	v_mfma_f32_16x16x32_bf16 v[96:99], v[138:141], v[220:223], v[96:99]
	v_mfma_f32_16x16x32_bf16 v[228:231], v[154:157], v[162:165], v[88:91]
	v_mfma_f32_16x16x32_bf16 v[232:235], v[154:157], v[166:169], v[76:79]
	v_mfma_f32_16x16x32_bf16 v[68:71], v[154:157], v[216:219], v[68:71]
	v_mfma_f32_16x16x32_bf16 v[64:67], v[154:157], v[220:223], v[64:67]
	v_mfma_f32_16x16x32_bf16 v[44:47], v[158:161], v[162:165], v[44:47]
	v_mfma_f32_16x16x32_bf16 v[40:43], v[158:161], v[166:169], v[40:43]
	v_mfma_f32_16x16x32_bf16 v[36:39], v[158:161], v[216:219], v[36:39]
	v_mfma_f32_16x16x32_bf16 v[32:35], v[158:161], v[220:223], v[32:35]
	ds_read_b128 v[76:79], v173
	ds_read_b128 v[88:91], v174
	s_waitcnt lgkmcnt(0)
	v_mfma_f32_16x16x32_bf16 v[162:165], v[134:137], v[76:79], v[92:95]
	s_nop 2
	ds_read_b128 v[92:95], v178
	v_mfma_f32_16x16x32_bf16 v[166:169], v[134:137], v[88:91], v[84:87]
	s_nop 2
	ds_read_b128 v[84:87], v175
	s_waitcnt lgkmcnt(0)
	v_mfma_f32_16x16x32_bf16 v[172:175], v[134:137], v[84:87], v[80:83]
	v_mfma_f32_16x16x32_bf16 v[134:137], v[134:137], v[92:95], v[72:75]
	v_mfma_f32_16x16x32_bf16 v[216:219], v[138:141], v[76:79], v[60:63]
	v_mfma_f32_16x16x32_bf16 v[220:223], v[138:141], v[88:91], v[56:59]
	v_mfma_f32_16x16x32_bf16 v[52:55], v[138:141], v[84:87], v[52:55]
	v_mfma_f32_16x16x32_bf16 v[48:51], v[138:141], v[92:95], v[48:51]
	v_mfma_f32_16x16x32_bf16 v[138:141], v[154:157], v[76:79], v[28:31]
	v_mfma_f32_16x16x32_bf16 v[236:239], v[154:157], v[88:91], v[24:27]
	v_mfma_f32_16x16x32_bf16 v[20:23], v[154:157], v[84:87], v[20:23]
	v_mfma_f32_16x16x32_bf16 v[16:19], v[154:157], v[92:95], v[16:19]
	v_mfma_f32_16x16x32_bf16 v[154:157], v[158:161], v[76:79], v[12:15]
	v_mfma_f32_16x16x32_bf16 v[240:243], v[158:161], v[88:91], v[8:11]
	v_mfma_f32_16x16x32_bf16 v[244:247], v[158:161], v[84:87], v[4:7]
	v_mfma_f32_16x16x32_bf16 v[0:3], v[158:161], v[92:95], v[0:3]
	s_waitcnt vmcnt(0)
	s_barrier
	s_nop 0
	ds_read_b128 v[4:7], v176
	ds_read_b128 v[8:11], v176 offset:1024
	ds_read_b128 v[158:161], v176 offset:2048
	ds_read_b128 v[248:251], v176 offset:3072
	ds_read_b128 v[12:15], v179
	ds_read_b128 v[24:27], v180
	ds_read_b128 v[28:31], v181
	ds_read_b128 v[56:59], v182
	s_waitcnt lgkmcnt(0)
	v_mfma_f32_16x16x32_bf16 v[124:127], v[4:7], v[12:15], v[124:127]
	v_mfma_f32_16x16x32_bf16 v[108:111], v[4:7], v[24:27], v[120:123]
	v_mfma_f32_16x16x32_bf16 v[92:95], v[4:7], v[28:31], v[116:119]
	v_mfma_f32_16x16x32_bf16 v[76:79], v[4:7], v[56:59], v[112:115]
	v_mfma_f32_16x16x32_bf16 v[112:115], v[8:11], v[12:15], v[224:227]
	v_mfma_f32_16x16x32_bf16 v[104:107], v[8:11], v[24:27], v[104:107]
	v_mfma_f32_16x16x32_bf16 v[88:91], v[8:11], v[28:31], v[100:103]
	v_mfma_f32_16x16x32_bf16 v[72:75], v[8:11], v[56:59], v[96:99]
	v_mfma_f32_16x16x32_bf16 v[120:123], v[158:161], v[12:15], v[228:231]
	v_mfma_f32_16x16x32_bf16 v[100:103], v[158:161], v[24:27], v[232:235]
	v_mfma_f32_16x16x32_bf16 v[84:87], v[158:161], v[28:31], v[68:71]
	v_mfma_f32_16x16x32_bf16 v[68:71], v[158:161], v[56:59], v[64:67]
	v_mfma_f32_16x16x32_bf16 v[178:181], v[248:251], v[12:15], v[44:47]
	v_mfma_f32_16x16x32_bf16 v[96:99], v[248:251], v[24:27], v[40:43]
	v_mfma_f32_16x16x32_bf16 v[80:83], v[248:251], v[28:31], v[36:39]
	v_mfma_f32_16x16x32_bf16 v[64:67], v[248:251], v[56:59], v[32:35]
	s_nop 2
	ds_read_b128 v[32:35], v142
	ds_read_b128 v[116:119], v143
	s_waitcnt lgkmcnt(0)
	v_mfma_f32_16x16x32_bf16 v[60:63], v[4:7], v[32:35], v[162:165]
	s_nop 2
	ds_read_b128 v[162:165], v144
	ds_read_b128 v[142:145], v145
	v_mfma_f32_16x16x32_bf16 v[44:47], v[4:7], v[116:119], v[166:169]
	s_waitcnt lgkmcnt(0)
	v_mfma_f32_16x16x32_bf16 v[28:31], v[4:7], v[162:165], v[172:175]
	v_mfma_f32_16x16x32_bf16 v[12:15], v[4:7], v[142:145], v[134:137]
	v_mfma_f32_16x16x32_bf16 v[56:59], v[8:11], v[32:35], v[216:219]
	v_mfma_f32_16x16x32_bf16 v[40:43], v[8:11], v[116:119], v[220:223]
	v_mfma_f32_16x16x32_bf16 v[24:27], v[8:11], v[162:165], v[52:55]
	v_mfma_f32_16x16x32_bf16 v[8:11], v[8:11], v[142:145], v[48:51]
	v_mfma_f32_16x16x32_bf16 v[52:55], v[158:161], v[32:35], v[138:141]
	v_mfma_f32_16x16x32_bf16 v[36:39], v[158:161], v[116:119], v[236:239]
	v_mfma_f32_16x16x32_bf16 v[20:23], v[158:161], v[162:165], v[20:23]
	v_mfma_f32_16x16x32_bf16 v[4:7], v[158:161], v[142:145], v[16:19]
	v_mfma_f32_16x16x32_bf16 v[48:51], v[248:251], v[32:35], v[154:157]
	v_mfma_f32_16x16x32_bf16 v[32:35], v[248:251], v[116:119], v[240:243]
	v_mfma_f32_16x16x32_bf16 v[16:19], v[248:251], v[162:165], v[244:247]
	v_mfma_f32_16x16x32_bf16 v[0:3], v[248:251], v[142:145], v[0:3]
	v_mov_b32_e32 v116, v215
	s_lshl_b32 s10, s10, 8
	v_and_b32_e32 v117, 16, v116
	v_lshrrev_b32_e32 v118, 2, v116
	v_and_or_b32 v136, v118, 8, v117
	v_lshlrev_b32_e32 v117, 1, v116
	v_and_b32_e32 v119, 15, v116
	v_and_b32_e32 v117, 0x80, v117
	v_lshl_or_b32 v134, s15, 8, v117
	v_or_b32_e32 v117, v117, v119
	v_ashrrev_i32_e32 v116, 1, v116
	v_lshlrev_b32_e32 v118, 2, v117
	v_and_b32_e32 v116, 0xffffffc0, v116
	v_add3_u32 v135, s10, v150, v116
	v_or_b32_e32 v116, 0x20000, v118
	ds_read_b32 v137, v116
	v_lshlrev_b32_e32 v152, 6, v119
	v_or_b32_e32 v119, 0x20040, v118
	v_readlane_b32 s64, v252, 4
	ds_read_b32 v119, v119
	s_waitcnt lgkmcnt(0)
; __device__ __forceinline__ int widen_off(int fq) { return ((fq & 1) << 4) + ((fq >> 1) << 3); }
; template <int MODE, int NSUB>
; __device__ __forceinline__ void epilogue(const Params& p, int layer, f32x4 (&acc)[4][NSUB], int tm, int tn, int g,
;                                          const float* s_rstd, const int tid_in) {
;     ...
;   } else if constexpr (MODE == EPI_UP) {
;     const int woff = widen_off(fq);
; #pragma unroll
;     for (int n = 0; n < NSUB; ++n) {
;       const int nl = wc * (NSUB * 16) + n * 16 + fr;
;       const int t = tn * (NSUB * 32) + nl;
;       const float rs = s_rstd[nl];
; #pragma unroll
;       for (int mp = 0; mp < 2; ++mp) {
;         bf16x4 pk[2];
; #pragma unroll
;         for (int h2 = 0; h2 < 2; ++h2) {
;           const int m = mp * 2 + h2;
;           float v[4];
; #pragma unroll
;           for (int j = 0; j < 4; ++j) {
;             float a = fmaxf(acc[m][n][j] * rs, 0.f);
;             v[j] = a * a;
;           }
;           pk[h2] = pack4(v[0], v[1], v[2], v[3]);
;         }
;         const int f = tm * 128 + wr * 64 + mp * 32 + woff;
;         __builtin_nontemporal_store(widen_pair(pk[0], pk[1]), reinterpret_cast<u32x4*>(p.hm + blk(t, f, 128)));
;       }
;     }
	v_mul_f32_e32 v116, v124, v137
	v_mul_f32_e32 v117, v125, v137
	v_mul_f32_e32 v124, v126, v137
	v_mul_f32_e32 v125, v127, v137
	v_mul_f32_e32 v112, v112, v137
	v_mul_f32_e32 v113, v113, v137
	v_max_f32_e32 v124, 0, v124
	v_max_f32_e32 v125, 0, v125
	v_max_f32_e32 v112, 0, v112
	v_max_f32_e32 v113, 0, v113
	v_mul_f32_e32 v114, v114, v137
	v_mul_f32_e32 v115, v115, v137
	v_pk_mul_f32 v[126:127], v[124:125], v[124:125]
	v_pk_mul_f32 v[112:113], v[112:113], v[112:113]
	v_max_f32_e32 v114, 0, v114
	v_max_f32_e32 v115, 0, v115
	v_cvt_pk_bf16_f32 v125, v126, v127
	v_pk_mul_f32 v[114:115], v[114:115], v[114:115]
	v_cvt_pk_bf16_f32 v126, v112, v113
	v_ashrrev_i32_e32 v112, 5, v135
	v_cvt_pk_bf16_f32 v127, v114, v115
	v_add_u32_e32 v114, v112, v134
	v_ashrrev_i32_e32 v115, 31, v114
	v_lshlrev_b64 v[112:113], 13, v[114:115]
	v_mul_f32_e32 v115, v120, v137
	v_max_f32_e32 v120, 0, v115
	v_mul_f32_e32 v115, v121, v137
	v_max_f32_e32 v121, 0, v115
	v_mul_f32_e32 v115, v122, v137
	v_max_f32_e32 v116, 0, v116
	v_max_f32_e32 v117, 0, v117
	v_max_f32_e32 v122, 0, v115
	v_mul_f32_e32 v115, v123, v137
	v_pk_mul_f32 v[116:117], v[116:117], v[116:117]
	v_readlane_b32 s78, v252, 18
	v_readlane_b32 s79, v252, 19
	v_max_f32_e32 v123, 0, v115
	v_cvt_pk_bf16_f32 v124, v116, v117
	v_lshl_add_u64 v[116:117], s[78:79], 0, v[112:113]
	v_pk_mul_f32 v[120:121], v[120:121], v[120:121]
	v_pk_mul_f32 v[122:123], v[122:123], v[122:123]
	v_mul_f32_e32 v115, v178, v137
	v_lshl_add_u64 v[134:135], v[116:117], 0, v[152:153]
	v_lshlrev_b32_e32 v112, 1, v136
	v_mov_b32_e32 v113, v153
	v_cvt_pk_bf16_f32 v120, v120, v121
	v_cvt_pk_bf16_f32 v121, v122, v123
	v_max_f32_e32 v122, 0, v115
	v_mul_f32_e32 v115, v179, v137
	v_permlane16_swap_b32_e32 v124, v126
	v_permlane16_swap_b32_e32 v125, v127
	v_lshl_add_u64 v[134:135], v[134:135], 0, v[112:113]
	v_max_f32_e32 v123, 0, v115
	v_mul_f32_e32 v115, v180, v137
	global_store_dwordx4 v[134:135], v[124:127], off nt
	v_add_u32_e32 v114, 1, v114
	v_mul_f32_e32 v108, v108, v119
	v_max_f32_e32 v124, 0, v115
	v_mul_f32_e32 v115, v181, v137
	v_mul_f32_e32 v109, v109, v119
	v_mul_f32_e32 v110, v110, v119
	v_mul_f32_e32 v111, v111, v119
	v_mul_f32_e32 v104, v104, v119
	v_mul_f32_e32 v105, v105, v119
	v_max_f32_e32 v125, 0, v115
	v_ashrrev_i32_e32 v115, 31, v114
	v_max_f32_e32 v108, 0, v108
	v_max_f32_e32 v109, 0, v109
	v_max_f32_e32 v110, 0, v110
	v_max_f32_e32 v111, 0, v111
	v_max_f32_e32 v104, 0, v104
	v_max_f32_e32 v105, 0, v105
	v_mul_f32_e32 v100, v100, v119
	v_mul_f32_e32 v101, v101, v119
	v_mul_f32_e32 v102, v102, v119
	v_mul_f32_e32 v103, v103, v119
	v_mul_f32_e32 v96, v96, v119
	v_mul_f32_e32 v97, v97, v119
	v_mul_f32_e32 v98, v98, v119
	v_mul_f32_e32 v99, v99, v119
	v_lshlrev_b64 v[114:115], 13, v[114:115]
	v_pk_mul_f32 v[108:109], v[108:109], v[108:109]
	v_pk_mul_f32 v[110:111], v[110:111], v[110:111]
	v_pk_mul_f32 v[104:105], v[104:105], v[104:105]
	v_max_f32_e32 v100, 0, v100
	v_max_f32_e32 v101, 0, v101
	v_max_f32_e32 v102, 0, v102
	v_max_f32_e32 v103, 0, v103
	v_max_f32_e32 v96, 0, v96
	v_max_f32_e32 v97, 0, v97
	v_max_f32_e32 v98, 0, v98
	v_max_f32_e32 v99, 0, v99
	v_lshl_add_u64 v[114:115], s[78:79], 0, v[114:115]
	v_cvt_pk_bf16_f32 v108, v108, v109
	v_cvt_pk_bf16_f32 v109, v110, v111
	v_cvt_pk_bf16_f32 v110, v104, v105
	v_or_b32_e32 v104, 0x400, v152
	v_mov_b32_e32 v105, v153
	v_pk_mul_f32 v[100:101], v[100:101], v[100:101]
	v_pk_mul_f32 v[102:103], v[102:103], v[102:103]
	v_pk_mul_f32 v[96:97], v[96:97], v[96:97]
	v_pk_mul_f32 v[98:99], v[98:99], v[98:99]
	v_cvt_pk_bf16_f32 v100, v100, v101
	v_cvt_pk_bf16_f32 v101, v102, v103
	v_cvt_pk_bf16_f32 v102, v96, v97
	v_cvt_pk_bf16_f32 v103, v98, v99
	v_lshl_add_u64 v[96:97], v[114:115], 0, v[104:105]
	v_permlane16_swap_b32_e32 v100, v102
	v_permlane16_swap_b32_e32 v101, v103
	v_lshl_add_u64 v[96:97], v[96:97], 0, v[112:113]
	global_store_dwordx4 v[96:97], v[100:103], off nt
	v_or_b32_e32 v96, 0x20080, v118
	ds_read_b32 v96, v96
	v_mul_f32_e32 v106, v106, v119
	v_mul_f32_e32 v107, v107, v119
	v_pk_mul_f32 v[122:123], v[122:123], v[122:123]
	v_pk_mul_f32 v[124:125], v[124:125], v[124:125]
	s_waitcnt lgkmcnt(0)
	v_mul_f32_e32 v92, v92, v96
	v_mul_f32_e32 v93, v93, v96
	v_mul_f32_e32 v94, v94, v96
	v_mul_f32_e32 v95, v95, v96
	v_mul_f32_e32 v88, v88, v96
	v_mul_f32_e32 v89, v89, v96
	v_max_f32_e32 v92, 0, v92
	v_max_f32_e32 v93, 0, v93
	v_max_f32_e32 v94, 0, v94
	v_max_f32_e32 v95, 0, v95
	v_max_f32_e32 v88, 0, v88
	v_max_f32_e32 v89, 0, v89
	v_mul_f32_e32 v84, v84, v96
	v_mul_f32_e32 v85, v85, v96
	v_mul_f32_e32 v86, v86, v96
	v_mul_f32_e32 v87, v87, v96
	v_mul_f32_e32 v80, v80, v96
	v_mul_f32_e32 v81, v81, v96
	v_mul_f32_e32 v82, v82, v96
	v_mul_f32_e32 v83, v83, v96
	v_pk_mul_f32 v[92:93], v[92:93], v[92:93]
	v_pk_mul_f32 v[94:95], v[94:95], v[94:95]
	v_pk_mul_f32 v[88:89], v[88:89], v[88:89]
	v_max_f32_e32 v84, 0, v84
	v_max_f32_e32 v85, 0, v85
	v_max_f32_e32 v86, 0, v86
	v_max_f32_e32 v87, 0, v87
	v_max_f32_e32 v80, 0, v80
	v_max_f32_e32 v81, 0, v81
	v_max_f32_e32 v82, 0, v82
	v_max_f32_e32 v83, 0, v83
	v_cvt_pk_bf16_f32 v92, v92, v93
	v_cvt_pk_bf16_f32 v93, v94, v95
	v_cvt_pk_bf16_f32 v94, v88, v89
	v_or_b32_e32 v88, 0x800, v152
	v_mov_b32_e32 v89, v153
	v_pk_mul_f32 v[84:85], v[84:85], v[84:85]
	v_pk_mul_f32 v[86:87], v[86:87], v[86:87]
	v_pk_mul_f32 v[80:81], v[80:81], v[80:81]
	v_pk_mul_f32 v[82:83], v[82:83], v[82:83]
	v_cvt_pk_bf16_f32 v84, v84, v85
	v_cvt_pk_bf16_f32 v85, v86, v87
	v_cvt_pk_bf16_f32 v86, v80, v81
	v_cvt_pk_bf16_f32 v87, v82, v83
	v_lshl_add_u64 v[80:81], v[114:115], 0, v[88:89]
	v_permlane16_swap_b32_e32 v84, v86
	v_permlane16_swap_b32_e32 v85, v87
	v_lshl_add_u64 v[80:81], v[80:81], 0, v[112:113]
	global_store_dwordx4 v[80:81], v[84:87], off nt
	v_or_b32_e32 v80, 0x200c0, v118
	ds_read_b32 v80, v80
	v_mul_f32_e32 v90, v90, v96
	v_mul_f32_e32 v91, v91, v96
	v_max_f32_e32 v106, 0, v106
	v_max_f32_e32 v107, 0, v107
	s_waitcnt lgkmcnt(0)
; template <int MODE, int NSUB>
; __device__ __forceinline__ void epilogue(const Params& p, int layer, f32x4 (&acc)[4][NSUB], int tm, int tn, int g,
;                                          const float* s_rstd, const int tid_in) {
;     ...
; #pragma unroll
;       for (int mp = 0; mp < 2; ++mp) {
;         bf16x4 pk[2];
; #pragma unroll
;         for (int h2 = 0; h2 < 2; ++h2) {
;           const int m = mp * 2 + h2;
;           float v[4];
; #pragma unroll
;           for (int j = 0; j < 4; ++j) {
;             float a = fmaxf(acc[m][n][j] * rs, 0.f);
;             v[j] = a * a;
;           }
;           pk[h2] = pack4(v[0], v[1], v[2], v[3]);
;         }
;         const int f = tm * 128 + wr * 64 + mp * 32 + woff;
;         __builtin_nontemporal_store(widen_pair(pk[0], pk[1]), reinterpret_cast<u32x4*>(p.hm + blk(t, f, 128)));
;       }
	v_mul_f32_e32 v76, v76, v80
	v_mul_f32_e32 v77, v77, v80
	v_mul_f32_e32 v78, v78, v80
	v_mul_f32_e32 v79, v79, v80
	v_mul_f32_e32 v72, v72, v80
	v_mul_f32_e32 v73, v73, v80
	v_max_f32_e32 v76, 0, v76
	v_max_f32_e32 v77, 0, v77
	v_max_f32_e32 v78, 0, v78
	v_max_f32_e32 v79, 0, v79
	v_max_f32_e32 v72, 0, v72
	v_max_f32_e32 v73, 0, v73
	v_mul_f32_e32 v68, v68, v80
	v_mul_f32_e32 v69, v69, v80
	v_mul_f32_e32 v70, v70, v80
	v_mul_f32_e32 v71, v71, v80
	v_mul_f32_e32 v64, v64, v80
	v_mul_f32_e32 v65, v65, v80
	v_mul_f32_e32 v66, v66, v80
	v_mul_f32_e32 v67, v67, v80
	v_pk_mul_f32 v[76:77], v[76:77], v[76:77]
	v_pk_mul_f32 v[78:79], v[78:79], v[78:79]
	v_pk_mul_f32 v[72:73], v[72:73], v[72:73]
	v_max_f32_e32 v68, 0, v68
	v_max_f32_e32 v69, 0, v69
	v_max_f32_e32 v70, 0, v70
	v_max_f32_e32 v71, 0, v71
	v_max_f32_e32 v64, 0, v64
	v_max_f32_e32 v65, 0, v65
	v_max_f32_e32 v66, 0, v66
	v_max_f32_e32 v67, 0, v67
	v_cvt_pk_bf16_f32 v76, v76, v77
	v_cvt_pk_bf16_f32 v77, v78, v79
	v_cvt_pk_bf16_f32 v78, v72, v73
	v_or_b32_e32 v72, 0xc00, v152
	v_mov_b32_e32 v73, v153
	v_pk_mul_f32 v[68:69], v[68:69], v[68:69]
	v_pk_mul_f32 v[70:71], v[70:71], v[70:71]
	v_pk_mul_f32 v[64:65], v[64:65], v[64:65]
	v_pk_mul_f32 v[66:67], v[66:67], v[66:67]
	v_cvt_pk_bf16_f32 v68, v68, v69
	v_cvt_pk_bf16_f32 v69, v70, v71
	v_cvt_pk_bf16_f32 v70, v64, v65
	v_cvt_pk_bf16_f32 v71, v66, v67
	v_lshl_add_u64 v[64:65], v[114:115], 0, v[72:73]
	v_permlane16_swap_b32_e32 v68, v70
	v_permlane16_swap_b32_e32 v69, v71
	v_lshl_add_u64 v[64:65], v[64:65], 0, v[112:113]
	global_store_dwordx4 v[64:65], v[68:71], off nt
	v_or_b32_e32 v64, 0x20100, v118
	ds_read_b32 v64, v64
	v_mul_f32_e32 v74, v74, v80
	v_mul_f32_e32 v75, v75, v80
	v_max_f32_e32 v90, 0, v90
	v_max_f32_e32 v91, 0, v91
	s_waitcnt lgkmcnt(0)
	v_mul_f32_e32 v60, v60, v64
	v_mul_f32_e32 v61, v61, v64
	v_mul_f32_e32 v62, v62, v64
	v_mul_f32_e32 v63, v63, v64
	v_mul_f32_e32 v56, v56, v64
	v_mul_f32_e32 v57, v57, v64
	v_max_f32_e32 v60, 0, v60
	v_max_f32_e32 v61, 0, v61
	v_max_f32_e32 v62, 0, v62
	v_max_f32_e32 v63, 0, v63
	v_max_f32_e32 v56, 0, v56
	v_max_f32_e32 v57, 0, v57
	v_mul_f32_e32 v52, v52, v64
	v_mul_f32_e32 v53, v53, v64
	v_mul_f32_e32 v54, v54, v64
	v_mul_f32_e32 v55, v55, v64
	v_mul_f32_e32 v48, v48, v64
	v_mul_f32_e32 v49, v49, v64
	v_mul_f32_e32 v50, v50, v64
	v_mul_f32_e32 v51, v51, v64
	v_pk_mul_f32 v[60:61], v[60:61], v[60:61]
	v_pk_mul_f32 v[62:63], v[62:63], v[62:63]
	v_pk_mul_f32 v[56:57], v[56:57], v[56:57]
	v_max_f32_e32 v52, 0, v52
	v_max_f32_e32 v53, 0, v53
	v_max_f32_e32 v54, 0, v54
	v_max_f32_e32 v55, 0, v55
	v_max_f32_e32 v48, 0, v48
	v_max_f32_e32 v49, 0, v49
	v_max_f32_e32 v50, 0, v50
	v_max_f32_e32 v51, 0, v51
	v_cvt_pk_bf16_f32 v60, v60, v61
	v_cvt_pk_bf16_f32 v61, v62, v63
	v_cvt_pk_bf16_f32 v62, v56, v57
	v_or_b32_e32 v56, 0x1000, v152
	v_mov_b32_e32 v57, v153
	v_pk_mul_f32 v[52:53], v[52:53], v[52:53]
	v_pk_mul_f32 v[54:55], v[54:55], v[54:55]
	v_pk_mul_f32 v[48:49], v[48:49], v[48:49]
	v_pk_mul_f32 v[50:51], v[50:51], v[50:51]
	v_cvt_pk_bf16_f32 v52, v52, v53
	v_cvt_pk_bf16_f32 v53, v54, v55
	v_cvt_pk_bf16_f32 v54, v48, v49
	v_cvt_pk_bf16_f32 v55, v50, v51
	v_lshl_add_u64 v[48:49], v[114:115], 0, v[56:57]
	v_permlane16_swap_b32_e32 v52, v54
	v_permlane16_swap_b32_e32 v53, v55
	v_lshl_add_u64 v[48:49], v[48:49], 0, v[112:113]
	global_store_dwordx4 v[48:49], v[52:55], off nt
	v_or_b32_e32 v48, 0x20140, v118
	ds_read_b32 v48, v48
	v_mul_f32_e32 v58, v58, v64
	v_mul_f32_e32 v59, v59, v64
	v_max_f32_e32 v74, 0, v74
	v_max_f32_e32 v75, 0, v75
	s_waitcnt lgkmcnt(0)
	v_mul_f32_e32 v44, v44, v48
	v_mul_f32_e32 v45, v45, v48
	v_mul_f32_e32 v46, v46, v48
	v_mul_f32_e32 v47, v47, v48
	v_mul_f32_e32 v40, v40, v48
	v_mul_f32_e32 v41, v41, v48
	v_max_f32_e32 v44, 0, v44
	v_max_f32_e32 v45, 0, v45
	v_max_f32_e32 v46, 0, v46
	v_max_f32_e32 v47, 0, v47
	v_max_f32_e32 v40, 0, v40
	v_max_f32_e32 v41, 0, v41
	v_mul_f32_e32 v36, v36, v48
	v_mul_f32_e32 v37, v37, v48
	v_mul_f32_e32 v38, v38, v48
	v_mul_f32_e32 v39, v39, v48
	v_mul_f32_e32 v32, v32, v48
	v_mul_f32_e32 v33, v33, v48
	v_mul_f32_e32 v34, v34, v48
	v_mul_f32_e32 v35, v35, v48
	v_pk_mul_f32 v[44:45], v[44:45], v[44:45]
	v_pk_mul_f32 v[46:47], v[46:47], v[46:47]
	v_pk_mul_f32 v[40:41], v[40:41], v[40:41]
	v_max_f32_e32 v36, 0, v36
	v_max_f32_e32 v37, 0, v37
	v_max_f32_e32 v38, 0, v38
	v_max_f32_e32 v39, 0, v39
	v_max_f32_e32 v32, 0, v32
	v_max_f32_e32 v33, 0, v33
	v_max_f32_e32 v34, 0, v34
	v_max_f32_e32 v35, 0, v35
	v_cvt_pk_bf16_f32 v44, v44, v45
	v_cvt_pk_bf16_f32 v45, v46, v47
	v_cvt_pk_bf16_f32 v46, v40, v41
	v_or_b32_e32 v40, 0x1400, v152
	v_mov_b32_e32 v41, v153
	v_pk_mul_f32 v[36:37], v[36:37], v[36:37]
	v_pk_mul_f32 v[38:39], v[38:39], v[38:39]
	v_pk_mul_f32 v[32:33], v[32:33], v[32:33]
	v_pk_mul_f32 v[34:35], v[34:35], v[34:35]
	v_cvt_pk_bf16_f32 v36, v36, v37
	v_cvt_pk_bf16_f32 v37, v38, v39
	v_cvt_pk_bf16_f32 v38, v32, v33
	v_cvt_pk_bf16_f32 v39, v34, v35
	v_lshl_add_u64 v[32:33], v[114:115], 0, v[40:41]
	v_permlane16_swap_b32_e32 v36, v38
	v_permlane16_swap_b32_e32 v37, v39
	v_lshl_add_u64 v[32:33], v[32:33], 0, v[112:113]
	global_store_dwordx4 v[32:33], v[36:39], off nt
	v_or_b32_e32 v32, 0x20180, v118
	ds_read_b32 v32, v32
	v_mul_f32_e32 v42, v42, v48
	v_mul_f32_e32 v43, v43, v48
	v_max_f32_e32 v58, 0, v58
	v_max_f32_e32 v59, 0, v59
	s_waitcnt lgkmcnt(0)
; template <int MODE, int NSUB>
; __device__ __forceinline__ void epilogue(const Params& p, int layer, f32x4 (&acc)[4][NSUB], int tm, int tn, int g,
;                                          const float* s_rstd, const int tid_in) {
;     ...
; #pragma unroll
;       for (int mp = 0; mp < 2; ++mp) {
;         bf16x4 pk[2];
; #pragma unroll
;         for (int h2 = 0; h2 < 2; ++h2) {
;           const int m = mp * 2 + h2;
;           float v[4];
; #pragma unroll
;           for (int j = 0; j < 4; ++j) {
;             float a = fmaxf(acc[m][n][j] * rs, 0.f);
;             v[j] = a * a;
;           }
;           pk[h2] = pack4(v[0], v[1], v[2], v[3]);
;         }
;         const int f = tm * 128 + wr * 64 + mp * 32 + woff;
;         __builtin_nontemporal_store(widen_pair(pk[0], pk[1]), reinterpret_cast<u32x4*>(p.hm + blk(t, f, 128)));
;       }
;     }
; __global__ void __launch_bounds__(NTHREADS) fwd_megakernel(Params p) {
;     ...
;           for (int id = rvid; id < 16 * CHUNK_TT; id += Greal) {
;             int ftb, ttl;
;             tile_decode_fb(id, 16, 4, ftb, ttl);
;             compute_rstd(p.part, 16, 1.0f / 1024.f, (chunk * CHUNK_TT + ttl) * 256, 256, s_rstd_b, tid_full);
;             f32x4 acc[4][8];
;             gemm_big<32>(acc, W + (long)ftb * 256 * 1024, 128 * 1024, p.xb + (long)(chunk * CHUNK_TT + ttl) * 256 * 1024, 128 * 1024, smem_all, tid_full);
;             const int ft = ftb * 2 + (widf >> 2);
;             epilogue<EPI_UP, 8>(p, l, acc, ft, ttl, 0, s_rstd_b, tid_e);
;             __syncthreads();
;           }
	v_mul_f32_e32 v28, v28, v32
	v_mul_f32_e32 v29, v29, v32
	v_mul_f32_e32 v30, v30, v32
	v_mul_f32_e32 v31, v31, v32
	v_mul_f32_e32 v24, v24, v32
	v_mul_f32_e32 v25, v25, v32
	v_max_f32_e32 v28, 0, v28
	v_max_f32_e32 v29, 0, v29
	v_max_f32_e32 v30, 0, v30
	v_max_f32_e32 v31, 0, v31
	v_max_f32_e32 v24, 0, v24
	v_max_f32_e32 v25, 0, v25
	v_mul_f32_e32 v20, v20, v32
	v_mul_f32_e32 v21, v21, v32
	v_mul_f32_e32 v22, v22, v32
	v_mul_f32_e32 v23, v23, v32
	v_mul_f32_e32 v16, v16, v32
	v_mul_f32_e32 v17, v17, v32
	v_mul_f32_e32 v18, v18, v32
	v_mul_f32_e32 v19, v19, v32
	v_pk_mul_f32 v[28:29], v[28:29], v[28:29]
	v_pk_mul_f32 v[30:31], v[30:31], v[30:31]
	v_pk_mul_f32 v[24:25], v[24:25], v[24:25]
	v_max_f32_e32 v20, 0, v20
	v_max_f32_e32 v21, 0, v21
	v_max_f32_e32 v22, 0, v22
	v_max_f32_e32 v23, 0, v23
	v_max_f32_e32 v16, 0, v16
	v_max_f32_e32 v17, 0, v17
	v_max_f32_e32 v18, 0, v18
	v_max_f32_e32 v19, 0, v19
	v_cvt_pk_bf16_f32 v28, v28, v29
	v_cvt_pk_bf16_f32 v29, v30, v31
	v_cvt_pk_bf16_f32 v30, v24, v25
	v_or_b32_e32 v24, 0x1800, v152
	v_mov_b32_e32 v25, v153
	v_pk_mul_f32 v[20:21], v[20:21], v[20:21]
	v_pk_mul_f32 v[22:23], v[22:23], v[22:23]
	v_pk_mul_f32 v[16:17], v[16:17], v[16:17]
	v_pk_mul_f32 v[18:19], v[18:19], v[18:19]
	v_cvt_pk_bf16_f32 v20, v20, v21
	v_cvt_pk_bf16_f32 v21, v22, v23
	v_cvt_pk_bf16_f32 v22, v16, v17
	v_cvt_pk_bf16_f32 v23, v18, v19
	v_lshl_add_u64 v[16:17], v[114:115], 0, v[24:25]
	v_permlane16_swap_b32_e32 v20, v22
	v_permlane16_swap_b32_e32 v21, v23
	v_lshl_add_u64 v[16:17], v[16:17], 0, v[112:113]
	global_store_dwordx4 v[16:17], v[20:23], off nt
	v_or_b32_e32 v16, 0x201c0, v118
	ds_read_b32 v16, v16
	v_mul_f32_e32 v26, v26, v32
	v_mul_f32_e32 v27, v27, v32
	v_max_f32_e32 v42, 0, v42
	v_max_f32_e32 v43, 0, v43
	s_waitcnt lgkmcnt(0)
	v_mul_f32_e32 v12, v12, v16
	v_mul_f32_e32 v13, v13, v16
	v_mul_f32_e32 v14, v14, v16
	v_mul_f32_e32 v15, v15, v16
	v_mul_f32_e32 v8, v8, v16
	v_mul_f32_e32 v9, v9, v16
	v_mul_f32_e32 v10, v10, v16
	v_mul_f32_e32 v11, v11, v16
	v_mul_f32_e32 v4, v4, v16
	v_mul_f32_e32 v5, v5, v16
	v_mul_f32_e32 v6, v6, v16
	v_mul_f32_e32 v7, v7, v16
	v_mul_f32_e32 v0, v0, v16
	v_mul_f32_e32 v1, v1, v16
	v_mul_f32_e32 v2, v2, v16
	v_mul_f32_e32 v3, v3, v16
	v_max_f32_e32 v26, 0, v26
	v_max_f32_e32 v27, 0, v27
	v_max_f32_e32 v12, 0, v12
	v_max_f32_e32 v13, 0, v13
	v_max_f32_e32 v14, 0, v14
	v_max_f32_e32 v15, 0, v15
	v_max_f32_e32 v8, 0, v8
	v_max_f32_e32 v9, 0, v9
	v_max_f32_e32 v10, 0, v10
	v_max_f32_e32 v11, 0, v11
	v_max_f32_e32 v4, 0, v4
	v_max_f32_e32 v5, 0, v5
	v_max_f32_e32 v6, 0, v6
	v_max_f32_e32 v7, 0, v7
	v_max_f32_e32 v0, 0, v0
	v_max_f32_e32 v1, 0, v1
	v_max_f32_e32 v2, 0, v2
	v_max_f32_e32 v3, 0, v3
	v_cvt_pk_bf16_f32 v122, v122, v123
	v_cvt_pk_bf16_f32 v123, v124, v125
	v_lshl_add_u64 v[124:125], v[114:115], 0, v[152:153]
	v_pk_mul_f32 v[106:107], v[106:107], v[106:107]
	v_pk_mul_f32 v[90:91], v[90:91], v[90:91]
	v_pk_mul_f32 v[74:75], v[74:75], v[74:75]
	v_pk_mul_f32 v[58:59], v[58:59], v[58:59]
	v_pk_mul_f32 v[42:43], v[42:43], v[42:43]
	v_pk_mul_f32 v[26:27], v[26:27], v[26:27]
	v_pk_mul_f32 v[12:13], v[12:13], v[12:13]
	v_pk_mul_f32 v[14:15], v[14:15], v[14:15]
	v_pk_mul_f32 v[8:9], v[8:9], v[8:9]
	v_pk_mul_f32 v[10:11], v[10:11], v[10:11]
	v_or_b32_e32 v152, 0x1c00, v152
	v_pk_mul_f32 v[4:5], v[4:5], v[4:5]
	v_pk_mul_f32 v[6:7], v[6:7], v[6:7]
	v_pk_mul_f32 v[0:1], v[0:1], v[0:1]
	v_pk_mul_f32 v[2:3], v[2:3], v[2:3]
	v_cvt_pk_bf16_f32 v111, v106, v107
	v_lshl_add_u64 v[106:107], v[116:117], 0, v[104:105]
	v_cvt_pk_bf16_f32 v95, v90, v91
	v_lshl_add_u64 v[90:91], v[116:117], 0, v[88:89]
	v_cvt_pk_bf16_f32 v79, v74, v75
	v_lshl_add_u64 v[74:75], v[116:117], 0, v[72:73]
	v_cvt_pk_bf16_f32 v63, v58, v59
	v_lshl_add_u64 v[58:59], v[116:117], 0, v[56:57]
	v_cvt_pk_bf16_f32 v47, v42, v43
	v_lshl_add_u64 v[42:43], v[116:117], 0, v[40:41]
	v_cvt_pk_bf16_f32 v31, v26, v27
	v_lshl_add_u64 v[26:27], v[116:117], 0, v[24:25]
	v_cvt_pk_bf16_f32 v12, v12, v13
	v_cvt_pk_bf16_f32 v13, v14, v15
	v_cvt_pk_bf16_f32 v14, v8, v9
	v_cvt_pk_bf16_f32 v15, v10, v11
	v_lshl_add_u64 v[8:9], v[116:117], 0, v[152:153]
	v_cvt_pk_bf16_f32 v4, v4, v5
	v_cvt_pk_bf16_f32 v5, v6, v7
	v_cvt_pk_bf16_f32 v6, v0, v1
	v_cvt_pk_bf16_f32 v7, v2, v3
	v_lshl_add_u64 v[0:1], v[114:115], 0, v[152:153]
	s_add_i32 s9, s9, s26
	v_permlane16_swap_b32_e32 v120, v122
	v_permlane16_swap_b32_e32 v121, v123
	v_lshl_add_u64 v[124:125], v[124:125], 0, v[112:113]
	v_permlane16_swap_b32_e32 v108, v110
	v_permlane16_swap_b32_e32 v109, v111
	v_lshl_add_u64 v[106:107], v[106:107], 0, v[112:113]
	v_permlane16_swap_b32_e32 v92, v94
	v_permlane16_swap_b32_e32 v93, v95
	v_lshl_add_u64 v[90:91], v[90:91], 0, v[112:113]
	v_permlane16_swap_b32_e32 v76, v78
	v_permlane16_swap_b32_e32 v77, v79
	v_lshl_add_u64 v[74:75], v[74:75], 0, v[112:113]
	v_permlane16_swap_b32_e32 v60, v62
	v_permlane16_swap_b32_e32 v61, v63
	v_lshl_add_u64 v[58:59], v[58:59], 0, v[112:113]
	v_permlane16_swap_b32_e32 v44, v46
	v_permlane16_swap_b32_e32 v45, v47
	v_lshl_add_u64 v[42:43], v[42:43], 0, v[112:113]
	v_permlane16_swap_b32_e32 v28, v30
	v_permlane16_swap_b32_e32 v29, v31
	v_lshl_add_u64 v[26:27], v[26:27], 0, v[112:113]
	v_permlane16_swap_b32_e32 v12, v14
	v_permlane16_swap_b32_e32 v13, v15
	v_lshl_add_u64 v[8:9], v[8:9], 0, v[112:113]
	v_permlane16_swap_b32_e32 v4, v6
	v_permlane16_swap_b32_e32 v5, v7
	v_lshl_add_u64 v[0:1], v[0:1], 0, v[112:113]
	s_cmpk_gt_i32 s9, 0x13ff
	v_readlane_b32 s65, v252, 5
	v_readlane_b32 s66, v252, 6
	v_readlane_b32 s67, v252, 7
	v_readlane_b32 s68, v252, 8
	v_readlane_b32 s69, v252, 9
	v_readlane_b32 s70, v252, 10
	v_readlane_b32 s71, v252, 11
	v_readlane_b32 s72, v252, 12
	v_readlane_b32 s73, v252, 13
	v_readlane_b32 s74, v252, 14
	v_readlane_b32 s75, v252, 15
	v_readlane_b32 s76, v252, 16
	v_readlane_b32 s77, v252, 17
	global_store_dwordx4 v[124:125], v[120:123], off nt
	global_store_dwordx4 v[106:107], v[108:111], off nt
	global_store_dwordx4 v[90:91], v[92:95], off nt
	global_store_dwordx4 v[74:75], v[76:79], off nt
	global_store_dwordx4 v[58:59], v[60:63], off nt
	global_store_dwordx4 v[42:43], v[44:47], off nt
	global_store_dwordx4 v[26:27], v[28:31], off nt
	global_store_dwordx4 v[8:9], v[12:15], off nt
	global_store_dwordx4 v[0:1], v[4:7], off nt
	s_barrier
	s_cbranch_scc0 .LBB0_287

; template <int NK, bool BNT = false> ...
;     ...
;   auto stage = [&](int kt, int bufc) {
;     unsigned char* sa = smem + bufc * BIG_STAGE;
;     const unsigned char* Ab = Abase + (long)kt * 8192 + soff;
;     const unsigned char* Bb = Bbase + (long)kt * 8192 + soff;
;     glds16(Ab, sa + sb0);
;     glds16(Ab + astride * 2, sa + 8192 + sb0);
;     if constexpr (BNT) {
;       glds16_nt(Bb, sa + 16384 + sb0);
;       glds16_nt(Bb + bstride * 2, sa + 24576 + sb0);
;     } else {
;       glds16(Bb, sa + 16384 + sb0);
;       glds16(Bb + bstride * 2, sa + 24576 + sb0);
;     }
;   };
;   const int rd = fr * 64 + ((fq ^ (((fr >> 3) & 1) << 1)) * 16);
;   const int aoff = wr * 64 * 64 + rd;
;   const int boff = 16384 + wc * 128 * 64 + rd;
;   auto kstep = [&](int T, int cur, int nxt, bool do_stage) {
;     const unsigned char* sa = smem + cur * BIG_STAGE;
;     bf16x8 af[4], bfr[4];
; #pragma unroll
;     for (int m = 0; m < 4; ++m) af[m] = *reinterpret_cast<const bf16x8*>(sa + aoff + m * 1024);
; #pragma unroll
;     for (int n = 0; n < 4; ++n) bfr[n] = *reinterpret_cast<const bf16x8*>(sa + boff + n * 1024);
;     __builtin_amdgcn_sched_barrier(0);
;     if (do_stage) stage(T + 3, nxt);
; #pragma unroll
;     for (int m = 0; m < 4; ++m)
; #pragma unroll
;       for (int n = 0; n < 4; ++n) acc[m][n] = __builtin_amdgcn_mfma_f32_16x16x32_bf16(af[m], bfr[n], acc[m][n], 0, 0, 0);
;     if (do_stage) {
; #pragma unroll
;       for (int q = 0; q < NG; ++q) {
;         __builtin_amdgcn_sched_group_barrier(0x008, 3, 0);
;         __builtin_amdgcn_sched_group_barrier(0x010, 1, 0);
;       }
;       __builtin_amdgcn_sched_group_barrier(0x008, 16 - 3 * NG, 0);
;     }
;     __builtin_amdgcn_sched_barrier(0);
; #pragma unroll
;     for (int n = 0; n < 4; ++n) bfr[n] = *reinterpret_cast<const bf16x8*>(sa + boff + (4 + n) * 1024);
; #pragma unroll
;     for (int m = 0; m < 4; ++m)
; #pragma unroll
;       for (int n = 0; n < 4; ++n)
;         acc[m][4 + n] = __builtin_amdgcn_mfma_f32_16x16x32_bf16(af[m], bfr[n], acc[m][4 + n], 0, 0, 0);
;     __builtin_amdgcn_sched_barrier(0);
.LBB0_302:
	s_waitcnt lgkmcnt(3)
	v_mfma_f32_16x16x32_bf16 v[56:59], v[216:219], v[232:235], v[56:59]
	v_add_u32_e32 v163, 0x18000, v147
	v_lshl_add_u64 v[144:145], v[138:139], 0, s[6:7]
	v_mfma_f32_16x16x32_bf16 v[100:103], v[220:223], v[232:235], v[100:103]
	v_lshl_add_u64 v[164:165], v[144:145], 0, s[60:61]
	s_add_i32 m0, s100, 0x18000
	v_mfma_f32_16x16x32_bf16 v[104:107], v[224:227], v[232:235], v[104:107]
	s_waitcnt vmcnt(4)
	s_barrier
	v_lshl_add_u64 v[142:143], v[140:141], 0, s[6:7]
	v_lshl_add_u64 v[168:169], v[144:145], 0, s[80:81]
	v_mfma_f32_16x16x32_bf16 v[112:115], v[228:231], v[232:235], v[112:115]
	v_lshl_add_u64 v[166:167], v[142:143], 0, s[60:61]
	global_load_lds_dwordx4 v[164:165], off
	s_waitcnt lgkmcnt(2)
	v_mfma_f32_16x16x32_bf16 v[64:67], v[216:219], v[236:239], v[64:67]
	ds_read_b128 v[232:235], v149 offset:20480
	v_mfma_f32_16x16x32_bf16 v[80:83], v[220:223], v[236:239], v[80:83]
	v_add_u32_e32 v164, 0x1a000, v147
	v_add_u32_e32 v165, 0x1c000, v147
	v_mfma_f32_16x16x32_bf16 v[96:99], v[224:227], v[236:239], v[96:99]
	s_add_i32 m0, s100, 0x1a000
	v_mfma_f32_16x16x32_bf16 v[116:119], v[228:231], v[236:239], v[116:119]
	global_load_lds_dwordx4 v[168:169], off
	s_waitcnt lgkmcnt(2)
	v_mfma_f32_16x16x32_bf16 v[52:55], v[216:219], v[240:243], v[52:55]
	ds_read_b128 v[236:239], v149 offset:21504
	v_mfma_f32_16x16x32_bf16 v[68:71], v[220:223], v[240:243], v[68:71]
	s_add_i32 m0, s100, 0x1c000
	v_mfma_f32_16x16x32_bf16 v[108:111], v[224:227], v[240:243], v[108:111]
	v_lshl_add_u64 v[168:169], v[142:143], 0, s[80:81]
	v_mfma_f32_16x16x32_bf16 v[120:123], v[228:231], v[240:243], v[120:123]
	global_load_lds_dwordx4 v[166:167], off
	s_waitcnt lgkmcnt(2)
	v_mfma_f32_16x16x32_bf16 v[48:51], v[216:219], v[244:247], v[48:51]
	ds_read_b128 v[240:243], v149 offset:22528
	v_mfma_f32_16x16x32_bf16 v[72:75], v[220:223], v[244:247], v[72:75]
	v_add_u32_e32 v166, 0x1e000, v147
	v_mfma_f32_16x16x32_bf16 v[88:91], v[224:227], v[244:247], v[88:91]
	s_add_i32 m0, s100, 0x1e000
	v_mfma_f32_16x16x32_bf16 v[124:127], v[228:231], v[244:247], v[124:127]
	global_load_lds_dwordx4 v[168:169], off
	s_waitcnt lgkmcnt(2)
	v_mfma_f32_16x16x32_bf16 v[0:3], v[216:219], v[232:235], v[0:3]
	ds_read_b128 v[244:247], v149 offset:23552
	v_mfma_f32_16x16x32_bf16 v[16:19], v[220:223], v[232:235], v[16:19]
	ds_read_b128 v[186:189], v148 offset:32768
	v_mfma_f32_16x16x32_bf16 v[32:35], v[224:227], v[232:235], v[32:35]
	ds_read_b128 v[190:193], v148 offset:33792
	v_mfma_f32_16x16x32_bf16 v[60:63], v[228:231], v[232:235], v[60:63]
	ds_read_b128 v[194:197], v148 offset:34816
	s_waitcnt lgkmcnt(5)
	v_mfma_f32_16x16x32_bf16 v[4:7], v[216:219], v[236:239], v[4:7]
	ds_read_b128 v[202:205], v148 offset:35840
	ds_read_b128 v[232:235], v149 offset:49152
	v_mfma_f32_16x16x32_bf16 v[20:23], v[220:223], v[236:239], v[20:23]
	v_mfma_f32_16x16x32_bf16 v[36:39], v[224:227], v[236:239], v[36:39]
	v_mfma_f32_16x16x32_bf16 v[76:79], v[228:231], v[236:239], v[76:79]
	s_waitcnt lgkmcnt(6)
	v_mfma_f32_16x16x32_bf16 v[8:11], v[216:219], v[240:243], v[8:11]
	ds_read_b128 v[236:239], v149 offset:50176
	v_mfma_f32_16x16x32_bf16 v[24:27], v[220:223], v[240:243], v[24:27]
	v_mfma_f32_16x16x32_bf16 v[40:43], v[224:227], v[240:243], v[40:43]
	v_mfma_f32_16x16x32_bf16 v[84:87], v[228:231], v[240:243], v[84:87]
	s_waitcnt lgkmcnt(6)
	v_mfma_f32_16x16x32_bf16 v[12:15], v[216:219], v[244:247], v[12:15]
	ds_read_b128 v[240:243], v149 offset:51200
	v_mfma_f32_16x16x32_bf16 v[28:31], v[220:223], v[244:247], v[28:31]
	v_mfma_f32_16x16x32_bf16 v[44:47], v[224:227], v[244:247], v[44:47]
	v_mfma_f32_16x16x32_bf16 v[92:95], v[228:231], v[244:247], v[92:95]
	ds_read_b128 v[244:247], v149 offset:52224
	s_waitcnt lgkmcnt(3)
	v_mfma_f32_16x16x32_bf16 v[56:59], v[186:189], v[232:235], v[56:59]
	v_lshl_add_u64 v[168:169], v[144:145], 0, s[62:63]
	v_mfma_f32_16x16x32_bf16 v[100:103], v[190:193], v[232:235], v[100:103]
	s_mov_b32 m0, s100
	v_mfma_f32_16x16x32_bf16 v[104:107], v[194:197], v[232:235], v[104:107]
	s_waitcnt vmcnt(4)
	s_barrier
	v_lshl_add_u64 v[182:183], v[142:143], 0, s[62:63]
	v_mfma_f32_16x16x32_bf16 v[112:115], v[202:205], v[232:235], v[112:115]
	global_load_lds_dwordx4 v[168:169], off
	s_waitcnt lgkmcnt(2)
	v_mfma_f32_16x16x32_bf16 v[64:67], v[186:189], v[236:239], v[64:67]
	ds_read_b128 v[232:235], v149 offset:53248
	v_mfma_f32_16x16x32_bf16 v[80:83], v[190:193], v[236:239], v[80:83]
	v_lshl_add_u64 v[168:169], v[144:145], 0, s[0:1]
	v_mfma_f32_16x16x32_bf16 v[96:99], v[194:197], v[236:239], v[96:99]
	s_add_i32 m0, s100, 0x2000
	v_mfma_f32_16x16x32_bf16 v[116:119], v[202:205], v[236:239], v[116:119]
	global_load_lds_dwordx4 v[168:169], off
	s_waitcnt lgkmcnt(2)
	v_mfma_f32_16x16x32_bf16 v[52:55], v[186:189], v[240:243], v[52:55]
	ds_read_b128 v[236:239], v149 offset:54272
	v_mfma_f32_16x16x32_bf16 v[68:71], v[190:193], v[240:243], v[68:71]
	s_add_i32 m0, s100, 0x4000
	v_mfma_f32_16x16x32_bf16 v[108:111], v[194:197], v[240:243], v[108:111]
	v_lshl_add_u64 v[168:169], v[142:143], 0, s[0:1]
	v_mfma_f32_16x16x32_bf16 v[120:123], v[202:205], v[240:243], v[120:123]
	global_load_lds_dwordx4 v[182:183], off
	s_waitcnt lgkmcnt(2)
	v_mfma_f32_16x16x32_bf16 v[48:51], v[186:189], v[244:247], v[48:51]
	ds_read_b128 v[240:243], v149 offset:55296
	v_mfma_f32_16x16x32_bf16 v[72:75], v[190:193], v[244:247], v[72:75]
	s_add_i32 m0, s100, 0x6000
	v_mfma_f32_16x16x32_bf16 v[88:91], v[194:197], v[244:247], v[88:91]
	global_load_lds_dwordx4 v[168:169], off
	v_mfma_f32_16x16x32_bf16 v[124:127], v[202:205], v[244:247], v[124:127]
	s_waitcnt lgkmcnt(2)
; template <int NK, bool BNT = false> ...
;     ...
;   auto kstep = [&](int T, int cur, int nxt, bool do_stage) {
;     const unsigned char* sa = smem + cur * BIG_STAGE;
;     bf16x8 af[4], bfr[4];
; #pragma unroll
;     for (int m = 0; m < 4; ++m) af[m] = *reinterpret_cast<const bf16x8*>(sa + aoff + m * 1024);
; #pragma unroll
;     for (int n = 0; n < 4; ++n) bfr[n] = *reinterpret_cast<const bf16x8*>(sa + boff + n * 1024);
;     __builtin_amdgcn_sched_barrier(0);
;     if (do_stage) stage(T + 3, nxt);
; #pragma unroll
;     for (int m = 0; m < 4; ++m)
; #pragma unroll
;       for (int n = 0; n < 4; ++n) acc[m][n] = __builtin_amdgcn_mfma_f32_16x16x32_bf16(af[m], bfr[n], acc[m][n], 0, 0, 0);
;     if (do_stage) {
; #pragma unroll
;       for (int q = 0; q < NG; ++q) {
;         __builtin_amdgcn_sched_group_barrier(0x008, 3, 0);
;         __builtin_amdgcn_sched_group_barrier(0x010, 1, 0);
;       }
;       __builtin_amdgcn_sched_group_barrier(0x008, 16 - 3 * NG, 0);
;     }
;     __builtin_amdgcn_sched_barrier(0);
; #pragma unroll
;     for (int n = 0; n < 4; ++n) bfr[n] = *reinterpret_cast<const bf16x8*>(sa + boff + (4 + n) * 1024);
; #pragma unroll
;     for (int m = 0; m < 4; ++m)
; #pragma unroll
;       for (int n = 0; n < 4; ++n)
;         acc[m][4 + n] = __builtin_amdgcn_mfma_f32_16x16x32_bf16(af[m], bfr[n], acc[m][4 + n], 0, 0, 0);
;     __builtin_amdgcn_sched_barrier(0);
	v_mfma_f32_16x16x32_bf16 v[0:3], v[186:189], v[232:235], v[0:3]
	ds_read_b128 v[244:247], v149 offset:56320
	v_mfma_f32_16x16x32_bf16 v[16:19], v[190:193], v[232:235], v[16:19]
	ds_read_b128 v[216:219], v210
	v_mfma_f32_16x16x32_bf16 v[32:35], v[194:197], v[232:235], v[32:35]
	ds_read_b128 v[220:223], v210 offset:1024
	v_mfma_f32_16x16x32_bf16 v[60:63], v[202:205], v[232:235], v[60:63]
	ds_read_b128 v[224:227], v210 offset:2048
	s_waitcnt lgkmcnt(5)
	v_mfma_f32_16x16x32_bf16 v[4:7], v[186:189], v[236:239], v[4:7]
	ds_read_b128 v[228:231], v210 offset:3072
	ds_read_b128 v[232:235], v211
	v_mfma_f32_16x16x32_bf16 v[20:23], v[190:193], v[236:239], v[20:23]
	v_mfma_f32_16x16x32_bf16 v[36:39], v[194:197], v[236:239], v[36:39]
	v_mfma_f32_16x16x32_bf16 v[76:79], v[202:205], v[236:239], v[76:79]
	s_waitcnt lgkmcnt(6)
	v_mfma_f32_16x16x32_bf16 v[8:11], v[186:189], v[240:243], v[8:11]
	ds_read_b128 v[236:239], v211 offset:1024
	v_mfma_f32_16x16x32_bf16 v[24:27], v[190:193], v[240:243], v[24:27]
	v_mfma_f32_16x16x32_bf16 v[40:43], v[194:197], v[240:243], v[40:43]
	v_mfma_f32_16x16x32_bf16 v[84:87], v[202:205], v[240:243], v[84:87]
	s_waitcnt lgkmcnt(6)
	v_mfma_f32_16x16x32_bf16 v[12:15], v[186:189], v[244:247], v[12:15]
	ds_read_b128 v[240:243], v211 offset:2048
	v_mfma_f32_16x16x32_bf16 v[28:31], v[190:193], v[244:247], v[28:31]
	v_mfma_f32_16x16x32_bf16 v[44:47], v[194:197], v[244:247], v[44:47]
	v_mfma_f32_16x16x32_bf16 v[92:95], v[202:205], v[244:247], v[92:95]
	ds_read_b128 v[244:247], v211 offset:3072
	s_waitcnt lgkmcnt(3)
	v_mfma_f32_16x16x32_bf16 v[56:59], v[216:219], v[232:235], v[56:59]
	v_lshl_add_u64 v[174:175], v[144:145], 0, s[2:3]
	v_mfma_f32_16x16x32_bf16 v[100:103], v[220:223], v[232:235], v[100:103]
	s_add_i32 m0, s100, 0x8000
	v_mfma_f32_16x16x32_bf16 v[104:107], v[224:227], v[232:235], v[104:107]
	s_waitcnt vmcnt(4)
	s_barrier
	v_lshl_add_u64 v[178:179], v[142:143], 0, s[2:3]
	v_mfma_f32_16x16x32_bf16 v[112:115], v[228:231], v[232:235], v[112:115]
	global_load_lds_dwordx4 v[174:175], off
	s_waitcnt lgkmcnt(2)
	v_mfma_f32_16x16x32_bf16 v[64:67], v[216:219], v[236:239], v[64:67]
	ds_read_b128 v[232:235], v211 offset:4096
	v_mfma_f32_16x16x32_bf16 v[80:83], v[220:223], v[236:239], v[80:83]
	v_lshl_add_u64 v[174:175], v[144:145], 0, s[52:53]
	v_mfma_f32_16x16x32_bf16 v[96:99], v[224:227], v[236:239], v[96:99]
	s_add_i32 m0, s100, 0xa000
	v_mfma_f32_16x16x32_bf16 v[116:119], v[228:231], v[236:239], v[116:119]
	global_load_lds_dwordx4 v[174:175], off
	s_waitcnt lgkmcnt(2)
	v_mfma_f32_16x16x32_bf16 v[52:55], v[216:219], v[240:243], v[52:55]
	ds_read_b128 v[236:239], v211 offset:5120
	v_mfma_f32_16x16x32_bf16 v[68:71], v[220:223], v[240:243], v[68:71]
	s_add_i32 m0, s100, 0xc000
	v_mfma_f32_16x16x32_bf16 v[108:111], v[224:227], v[240:243], v[108:111]
	v_lshl_add_u64 v[174:175], v[142:143], 0, s[52:53]
	v_mfma_f32_16x16x32_bf16 v[120:123], v[228:231], v[240:243], v[120:123]
	global_load_lds_dwordx4 v[178:179], off
	s_waitcnt lgkmcnt(2)
	v_mfma_f32_16x16x32_bf16 v[48:51], v[216:219], v[244:247], v[48:51]
	ds_read_b128 v[240:243], v211 offset:6144
	v_mfma_f32_16x16x32_bf16 v[72:75], v[220:223], v[244:247], v[72:75]
	s_add_i32 m0, s100, 0xe000
	v_mfma_f32_16x16x32_bf16 v[88:91], v[224:227], v[244:247], v[88:91]
	global_load_lds_dwordx4 v[174:175], off
	v_mfma_f32_16x16x32_bf16 v[124:127], v[228:231], v[244:247], v[124:127]
	s_waitcnt lgkmcnt(2)
	v_mfma_f32_16x16x32_bf16 v[0:3], v[216:219], v[232:235], v[0:3]
	ds_read_b128 v[244:247], v211 offset:7168
	v_mfma_f32_16x16x32_bf16 v[16:19], v[220:223], v[232:235], v[16:19]
	ds_read_b128 v[186:189], v210 offset:32768
	v_mfma_f32_16x16x32_bf16 v[32:35], v[224:227], v[232:235], v[32:35]
	ds_read_b128 v[190:193], v210 offset:33792
	v_mfma_f32_16x16x32_bf16 v[60:63], v[228:231], v[232:235], v[60:63]
	ds_read_b128 v[194:197], v210 offset:34816
	s_waitcnt lgkmcnt(5)
	v_mfma_f32_16x16x32_bf16 v[4:7], v[216:219], v[236:239], v[4:7]
	ds_read_b128 v[202:205], v210 offset:35840
	ds_read_b128 v[232:235], v211 offset:32768
	v_mfma_f32_16x16x32_bf16 v[20:23], v[220:223], v[236:239], v[20:23]
	v_mfma_f32_16x16x32_bf16 v[36:39], v[224:227], v[236:239], v[36:39]
	v_mfma_f32_16x16x32_bf16 v[76:79], v[228:231], v[236:239], v[76:79]
	s_waitcnt lgkmcnt(6)
	v_mfma_f32_16x16x32_bf16 v[8:11], v[216:219], v[240:243], v[8:11]
	ds_read_b128 v[236:239], v211 offset:33792
	v_mfma_f32_16x16x32_bf16 v[24:27], v[220:223], v[240:243], v[24:27]
	v_mfma_f32_16x16x32_bf16 v[40:43], v[224:227], v[240:243], v[40:43]
	v_mfma_f32_16x16x32_bf16 v[84:87], v[228:231], v[240:243], v[84:87]
	s_waitcnt lgkmcnt(6)
	v_mfma_f32_16x16x32_bf16 v[12:15], v[216:219], v[244:247], v[12:15]
	ds_read_b128 v[240:243], v211 offset:34816
	v_mfma_f32_16x16x32_bf16 v[28:31], v[220:223], v[244:247], v[28:31]
	v_mfma_f32_16x16x32_bf16 v[44:47], v[224:227], v[244:247], v[44:47]
	v_mfma_f32_16x16x32_bf16 v[92:95], v[228:231], v[244:247], v[92:95]
	ds_read_b128 v[244:247], v211 offset:35840
	s_waitcnt lgkmcnt(3)
	v_mfma_f32_16x16x32_bf16 v[56:59], v[186:189], v[232:235], v[56:59]
	v_lshl_add_u64 v[248:249], v[144:145], 0, s[54:55]
	v_mfma_f32_16x16x32_bf16 v[100:103], v[190:193], v[232:235], v[100:103]
	s_add_i32 m0, s100, 0x10000
	v_mfma_f32_16x16x32_bf16 v[104:107], v[194:197], v[232:235], v[104:107]
	s_waitcnt vmcnt(4)
	s_barrier
; #define BIG_SYNC(N)                                              \
;   asm volatile("s_waitcnt vmcnt(%0)" ::"n"(N) : "memory");       \
;   __builtin_amdgcn_s_barrier();                                  \
;   asm volatile("" ::: "memory");                                 \
;   __builtin_amdgcn_sched_barrier(0);
; template <int NK, bool BNT = false> ...
;     ...
;   for (int it = 0; it < NK / 4 - 1; ++it) {
;     const int t = it * 4;
;     BIG_SYNC(2 * NG); kstep(t, 0, 3, true);
;     BIG_SYNC(2 * NG); kstep(t + 1, 1, 0, true);
;     BIG_SYNC(2 * NG); kstep(t + 2, 2, 1, true);
;     BIG_SYNC(2 * NG); kstep(t + 3, 3, 2, true);
;   }
;   BIG_SYNC(2 * NG); kstep(NK - 4, 0, 3, true);
;   BIG_SYNC(2 * NG); kstep(NK - 3, 1, 0, false);
;   BIG_SYNC(NG);     kstep(NK - 2, 2, 0, false);
;   BIG_SYNC(0);      kstep(NK - 1, 3, 0, false);
	v_lshl_add_u64 v[144:145], v[144:145], 0, s[56:57]
	v_mfma_f32_16x16x32_bf16 v[112:115], v[202:205], v[232:235], v[112:115]
	v_lshl_add_u64 v[250:251], v[142:143], 0, s[54:55]
	s_waitcnt lgkmcnt(2)
	v_mfma_f32_16x16x32_bf16 v[64:67], v[186:189], v[236:239], v[64:67]
	ds_read_b128 v[232:235], v211 offset:36864
	v_mfma_f32_16x16x32_bf16 v[80:83], v[190:193], v[236:239], v[80:83]
	v_lshl_add_u64 v[142:143], v[142:143], 0, s[56:57]
	v_mfma_f32_16x16x32_bf16 v[96:99], v[194:197], v[236:239], v[96:99]
	global_load_lds_dwordx4 v[248:249], off
	v_mfma_f32_16x16x32_bf16 v[116:119], v[202:205], v[236:239], v[116:119]
	s_add_i32 m0, s100, 0x12000
	s_waitcnt lgkmcnt(2)
	v_mfma_f32_16x16x32_bf16 v[52:55], v[186:189], v[240:243], v[52:55]
	ds_read_b128 v[236:239], v211 offset:37888
	v_mfma_f32_16x16x32_bf16 v[68:71], v[190:193], v[240:243], v[68:71]
	global_load_lds_dwordx4 v[144:145], off
	v_mfma_f32_16x16x32_bf16 v[108:111], v[194:197], v[240:243], v[108:111]
	s_add_i32 m0, s100, 0x14000
	v_mfma_f32_16x16x32_bf16 v[120:123], v[202:205], v[240:243], v[120:123]
	global_load_lds_dwordx4 v[250:251], off
	s_waitcnt lgkmcnt(2)
	v_mfma_f32_16x16x32_bf16 v[48:51], v[186:189], v[244:247], v[48:51]
	ds_read_b128 v[240:243], v211 offset:38912
	v_mfma_f32_16x16x32_bf16 v[72:75], v[190:193], v[244:247], v[72:75]
	s_add_i32 m0, s100, 0x16000
	v_mfma_f32_16x16x32_bf16 v[88:91], v[194:197], v[244:247], v[88:91]
	global_load_lds_dwordx4 v[142:143], off
	v_mfma_f32_16x16x32_bf16 v[124:127], v[202:205], v[244:247], v[124:127]
	s_waitcnt lgkmcnt(2)
	v_mfma_f32_16x16x32_bf16 v[0:3], v[186:189], v[232:235], v[0:3]
	ds_read_b128 v[244:247], v211 offset:39936
	v_mfma_f32_16x16x32_bf16 v[16:19], v[190:193], v[232:235], v[16:19]
	ds_read_b128 v[216:219], v148
	v_mfma_f32_16x16x32_bf16 v[32:35], v[194:197], v[232:235], v[32:35]
	ds_read_b128 v[220:223], v148 offset:1024
	v_mfma_f32_16x16x32_bf16 v[60:63], v[202:205], v[232:235], v[60:63]
	ds_read_b128 v[224:227], v148 offset:2048
	s_waitcnt lgkmcnt(5)
	v_mfma_f32_16x16x32_bf16 v[4:7], v[186:189], v[236:239], v[4:7]
	ds_read_b128 v[228:231], v148 offset:3072
	ds_read_b128 v[232:235], v149 offset:16384
	v_mfma_f32_16x16x32_bf16 v[20:23], v[190:193], v[236:239], v[20:23]
	v_mfma_f32_16x16x32_bf16 v[36:39], v[194:197], v[236:239], v[36:39]
	v_mfma_f32_16x16x32_bf16 v[76:79], v[202:205], v[236:239], v[76:79]
	s_waitcnt lgkmcnt(6)
	v_mfma_f32_16x16x32_bf16 v[8:11], v[186:189], v[240:243], v[8:11]
	ds_read_b128 v[236:239], v149 offset:17408
	v_mfma_f32_16x16x32_bf16 v[24:27], v[190:193], v[240:243], v[24:27]
	v_mfma_f32_16x16x32_bf16 v[40:43], v[194:197], v[240:243], v[40:43]
	v_mfma_f32_16x16x32_bf16 v[84:87], v[202:205], v[240:243], v[84:87]
	s_waitcnt lgkmcnt(6)
	v_mfma_f32_16x16x32_bf16 v[12:15], v[186:189], v[244:247], v[12:15]
	ds_read_b128 v[240:243], v149 offset:18432
	v_mfma_f32_16x16x32_bf16 v[28:31], v[190:193], v[244:247], v[28:31]
	v_mfma_f32_16x16x32_bf16 v[44:47], v[194:197], v[244:247], v[44:47]
	v_mfma_f32_16x16x32_bf16 v[92:95], v[202:205], v[244:247], v[92:95]
	ds_read_b128 v[244:247], v149 offset:19456
	s_add_u32 s6, s6, 0x8000
	s_addc_u32 s7, s7, 0
	s_cmp_lg_u32 s6, 0x38000
	s_cbranch_scc1 .LBB0_302
	v_add_u32_e32 v167, 0x10000, v148
	v_or_b32_e32 v168, 0x10000, v150
	v_add_u32_e32 v169, 0x10400, v150
	v_add_u32_e32 v170, 0x10800, v150
	v_add_u32_e32 v172, 0x10c00, v150
	v_add_u32_e32 v173, 0x11000, v150
	v_add_u32_e32 v174, 0x11400, v150
	v_add_u32_e32 v175, 0x11800, v150
	v_add_u32_e32 v178, 0x11c00, v150
	v_add_u32_e32 v176, 0x18000, v148
	v_or_b32_e32 v179, 0x18000, v150
	v_add_u32_e32 v180, 0x18400, v150
	v_add_u32_e32 v181, 0x18800, v150
	v_add_u32_e32 v182, 0x18c00, v150
	v_add_u32_e32 v142, 0x19000, v150
	v_add_u32_e32 v143, 0x19400, v150
	v_add_u32_e32 v144, 0x19800, v150
	v_add_u32_e32 v145, 0x19c00, v150
	s_waitcnt lgkmcnt(3)
	v_mfma_f32_16x16x32_bf16 v[56:59], v[216:219], v[232:235], v[56:59]
	s_sext_i32_i8 s4, s4
	s_mov_b64 s[6:7], 0x3e000
	v_mfma_f32_16x16x32_bf16 v[100:103], v[220:223], v[232:235], v[100:103]
	v_readfirstlane_b32 s5, v163
	v_lshl_add_u64 v[198:199], v[136:137], 0, s[6:7]
	v_mfma_f32_16x16x32_bf16 v[104:107], v[224:227], v[232:235], v[104:107]
	s_waitcnt vmcnt(4)
	s_barrier
	v_lshl_add_u64 v[200:201], v[134:135], 0, s[6:7]
	s_mov_b32 m0, s5
	v_mfma_f32_16x16x32_bf16 v[112:115], v[228:231], v[232:235], v[112:115]
	s_mov_b64 s[6:7], 0x7e000
	v_readfirstlane_b32 s5, v164
	s_waitcnt lgkmcnt(2)
	v_mfma_f32_16x16x32_bf16 v[64:67], v[216:219], v[236:239], v[64:67]
	ds_read_b128 v[232:235], v149 offset:20480
	v_mfma_f32_16x16x32_bf16 v[80:83], v[220:223], v[236:239], v[80:83]
	v_lshl_add_u64 v[136:137], v[136:137], 0, s[6:7]
	v_lshl_add_u64 v[134:135], v[134:135], 0, s[6:7]
	v_mfma_f32_16x16x32_bf16 v[96:99], v[224:227], v[236:239], v[96:99]
	global_load_lds_dwordx4 v[198:199], off
	s_mov_b32 m0, s5
	v_mfma_f32_16x16x32_bf16 v[116:119], v[228:231], v[236:239], v[116:119]
	v_readfirstlane_b32 s5, v165
	s_waitcnt lgkmcnt(2)
	v_mfma_f32_16x16x32_bf16 v[52:55], v[216:219], v[240:243], v[52:55]
	ds_read_b128 v[236:239], v149 offset:21504
	v_mfma_f32_16x16x32_bf16 v[68:71], v[220:223], v[240:243], v[68:71]
	global_load_lds_dwordx4 v[136:137], off
	v_mfma_f32_16x16x32_bf16 v[108:111], v[224:227], v[240:243], v[108:111]
	s_mov_b32 m0, s5
	v_mfma_f32_16x16x32_bf16 v[120:123], v[228:231], v[240:243], v[120:123]
	v_readfirstlane_b32 s5, v166
	s_waitcnt lgkmcnt(2)
	v_mfma_f32_16x16x32_bf16 v[48:51], v[216:219], v[244:247], v[48:51]
	ds_read_b128 v[240:243], v149 offset:22528
	v_mfma_f32_16x16x32_bf16 v[72:75], v[220:223], v[244:247], v[72:75]
	global_load_lds_dwordx4 v[200:201], off
	v_mfma_f32_16x16x32_bf16 v[88:91], v[224:227], v[244:247], v[88:91]
	s_mov_b32 m0, s5
	v_mfma_f32_16x16x32_bf16 v[124:127], v[228:231], v[244:247], v[124:127]
	global_load_lds_dwordx4 v[134:135], off
	s_waitcnt lgkmcnt(2)
; #define BIG_SYNC(N)                                              \
;   asm volatile("s_waitcnt vmcnt(%0)" ::"n"(N) : "memory");       \
;   __builtin_amdgcn_s_barrier();                                  \
;   asm volatile("" ::: "memory");                                 \
;   __builtin_amdgcn_sched_barrier(0);
; template <int NK, bool BNT = false> ...
;     ...
;   auto kstep = [&](int T, int cur, int nxt, bool do_stage) {
;     const unsigned char* sa = smem + cur * BIG_STAGE;
;     bf16x8 af[4], bfr[4];
; #pragma unroll
;     for (int m = 0; m < 4; ++m) af[m] = *reinterpret_cast<const bf16x8*>(sa + aoff + m * 1024);
; #pragma unroll
;     for (int n = 0; n < 4; ++n) bfr[n] = *reinterpret_cast<const bf16x8*>(sa + boff + n * 1024);
;     __builtin_amdgcn_sched_barrier(0);
;     if (do_stage) stage(T + 3, nxt);
; #pragma unroll
;     for (int m = 0; m < 4; ++m)
; #pragma unroll
;       for (int n = 0; n < 4; ++n) acc[m][n] = __builtin_amdgcn_mfma_f32_16x16x32_bf16(af[m], bfr[n], acc[m][n], 0, 0, 0);
;     if (do_stage) {
; #pragma unroll
;       for (int q = 0; q < NG; ++q) {
;         __builtin_amdgcn_sched_group_barrier(0x008, 3, 0);
;         __builtin_amdgcn_sched_group_barrier(0x010, 1, 0);
;       }
;       __builtin_amdgcn_sched_group_barrier(0x008, 16 - 3 * NG, 0);
;     }
;     __builtin_amdgcn_sched_barrier(0);
; #pragma unroll
;     for (int n = 0; n < 4; ++n) bfr[n] = *reinterpret_cast<const bf16x8*>(sa + boff + (4 + n) * 1024);
; #pragma unroll
;     for (int m = 0; m < 4; ++m)
; #pragma unroll
;       for (int n = 0; n < 4; ++n)
;         acc[m][4 + n] = __builtin_amdgcn_mfma_f32_16x16x32_bf16(af[m], bfr[n], acc[m][4 + n], 0, 0, 0);
;     __builtin_amdgcn_sched_barrier(0);
;   };
;     ...
;   stage(0, 0);
;   stage(1, 1);
;   stage(2, 2);
;   for (int it = 0; it < NK / 4 - 1; ++it) {
;     const int t = it * 4;
;     BIG_SYNC(2 * NG); kstep(t, 0, 3, true);
;     BIG_SYNC(2 * NG); kstep(t + 1, 1, 0, true);
;     BIG_SYNC(2 * NG); kstep(t + 2, 2, 1, true);
;     BIG_SYNC(2 * NG); kstep(t + 3, 3, 2, true);
;   }
;   BIG_SYNC(2 * NG); kstep(NK - 4, 0, 3, true);
;   BIG_SYNC(2 * NG); kstep(NK - 3, 1, 0, false);
;   BIG_SYNC(NG);     kstep(NK - 2, 2, 0, false);
;   BIG_SYNC(0);      kstep(NK - 1, 3, 0, false);
	v_mfma_f32_16x16x32_bf16 v[0:3], v[216:219], v[232:235], v[0:3]
	ds_read_b128 v[244:247], v149 offset:23552
	v_mfma_f32_16x16x32_bf16 v[16:19], v[220:223], v[232:235], v[16:19]
	ds_read_b128 v[186:189], v148 offset:32768
	v_mfma_f32_16x16x32_bf16 v[32:35], v[224:227], v[232:235], v[32:35]
	ds_read_b128 v[190:193], v148 offset:33792
	v_mfma_f32_16x16x32_bf16 v[60:63], v[228:231], v[232:235], v[60:63]
	ds_read_b128 v[194:197], v148 offset:34816
	s_waitcnt lgkmcnt(5)
	v_mfma_f32_16x16x32_bf16 v[4:7], v[216:219], v[236:239], v[4:7]
	ds_read_b128 v[202:205], v148 offset:35840
	ds_read_b128 v[232:235], v149 offset:49152
	v_mfma_f32_16x16x32_bf16 v[20:23], v[220:223], v[236:239], v[20:23]
	v_mfma_f32_16x16x32_bf16 v[36:39], v[224:227], v[236:239], v[36:39]
	v_mfma_f32_16x16x32_bf16 v[76:79], v[228:231], v[236:239], v[76:79]
	s_waitcnt lgkmcnt(6)
	v_mfma_f32_16x16x32_bf16 v[8:11], v[216:219], v[240:243], v[8:11]
	ds_read_b128 v[236:239], v149 offset:50176
	v_mfma_f32_16x16x32_bf16 v[24:27], v[220:223], v[240:243], v[24:27]
	v_mfma_f32_16x16x32_bf16 v[40:43], v[224:227], v[240:243], v[40:43]
	v_mfma_f32_16x16x32_bf16 v[84:87], v[228:231], v[240:243], v[84:87]
	s_waitcnt lgkmcnt(6)
	v_mfma_f32_16x16x32_bf16 v[12:15], v[216:219], v[244:247], v[12:15]
	ds_read_b128 v[240:243], v149 offset:51200
	v_mfma_f32_16x16x32_bf16 v[28:31], v[220:223], v[244:247], v[28:31]
	v_mfma_f32_16x16x32_bf16 v[44:47], v[224:227], v[244:247], v[44:47]
	v_mfma_f32_16x16x32_bf16 v[92:95], v[228:231], v[244:247], v[92:95]
	ds_read_b128 v[244:247], v149 offset:52224
	s_waitcnt lgkmcnt(3)
	v_mfma_f32_16x16x32_bf16 v[56:59], v[186:189], v[232:235], v[56:59]
	v_mfma_f32_16x16x32_bf16 v[100:103], v[190:193], v[232:235], v[100:103]
	v_mfma_f32_16x16x32_bf16 v[104:107], v[194:197], v[232:235], v[104:107]
	v_mfma_f32_16x16x32_bf16 v[112:115], v[202:205], v[232:235], v[112:115]
	s_waitcnt vmcnt(4)
	s_barrier
	s_waitcnt lgkmcnt(2)
	v_mfma_f32_16x16x32_bf16 v[64:67], v[186:189], v[236:239], v[64:67]
	ds_read_b128 v[232:235], v149 offset:53248
	v_mfma_f32_16x16x32_bf16 v[80:83], v[190:193], v[236:239], v[80:83]
	v_mfma_f32_16x16x32_bf16 v[96:99], v[194:197], v[236:239], v[96:99]
	v_mfma_f32_16x16x32_bf16 v[116:119], v[202:205], v[236:239], v[116:119]
	s_waitcnt lgkmcnt(2)
	v_mfma_f32_16x16x32_bf16 v[52:55], v[186:189], v[240:243], v[52:55]
	ds_read_b128 v[236:239], v149 offset:54272
	v_mfma_f32_16x16x32_bf16 v[68:71], v[190:193], v[240:243], v[68:71]
	v_mfma_f32_16x16x32_bf16 v[108:111], v[194:197], v[240:243], v[108:111]
	v_mfma_f32_16x16x32_bf16 v[120:123], v[202:205], v[240:243], v[120:123]
	s_waitcnt lgkmcnt(2)
	v_mfma_f32_16x16x32_bf16 v[48:51], v[186:189], v[244:247], v[48:51]
	ds_read_b128 v[240:243], v149 offset:55296
	v_mfma_f32_16x16x32_bf16 v[72:75], v[190:193], v[244:247], v[72:75]
	v_mfma_f32_16x16x32_bf16 v[88:91], v[194:197], v[244:247], v[88:91]
	v_mfma_f32_16x16x32_bf16 v[124:127], v[202:205], v[244:247], v[124:127]
	s_waitcnt lgkmcnt(2)
	v_mfma_f32_16x16x32_bf16 v[0:3], v[186:189], v[232:235], v[0:3]
	ds_read_b128 v[244:247], v149 offset:56320
	v_mfma_f32_16x16x32_bf16 v[16:19], v[190:193], v[232:235], v[16:19]
	v_mfma_f32_16x16x32_bf16 v[32:35], v[194:197], v[232:235], v[32:35]
	v_mfma_f32_16x16x32_bf16 v[60:63], v[202:205], v[232:235], v[60:63]
	s_waitcnt lgkmcnt(2)
	v_mfma_f32_16x16x32_bf16 v[4:7], v[186:189], v[236:239], v[4:7]
	v_mfma_f32_16x16x32_bf16 v[20:23], v[190:193], v[236:239], v[20:23]
	v_mfma_f32_16x16x32_bf16 v[36:39], v[194:197], v[236:239], v[36:39]
	v_mfma_f32_16x16x32_bf16 v[76:79], v[202:205], v[236:239], v[76:79]
	s_waitcnt lgkmcnt(1)
	v_mfma_f32_16x16x32_bf16 v[8:11], v[186:189], v[240:243], v[8:11]
	v_mfma_f32_16x16x32_bf16 v[24:27], v[190:193], v[240:243], v[24:27]
	v_mfma_f32_16x16x32_bf16 v[40:43], v[194:197], v[240:243], v[40:43]
	v_mfma_f32_16x16x32_bf16 v[84:87], v[202:205], v[240:243], v[84:87]
	s_waitcnt lgkmcnt(0)
	v_mfma_f32_16x16x32_bf16 v[12:15], v[186:189], v[244:247], v[12:15]
	v_mfma_f32_16x16x32_bf16 v[28:31], v[190:193], v[244:247], v[28:31]
	v_mfma_f32_16x16x32_bf16 v[44:47], v[194:197], v[244:247], v[44:47]
	v_mfma_f32_16x16x32_bf16 v[92:95], v[202:205], v[244:247], v[92:95]
	v_mov_b32_e32 v186, 0xf149f2ca
	v_mov_b32_e32 v187, 0x3c0881c4
	v_mov_b32_e32 v188, 0xbab64f3b
	v_mov_b32_e32 v189, 0x24800
	v_mov_b32_e32 v190, 1
	v_mov_b32_e32 v191, 0x24804
	v_mov_b32_e32 v192, 0xfcf
	v_mov_b32_e32 v193, 0x7cf
	v_mov_b32_e32 v194, 0xfdf
	v_mov_b32_e32 v195, 0x7df
	v_mov_b32_e32 v196, 0xfef
	v_mov_b32_e32 v197, 0x7ef
	v_mov_b32_e32 v198, 0xfff
	v_mov_b32_e32 v199, 0x7ff
	v_mov_b32_e32 v200, 0x20000
	v_mov_b32_e32 v201, 0xf8f
	v_mov_b32_e32 v202, 0x78f
	v_mov_b32_e32 v203, 0xf9f
	v_mov_b32_e32 v204, 0x79f
	v_mov_b32_e32 v205, 0xfaf
	v_mov_b32_e32 v210, 0x7f800000
	v_not_b32_e32 v211, 63
	v_not_b32_e32 v212, 31
	v_mov_b32_e32 v213, 0x7fc00000
	s_waitcnt vmcnt(4)
	s_barrier
; template <int NK, bool BNT = false> ...
;     ...
;     for (int m = 0; m < 4; ++m) af[m] = *reinterpret_cast<const bf16x8*>(sa + aoff + m * 1024);
; #pragma unroll
;     for (int n = 0; n < 4; ++n) bfr[n] = *reinterpret_cast<const bf16x8*>(sa + boff + n * 1024);
;     __builtin_amdgcn_sched_barrier(0);
;     if (do_stage) stage(T + 3, nxt);
; #pragma unroll
;     for (int m = 0; m < 4; ++m)
; #pragma unroll
;       for (int n = 0; n < 4; ++n) acc[m][n] = __builtin_amdgcn_mfma_f32_16x16x32_bf16(af[m], bfr[n], acc[m][n], 0, 0, 0);
;     if (do_stage) {
; #pragma unroll
;       for (int q = 0; q < NG; ++q) {
;         __builtin_amdgcn_sched_group_barrier(0x008, 3, 0);
;         __builtin_amdgcn_sched_group_barrier(0x010, 1, 0);
;       }
;       __builtin_amdgcn_sched_group_barrier(0x008, 16 - 3 * NG, 0);
;     }
;     __builtin_amdgcn_sched_barrier(0);
; #pragma unroll
;     for (int n = 0; n < 4; ++n) bfr[n] = *reinterpret_cast<const bf16x8*>(sa + boff + (4 + n) * 1024);
; #pragma unroll
;     for (int m = 0; m < 4; ++m)
; #pragma unroll
;       for (int n = 0; n < 4; ++n)
;         acc[m][4 + n] = __builtin_amdgcn_mfma_f32_16x16x32_bf16(af[m], bfr[n], acc[m][4 + n], 0, 0, 0);
;     __builtin_amdgcn_sched_barrier(0);
; template <int MODE, int NSUB>
; __device__ __forceinline__ void epilogue(const Params& p, int layer, f32x4 (&acc)[4][NSUB], int tm, int tn, int g,
;                                          const float* s_rstd, const int tid_in) {
;     ...
;   if constexpr (MODE == EPI_G1) {
;     const int ft = tm;
; #pragma unroll
;     for (int n = 0; n < NSUB; ++n) {
;       const int nl = wc * (NSUB * 16) + n * 16 + fr;
;       const int t = tn * (NSUB * 32) + nl;
;       const float rs = s_rstd[nl];
;       if (ft < 2) {
	ds_read_b128 v[134:137], v167
	ds_read_b128 v[138:141], v167 offset:1024
	ds_read_b128 v[154:157], v167 offset:2048
	ds_read_b128 v[158:161], v167 offset:3072
	ds_read_b128 v[162:165], v168
	ds_read_b128 v[166:169], v169
	ds_read_b128 v[216:219], v170
	ds_read_b128 v[220:223], v172
	s_waitcnt lgkmcnt(0)
	v_mfma_f32_16x16x32_bf16 v[56:59], v[134:137], v[162:165], v[56:59]
	v_mfma_f32_16x16x32_bf16 v[64:67], v[134:137], v[166:169], v[64:67]
	v_mfma_f32_16x16x32_bf16 v[52:55], v[134:137], v[216:219], v[52:55]
	v_mfma_f32_16x16x32_bf16 v[48:51], v[134:137], v[220:223], v[48:51]
	v_mfma_f32_16x16x32_bf16 v[100:103], v[138:141], v[162:165], v[100:103]
	v_mfma_f32_16x16x32_bf16 v[80:83], v[138:141], v[166:169], v[80:83]
	v_mfma_f32_16x16x32_bf16 v[68:71], v[138:141], v[216:219], v[68:71]
	v_mfma_f32_16x16x32_bf16 v[72:75], v[138:141], v[220:223], v[72:75]
	v_mfma_f32_16x16x32_bf16 v[96:99], v[154:157], v[166:169], v[96:99]
	v_mfma_f32_16x16x32_bf16 v[112:115], v[158:161], v[162:165], v[112:115]
	v_mfma_f32_16x16x32_bf16 v[224:227], v[154:157], v[162:165], v[104:107]
	v_mfma_f32_16x16x32_bf16 v[228:231], v[154:157], v[216:219], v[108:111]
	v_mfma_f32_16x16x32_bf16 v[232:235], v[154:157], v[220:223], v[88:91]
	v_mfma_f32_16x16x32_bf16 v[162:165], v[158:161], v[166:169], v[116:119]
	v_mfma_f32_16x16x32_bf16 v[166:169], v[158:161], v[216:219], v[120:123]
	v_mfma_f32_16x16x32_bf16 v[216:219], v[158:161], v[220:223], v[124:127]
	ds_read_b128 v[88:91], v173
	ds_read_b128 v[104:107], v174
	ds_read_b128 v[108:111], v175
	ds_read_b128 v[116:119], v178
	s_waitcnt lgkmcnt(0)
	v_mfma_f32_16x16x32_bf16 v[0:3], v[134:137], v[88:91], v[0:3]
	v_mfma_f32_16x16x32_bf16 v[4:7], v[134:137], v[104:107], v[4:7]
	v_mfma_f32_16x16x32_bf16 v[8:11], v[134:137], v[108:111], v[8:11]
	v_mfma_f32_16x16x32_bf16 v[12:15], v[134:137], v[116:119], v[12:15]
	v_mfma_f32_16x16x32_bf16 v[16:19], v[138:141], v[88:91], v[16:19]
	v_mfma_f32_16x16x32_bf16 v[20:23], v[138:141], v[104:107], v[20:23]
	v_mfma_f32_16x16x32_bf16 v[24:27], v[138:141], v[108:111], v[24:27]
	v_mfma_f32_16x16x32_bf16 v[134:137], v[138:141], v[116:119], v[28:31]
	v_mfma_f32_16x16x32_bf16 v[32:35], v[154:157], v[88:91], v[32:35]
	v_mfma_f32_16x16x32_bf16 v[36:39], v[154:157], v[104:107], v[36:39]
	v_mfma_f32_16x16x32_bf16 v[138:141], v[154:157], v[108:111], v[40:43]
	v_mfma_f32_16x16x32_bf16 v[154:157], v[154:157], v[116:119], v[44:47]
	v_mfma_f32_16x16x32_bf16 v[172:175], v[158:161], v[88:91], v[60:63]
	v_mfma_f32_16x16x32_bf16 v[220:223], v[158:161], v[104:107], v[76:79]
	v_mfma_f32_16x16x32_bf16 v[236:239], v[158:161], v[108:111], v[84:87]
	v_mfma_f32_16x16x32_bf16 v[158:161], v[158:161], v[116:119], v[92:95]
	s_waitcnt vmcnt(0)
	s_barrier
	ds_read_b128 v[40:43], v176
	ds_read_b128 v[28:31], v179
	ds_read_b128 v[44:47], v180
	ds_read_b128 v[60:63], v181
	ds_read_b128 v[240:243], v176 offset:1024
	ds_read_b128 v[244:247], v176 offset:2048
	ds_read_b128 v[248:251], v176 offset:3072
	ds_read_b128 v[178:181], v182
	s_waitcnt lgkmcnt(0)
	v_mfma_f32_16x16x32_bf16 v[124:127], v[40:43], v[28:31], v[56:59]
	v_mfma_f32_16x16x32_bf16 v[108:111], v[40:43], v[44:47], v[64:67]
	v_mfma_f32_16x16x32_bf16 v[92:95], v[40:43], v[60:63], v[52:55]
	v_mfma_f32_16x16x32_bf16 v[76:79], v[40:43], v[178:181], v[48:51]
	v_mfma_f32_16x16x32_bf16 v[120:123], v[240:243], v[28:31], v[100:103]
	v_mfma_f32_16x16x32_bf16 v[104:107], v[240:243], v[44:47], v[80:83]
	v_mfma_f32_16x16x32_bf16 v[88:91], v[240:243], v[60:63], v[68:71]
	v_mfma_f32_16x16x32_bf16 v[72:75], v[240:243], v[178:181], v[72:75]
	v_mfma_f32_16x16x32_bf16 v[116:119], v[244:247], v[28:31], v[224:227]
	v_mfma_f32_16x16x32_bf16 v[100:103], v[244:247], v[44:47], v[96:99]
	v_mfma_f32_16x16x32_bf16 v[84:87], v[244:247], v[60:63], v[228:231]
	v_mfma_f32_16x16x32_bf16 v[68:71], v[244:247], v[178:181], v[232:235]
	v_mfma_f32_16x16x32_bf16 v[112:115], v[248:251], v[28:31], v[112:115]
	v_mfma_f32_16x16x32_bf16 v[96:99], v[248:251], v[44:47], v[162:165]
	v_mfma_f32_16x16x32_bf16 v[80:83], v[248:251], v[60:63], v[166:169]
	v_mfma_f32_16x16x32_bf16 v[64:67], v[248:251], v[178:181], v[216:219]
	ds_read_b128 v[48:51], v142
	ds_read_b128 v[162:165], v143
	s_waitcnt lgkmcnt(0)
	v_mfma_f32_16x16x32_bf16 v[60:63], v[40:43], v[48:51], v[0:3]
	s_nop 2
	ds_read_b128 v[0:3], v144
	ds_read_b128 v[142:145], v145
	v_mfma_f32_16x16x32_bf16 v[44:47], v[40:43], v[162:165], v[4:7]
	s_waitcnt lgkmcnt(0)
	v_mfma_f32_16x16x32_bf16 v[28:31], v[40:43], v[0:3], v[8:11]
	v_mfma_f32_16x16x32_bf16 v[12:15], v[40:43], v[142:145], v[12:15]
	v_mfma_f32_16x16x32_bf16 v[56:59], v[240:243], v[48:51], v[16:19]
	v_mfma_f32_16x16x32_bf16 v[40:43], v[240:243], v[162:165], v[20:23]
	v_mfma_f32_16x16x32_bf16 v[24:27], v[240:243], v[0:3], v[24:27]
	v_mfma_f32_16x16x32_bf16 v[8:11], v[240:243], v[142:145], v[134:137]
	v_mfma_f32_16x16x32_bf16 v[52:55], v[244:247], v[48:51], v[32:35]
	v_mfma_f32_16x16x32_bf16 v[36:39], v[244:247], v[162:165], v[36:39]
	v_mfma_f32_16x16x32_bf16 v[20:23], v[244:247], v[0:3], v[138:141]
	v_mfma_f32_16x16x32_bf16 v[4:7], v[244:247], v[142:145], v[154:157]
	v_mfma_f32_16x16x32_bf16 v[48:51], v[248:251], v[48:51], v[172:175]
	v_mfma_f32_16x16x32_bf16 v[32:35], v[248:251], v[162:165], v[220:223]
	v_mfma_f32_16x16x32_bf16 v[16:19], v[248:251], v[0:3], v[236:239]
	v_mfma_f32_16x16x32_bf16 v[0:3], v[248:251], v[142:145], v[158:161]
	v_mov_b32_e32 v141, v215
	v_lshl_add_u32 v142, s4, 1, v151
	v_and_b32_e32 v140, 15, v141
	v_lshlrev_b32_e32 v134, 1, v141
	v_and_or_b32 v155, v134, s34, v140
	v_lshl_or_b32 v139, v155, 2, v200
	v_and_b32_e32 v134, 16, v141
	v_lshrrev_b32_e32 v138, 2, v141
	ds_read_b32 v146, v139
	v_ashrrev_i32_e32 v136, 7, v141
	v_and_or_b32 v134, v138, 8, v134
	v_lshlrev_b32_e32 v138, 7, v142
	v_lshl_add_u32 v138, v136, 6, v138
	v_bfe_u32 v137, v141, 4, 2
	v_add_u32_e32 v154, 0xfffffe00, v138
	v_or_b32_e32 v138, v138, v134
	v_cmp_lt_i32_e64 s[14:15], 1, v142
	v_cmp_lt_u32_e64 s[12:13], 3, v142
	v_cmp_lt_u32_e64 s[10:11], 5, v142
	v_cmp_ne_u32_e64 s[8:9], 6, v142
	v_cmp_gt_u32_e64 s[6:7], s34, v141
	v_lshlrev_b32_e32 v135, 2, v137
	v_cmp_eq_u32_e64 s[4:5], 0, v137
	v_ashrrev_i32_e32 v137, 31, v136
	v_lshlrev_b32_e32 v152, 1, v142
	v_add_u32_e32 v138, 0xffffff00, v138
	v_or_b32_e32 v144, s48, v155
	s_and_saveexec_b64 s[18:19], s[14:15]
	s_xor_b64 s[36:37], exec, s[18:19]
	s_cbranch_execz .LBB0_323
; __device__ __forceinline__ int widen_off(int fq) { return ((fq & 1) << 4) + ((fq >> 1) << 3); }
; template <int MODE, int NSUB>
; __device__ __forceinline__ void epilogue(const Params& p, int layer, f32x4 (&acc)[4][NSUB], int tm, int tn, int g,
;                                          const float* s_rstd, const int tid_in) {
;     ...
;       } else {
;         if (wr == 0) {
;           const int pos = tok_pos(t);
;           float o1[4], o2[4];
; #pragma unroll
;           for (int j = 0; j < 4; ++j) {
;             float2 cs = p.rope[pos * 16 + fq * 4 + j];
;             float x1 = acc[0][n][j] * rs, x2 = acc[1][n][j] * rs;
;             o1[j] = x1 * cs.x - x2 * cs.y;
;             o2[j] = x1 * cs.y + x2 * cs.x;
;           }
;           const u32x4 w = widen_pair(pack4(o1[0], o1[1], o1[2], o1[3]), pack4(o2[0], o2[1], o2[2], o2[3]));
; #pragma unroll
;           for (int hh = 0; hh < 8; ++hh)
;             __builtin_nontemporal_store(w, reinterpret_cast<u32x4*>(p.Kb + ((long)hh * NT + t) * 96 + 64 + widen_off(fq)));
;         }
	s_and_saveexec_b64 s[18:19], s[12:13]
	s_xor_b64 s[38:39], exec, s[18:19]
	s_cbranch_execz .LBB0_320
	s_and_saveexec_b64 s[18:19], s[10:11]
	s_xor_b64 s[40:41], exec, s[18:19]
	s_cbranch_execz .LBB0_315
	s_and_saveexec_b64 s[18:19], s[8:9]
	s_xor_b64 s[42:43], exec, s[18:19]
	s_cbranch_execz .LBB0_310
	s_and_saveexec_b64 s[44:45], s[6:7]
	s_cbranch_execz .LBB0_309
	s_mov_b32 s17, 0x10000
	v_cmp_gt_i32_e32 vcc, s17, v144
	v_lshlrev_b32_e32 v113, 3, v135
	v_readlane_b32 s64, v254, 51
	v_cndmask_b32_e32 v112, v201, v202, vcc
	v_and_b32_e32 v112, v112, v144
	v_lshl_or_b32 v116, v112, 7, v113
	v_readlane_b32 s70, v254, 57
	v_readlane_b32 s71, v254, 58
	s_nop 4
	global_load_dwordx4 v[112:115], v116, s[70:71] offset:16
	s_nop 0
	global_load_dwordx4 v[116:119], v116, s[70:71]
	v_mov_b32_e32 v161, v121
	v_mov_b32_e32 v121, v125
	v_mov_b32_e32 v160, v124
	s_waitcnt lgkmcnt(0)
	v_pk_mul_f32 v[120:121], v[120:121], v[146:147] op_sel_hi:[1,0]
	v_pk_mul_f32 v[160:161], v[160:161], v[146:147] op_sel_hi:[1,0]
	v_readlane_b32 s65, v254, 52
	v_readlane_b32 s66, v254, 53
	v_readlane_b32 s67, v254, 54
	v_readlane_b32 s68, v254, 55
	v_readlane_b32 s69, v254, 56
	v_readlane_b32 s72, v254, 59
	v_readlane_b32 s73, v254, 60
	v_readlane_b32 s74, v254, 61
	v_readlane_b32 s75, v254, 62
	v_readlane_b32 s76, v254, 63
	v_readlane_b32 s77, v252, 0
	v_readlane_b32 s78, v252, 1
	v_readlane_b32 s79, v252, 2
	v_readlane_b32 s64, v252, 4
	v_readlane_b32 s68, v252, 8
	v_readlane_b32 s69, v252, 9
	s_movk_i32 s17, 0xc0
	v_readlane_b32 s65, v252, 5
	v_readlane_b32 s66, v252, 6
	v_readlane_b32 s67, v252, 7
	v_readlane_b32 s70, v252, 10
	v_readlane_b32 s71, v252, 11
	v_readlane_b32 s72, v252, 12
	v_readlane_b32 s73, v252, 13
	v_readlane_b32 s74, v252, 14
	v_readlane_b32 s75, v252, 15
	v_readlane_b32 s76, v252, 16
	v_readlane_b32 s77, v252, 17
	v_readlane_b32 s78, v252, 18
	v_readlane_b32 s79, v252, 19
	s_waitcnt vmcnt(0)
	v_mov_b32_e32 v159, v114
	v_mov_b32_e32 v124, v116
	v_mov_b32_e32 v125, v119
	v_mov_b32_e32 v156, v117
	v_mov_b32_e32 v157, v118
	v_pk_mul_f32 v[124:125], v[120:121], v[124:125]
	v_mov_b32_e32 v163, v118
	v_pk_fma_f32 v[124:125], v[160:161], v[156:157], v[124:125]
	v_mov_b32_e32 v157, v121
	v_mov_b32_e32 v121, v161
	v_mov_b32_e32 v118, v117
	v_mov_b32_e32 v162, v116
	v_pk_mul_f32 v[116:117], v[120:121], v[118:119]
	v_mov_b32_e32 v118, v126
	v_mov_b32_e32 v119, v123
	v_mov_b32_e32 v123, v127
	v_mov_b32_e32 v156, v160
	v_pk_mul_f32 v[118:119], v[118:119], v[146:147] op_sel_hi:[1,0]
	v_pk_mul_f32 v[120:121], v[122:123], v[146:147] op_sel_hi:[1,0]
	v_mov_b32_e32 v122, v112
	v_mov_b32_e32 v123, v115
	v_pk_fma_f32 v[116:117], v[156:157], v[162:163], v[116:117] neg_lo:[0,0,1] neg_hi:[0,0,1]
	v_pk_mul_f32 v[122:123], v[120:121], v[122:123]
	v_mov_b32_e32 v127, v121
	v_mov_b32_e32 v157, v114
	v_mov_b32_e32 v121, v119
	v_mov_b32_e32 v114, v113
	v_mov_b32_e32 v158, v113
	v_mov_b32_e32 v126, v118
	v_mov_b32_e32 v156, v112
	v_pk_mul_f32 v[112:113], v[120:121], v[114:115]
	v_pk_fma_f32 v[122:123], v[118:119], v[158:159], v[122:123]
	v_pk_fma_f32 v[114:115], v[126:127], v[156:157], v[112:113] neg_lo:[0,0,1] neg_hi:[0,0,1]
	v_cvt_pk_bf16_f32 v112, v116, v117
	v_mov_b64_e32 v[116:117], s[68:69]
	v_mad_i64_i32 v[116:117], s[18:19], v144, s17, v[116:117]
	v_lshlrev_b32_e32 v118, 1, v134
	v_mov_b32_e32 v119, v153
	v_lshl_add_u64 v[116:117], v[116:117], 0, v[118:119]
	s_mov_b32 s17, 0xf00000
	v_cvt_pk_bf16_f32 v113, v114, v115
	v_cvt_pk_bf16_f32 v114, v124, v125
	v_cvt_pk_bf16_f32 v115, v122, v123
	v_add_co_u32_e32 v118, vcc, s17, v116
	v_permlane16_swap_b32_e32 v112, v114
	v_permlane16_swap_b32_e32 v113, v115
	v_addc_co_u32_e32 v119, vcc, 0, v117, vcc
	s_mov_b32 s17, 0x1e00000
	global_store_dwordx4 v[118:119], v[112:115], off offset:128 nt
	v_add_co_u32_e32 v118, vcc, s17, v116
	s_mov_b32 s17, 0x2d00000
	s_nop 0
	v_addc_co_u32_e32 v119, vcc, 0, v117, vcc
	global_store_dwordx4 v[118:119], v[112:115], off offset:128 nt
	v_add_co_u32_e32 v118, vcc, s17, v116
	global_store_dwordx4 v[116:117], v[112:115], off offset:128 nt
	s_nop 0
	v_addc_co_u32_e32 v119, vcc, 0, v117, vcc
	global_store_dwordx4 v[118:119], v[112:115], off offset:128 nt
	v_add_co_u32_e32 v118, vcc, 0x3c00000, v116
	s_nop 1
	v_addc_co_u32_e32 v119, vcc, 0, v117, vcc
	global_store_dwordx4 v[118:119], v[112:115], off offset:128 nt
	v_add_co_u32_e32 v118, vcc, 0x4b00000, v116
	s_nop 1
	v_addc_co_u32_e32 v119, vcc, 0, v117, vcc
	global_store_dwordx4 v[118:119], v[112:115], off offset:128 nt
	v_add_co_u32_e32 v118, vcc, 0x5a00000, v116
	s_nop 1
	v_addc_co_u32_e32 v119, vcc, 0, v117, vcc
	v_add_co_u32_e32 v116, vcc, 0x6900000, v116
	global_store_dwordx4 v[118:119], v[112:115], off offset:128 nt
	s_nop 0
	v_addc_co_u32_e32 v117, vcc, 0, v117, vcc
	global_store_dwordx4 v[116:117], v[112:115], off offset:128 nt
